# conv phase prefetch deepened to two columns ahead (3 raw buffers); adaLN-RMSNorm row loop hand-written (mul/add vectors hoisted, stores back-to-back)
# speedup vs baseline: 1.0553x; 1.0074x over previous
; __device__ __forceinline__ void phase_conv(KP p, int l, int tid) {
;     ...
;   for (int it = blockIdx.x * NTH + tid; it < total; it += gridDim.x * NTH) {
;     const int cc = it % 1408; const int rs = it / 1408; const int sgm = rs & 3, r0 = (rs >> 2) * RB; const int c0 = cc * 4;
;     f32x4 w[9];
; #pragma unroll
;     for (int k = 0; k < 9; ++k) w[k] = *(const f32x4*)(cw + k * DFF + c0);
;     const f32x4 bsv = *(const f32x4*)(cbias + c0);
;     const bf16_t* rowp[RB + 2]; bool rv[RB + 2];
; #pragma unroll
;     for (int di = 0; di < RB + 2; ++di) { const int rr = r0 + di - 1; rv[di] = (rr >= 0) && (rr < 256); const int rc = rr < 0 ? 0 : (rr > 255 ? 255 : rr); rowp[di] = A + (size_t)(rc * 64) * DFF + c0; }
;     float win[3][RB + 2][4];
;     const int j0 = sgm * 16;
;     {
;       u32x2 ra[2][RB + 2];
; #pragma unroll
;       for (int s = 0; s < 2; ++s) { const int col = j0 - 1 + s; const int cl = col < 0 ? 0 : col;
; #pragma unroll
;         for (int di = 0; di < RB + 2; ++di) ra[s][di] = *(const u32x2*)(rowp[di] + (size_t)cl * DFF); }
; #pragma unroll
;       for (int s = 0; s < 2; ++s) { const int col = j0 - 1 + s;
; #pragma unroll
;         for (int di = 0; di < RB + 2; ++di) { const bool ok = rv[di] && (col >= 0); unpack4(ra[s][di], win[s][di]);
; #pragma unroll
;           for (int k = 0; k < 4; ++k) win[s][di][k] = ok ? win[s][di][k] : 0.f; } }
;     }
; #pragma unroll 1
;     for (int jb = j0; jb < j0 + 16; jb += CB) {
;       u32x2 an[CB][RB + 2], ur[CB][RB];
; #pragma unroll
;       for (int q = 0; q < CB; ++q) { const int col = jb + q + 1; const int cl = col > 63 ? 63 : col;
; #pragma unroll
;         for (int di = 0; di < RB + 2; ++di) an[q][di] = *(const u32x2*)(rowp[di] + (size_t)cl * DFF);
; #pragma unroll
;         for (int rr = 0; rr < RB; ++rr) ur[q][rr] = *(const u32x2*)(U + (size_t)((r0 + rr) * 64 + jb + q) * DFF + c0); }
.Lcv_item:
	s_mov_b32 s0, 0x2e8ba2e9
	v_mul_hi_i32 v222, v142, s0
	v_lshrrev_b32_e32 v223, 31, v222
	v_ashrrev_i32_e32 v222, 8, v222
	v_add_u32_e32 v222, v222, v223
	v_mul_u32_u24_e32 v223, 0x580, v222
	v_sub_u32_e32 v223, v142, v223
	v_lshlrev_b32_e32 v224, 4, v223
	v_lshlrev_b32_e32 v223, 3, v223
	global_load_dwordx4 v[0:3], v224, s[20:21]
	v_add_u32_e32 v225, 0x5800, v224
	global_load_dwordx4 v[4:7], v225, s[20:21]
	v_add_u32_e32 v225, 0xb000, v224
	global_load_dwordx4 v[8:11], v225, s[20:21]
	v_add_u32_e32 v225, 0x10800, v224
	global_load_dwordx4 v[12:15], v225, s[20:21]
	v_add_u32_e32 v225, 0x16000, v224
	global_load_dwordx4 v[16:19], v225, s[20:21]
	v_add_u32_e32 v225, 0x1b800, v224
	global_load_dwordx4 v[20:23], v225, s[20:21]
	v_add_u32_e32 v225, 0x21000, v224
	global_load_dwordx4 v[24:27], v225, s[20:21]
	v_add_u32_e32 v225, 0x26800, v224
	global_load_dwordx4 v[28:31], v225, s[20:21]
	v_add_u32_e32 v225, 0x2c000, v224
	global_load_dwordx4 v[32:35], v225, s[20:21]
	global_load_dwordx4 v[36:39], v224, s[22:23]
	v_and_b32_e32 v224, 3, v222
	v_lshrrev_b32_e32 v222, 1, v222
	v_and_b32_e32 v222, -2, v222
	v_cmp_lt_u32_e32 vcc, 0, v222
	s_nop 1
	v_cndmask_b32_e32 v200, 0, v186, vcc
	v_mov_b32_e32 v201, v200
	v_cmp_gt_u32_e32 vcc, 0xfe, v222
	s_nop 1
	v_cndmask_b32_e32 v202, 0, v186, vcc
	v_mov_b32_e32 v203, v202
	v_sub_u32_e64 v225, v222, 1 clamp
	v_mul_u32_u24_e32 v206, 0xb0000, v225
	v_mul_u32_u24_e32 v207, 0xb0000, v222
	v_add_u32_e32 v208, 0xb0000, v207
	v_add_u32_e32 v225, 2, v222
	v_min_u32_e32 v225, 0xff, v225
	v_mul_u32_u24_e32 v209, 0xb0000, v225
	v_add_u32_e32 v206, v206, v223
	v_add_u32_e32 v207, v207, v223
	v_add_u32_e32 v208, v208, v223
	v_add_u32_e32 v209, v209, v223
	v_lshlrev_b32_e32 v224, 4, v224
	v_mul_u32_u24_e32 v210, 0x2c00, v224
	v_cmp_lt_u32_e32 vcc, 0, v224
	s_nop 1
	v_cndmask_b32_e32 v204, 0, v186, vcc
	v_mov_b32_e32 v205, v204
	v_sub_u32_e64 v225, v224, 1 clamp
	v_mul_u32_u24_e32 v225, 0x2c00, v225
	v_add_u32_e32 v212, v206, v225
	global_load_dwordx2 v[96:97], v212, s[6:7]
	v_add_u32_e32 v213, v207, v225
	global_load_dwordx2 v[98:99], v213, s[6:7]
	v_add_u32_e32 v214, v208, v225
	global_load_dwordx2 v[100:101], v214, s[6:7]
	v_add_u32_e32 v215, v209, v225
	global_load_dwordx2 v[102:103], v215, s[6:7]
	v_add_u32_e32 v212, v206, v210
	global_load_dwordx2 v[88:89], v212, s[6:7]
	v_add_u32_e32 v213, v207, v210
	global_load_dwordx2 v[90:91], v213, s[6:7]
	v_add_u32_e32 v214, v208, v210
	global_load_dwordx2 v[92:93], v214, s[6:7]
	v_add_u32_e32 v215, v209, v210
	global_load_dwordx2 v[94:95], v215, s[6:7]
	s_waitcnt vmcnt(0)
	v_lshlrev_b32_e32 v40, 16, v96
	v_and_b32_e32 v41, 0xffff0000, v96
	v_lshlrev_b32_e32 v42, 16, v97
	v_and_b32_e32 v43, 0xffff0000, v97
	v_lshlrev_b32_e32 v44, 16, v98
	v_and_b32_e32 v45, 0xffff0000, v98
	v_lshlrev_b32_e32 v46, 16, v99
	v_and_b32_e32 v47, 0xffff0000, v99
	v_lshlrev_b32_e32 v48, 16, v100
	v_and_b32_e32 v49, 0xffff0000, v100
	v_lshlrev_b32_e32 v50, 16, v101
	v_and_b32_e32 v51, 0xffff0000, v101
	v_lshlrev_b32_e32 v52, 16, v102
	v_and_b32_e32 v53, 0xffff0000, v102
	v_lshlrev_b32_e32 v54, 16, v103
	v_and_b32_e32 v55, 0xffff0000, v103
	v_pk_mul_f32 v[40:41], v[40:41], v[200:201]
	v_pk_mul_f32 v[42:43], v[42:43], v[200:201]
	v_pk_mul_f32 v[52:53], v[52:53], v[202:203]
	v_pk_mul_f32 v[54:55], v[54:55], v[202:203]
	v_pk_mul_f32 v[40:41], v[40:41], v[204:205]
	v_pk_mul_f32 v[42:43], v[42:43], v[204:205]
	v_pk_mul_f32 v[44:45], v[44:45], v[204:205]
	v_pk_mul_f32 v[46:47], v[46:47], v[204:205]
	v_pk_mul_f32 v[48:49], v[48:49], v[204:205]
	v_pk_mul_f32 v[50:51], v[50:51], v[204:205]
	v_pk_mul_f32 v[52:53], v[52:53], v[204:205]
	v_pk_mul_f32 v[54:55], v[54:55], v[204:205]
	v_lshlrev_b32_e32 v56, 16, v88
	v_and_b32_e32 v57, 0xffff0000, v88
	v_lshlrev_b32_e32 v58, 16, v89
	v_and_b32_e32 v59, 0xffff0000, v89
	v_lshlrev_b32_e32 v60, 16, v90
	v_and_b32_e32 v61, 0xffff0000, v90
	v_lshlrev_b32_e32 v62, 16, v91
	v_and_b32_e32 v63, 0xffff0000, v91
	v_lshlrev_b32_e32 v64, 16, v92
	v_and_b32_e32 v65, 0xffff0000, v92
	v_lshlrev_b32_e32 v66, 16, v93
	v_and_b32_e32 v67, 0xffff0000, v93
	v_lshlrev_b32_e32 v68, 16, v94
	v_and_b32_e32 v69, 0xffff0000, v94
	v_lshlrev_b32_e32 v70, 16, v95
	v_and_b32_e32 v71, 0xffff0000, v95
	v_pk_mul_f32 v[56:57], v[56:57], v[200:201]
	v_pk_mul_f32 v[58:59], v[58:59], v[200:201]
	v_pk_mul_f32 v[68:69], v[68:69], v[202:203]
	v_pk_mul_f32 v[70:71], v[70:71], v[202:203]
	v_add_u32_e32 v211, 0x2c00, v210
	v_add_u32_e32 v212, v206, v211
	global_load_dwordx2 v[88:89], v212, s[6:7]
	v_add_u32_e32 v213, v207, v211
	global_load_dwordx2 v[90:91], v213, s[6:7]
	v_add_u32_e32 v214, v208, v211
	global_load_dwordx2 v[92:93], v214, s[6:7]
	v_add_u32_e32 v215, v209, v211
	global_load_dwordx2 v[94:95], v215, s[6:7]
	v_add_u32_e32 v216, v207, v210
	global_load_dwordx2 v[112:113], v216, s[8:9]
	v_add_u32_e32 v217, v208, v210
	global_load_dwordx2 v[114:115], v217, s[8:9]
	v_add_u32_e32 v210, 0x2c00, v210
	v_add_u32_e32 v211, 0x2c00, v210
	v_add_u32_e32 v212, v206, v211
	global_load_dwordx2 v[96:97], v212, s[6:7]
	v_add_u32_e32 v213, v207, v211
	global_load_dwordx2 v[98:99], v213, s[6:7]
	v_add_u32_e32 v214, v208, v211
	global_load_dwordx2 v[100:101], v214, s[6:7]
	v_add_u32_e32 v215, v209, v211
	global_load_dwordx2 v[102:103], v215, s[6:7]
	v_add_u32_e32 v218, v207, v210
	global_load_dwordx2 v[116:117], v218, s[8:9]
	v_add_u32_e32 v219, v208, v210
	global_load_dwordx2 v[118:119], v219, s[8:9]
	v_cmp_gt_u32_e32 vcc, 48, v224
	s_nop 1
	v_cndmask_b32_e32 v204, 0, v186, vcc
	v_mov_b32_e32 v205, v204
	v_add_u32_e32 v210, 0x2c00, v210
	v_add_u32_e32 v211, 0x2c00, v210
	v_add_u32_e32 v212, v206, v211
	global_load_dwordx2 v[104:105], v212, s[6:7]
	v_add_u32_e32 v213, v207, v211
	global_load_dwordx2 v[106:107], v213, s[6:7]
	v_add_u32_e32 v214, v208, v211
	global_load_dwordx2 v[108:109], v214, s[6:7]
	v_add_u32_e32 v215, v209, v211
	global_load_dwordx2 v[110:111], v215, s[6:7]
	v_add_u32_e32 v220, v207, v210
	global_load_dwordx2 v[120:121], v220, s[8:9]
	v_add_u32_e32 v221, v208, v210
	global_load_dwordx2 v[122:123], v221, s[8:9]
	s_waitcnt vmcnt(12)
; __device__ __forceinline__ unsigned cvt_pk_bf16(float lo, float hi) { unsigned r; asm volatile("v_cvt_pk_bf16_f32 %0, %1, %2" : "=v"(r) : "v"(lo), "v"(hi)); return r; }
; __device__ __forceinline__ float gelu_as(float v) {
;   const float av = fabsf(v); const float t = __builtin_amdgcn_rcpf(av * 0.2316418882f + 1.0f);
;   float q = t * 0.5307027145f + (-0.7265760135f); q = q * t + 0.7107068705f; q = q * t + (-0.142248368f); q = q * t + 0.127414796f; q = q * t;
;   const float e = __builtin_amdgcn_exp2f((v * v) * (-0.72134752044f));
;   const float m = v * (q * e);
;   return v < 0.f ? m : v - m;
; }
; __device__ __forceinline__ void phase_conv(KP p, int l, int tid) {
;     ...
;     for (int jb = j0; jb < j0 + 16; jb += CB) {
;       u32x2 an[CB][RB + 2], ur[CB][RB];
; #pragma unroll
;       for (int q = 0; q < CB; ++q) { const int col = jb + q + 1; const int cl = col > 63 ? 63 : col;
; #pragma unroll
;         for (int di = 0; di < RB + 2; ++di) an[q][di] = *(const u32x2*)(rowp[di] + (size_t)cl * DFF);
; #pragma unroll
;         for (int rr = 0; rr < RB; ++rr) ur[q][rr] = *(const u32x2*)(U + (size_t)((r0 + rr) * 64 + jb + q) * DFF + c0); }
;       __builtin_amdgcn_sched_barrier(0);
; #pragma unroll
;       for (int q = 0; q < CB; ++q) {
;         const int col = jb + q + 1;
; #pragma unroll
;         for (int di = 0; di < RB + 2; ++di) { const bool ok = rv[di] && (col < 64); unpack4(an[q][di], win[2][di]);
; #pragma unroll
;           for (int k = 0; k < 4; ++k) win[2][di][k] = ok ? win[2][di][k] : 0.f; }
; #pragma unroll
;         for (int rr = 0; rr < RB; ++rr) {
;           float uv[4]; unpack4(ur[q][rr], uv);
;           float o[4];
; #pragma unroll
;           for (int k = 0; k < 4; ++k) {
;             float a = bsv[k];
; #pragma unroll
;             for (int di = 0; di < 3; ++di)
; #pragma unroll
;               for (int dj = 0; dj < 3; ++dj) a += win[dj][rr + di][k] * w[di * 3 + dj][k];
;             o[k] = gelu_as(a) * uv[k];
;           }
;           u32x2 ow; ow.x = cvt_pk_bf16(o[0], o[1]); ow.y = cvt_pk_bf16(o[2], o[3]);
;           *(u32x2*)(G + (size_t)((r0 + rr) * 64 + jb + q) * DFF + c0) = ow;
	v_lshlrev_b32_e32 v72, 16, v88
	v_and_b32_e32 v73, 0xffff0000, v88
	v_lshlrev_b32_e32 v74, 16, v89
	v_and_b32_e32 v75, 0xffff0000, v89
	v_lshlrev_b32_e32 v76, 16, v90
	v_and_b32_e32 v77, 0xffff0000, v90
	v_lshlrev_b32_e32 v78, 16, v91
	v_and_b32_e32 v79, 0xffff0000, v91
	v_lshlrev_b32_e32 v80, 16, v92
	v_and_b32_e32 v81, 0xffff0000, v92
	v_lshlrev_b32_e32 v82, 16, v93
	v_and_b32_e32 v83, 0xffff0000, v93
	v_lshlrev_b32_e32 v84, 16, v94
	v_and_b32_e32 v85, 0xffff0000, v94
	v_lshlrev_b32_e32 v86, 16, v95
	v_and_b32_e32 v87, 0xffff0000, v95
	v_pk_mul_f32 v[72:73], v[72:73], v[200:201]
	v_pk_mul_f32 v[74:75], v[74:75], v[200:201]
	v_pk_mul_f32 v[84:85], v[84:85], v[202:203]
	v_pk_mul_f32 v[86:87], v[86:87], v[202:203]
	v_lshlrev_b32_e32 v124, 16, v112
	v_and_b32_e32 v125, 0xffff0000, v112
	v_lshlrev_b32_e32 v126, 16, v113
	v_and_b32_e32 v127, 0xffff0000, v113
	v_lshlrev_b32_e32 v128, 16, v114
	v_and_b32_e32 v129, 0xffff0000, v114
	v_lshlrev_b32_e32 v130, 16, v115
	v_and_b32_e32 v131, 0xffff0000, v115
	v_pk_fma_f32 v[148:149], v[40:41], v[0:1], v[36:37]
	v_pk_fma_f32 v[150:151], v[42:43], v[2:3], v[38:39]
	v_pk_fma_f32 v[152:153], v[44:45], v[0:1], v[36:37]
	v_pk_fma_f32 v[154:155], v[46:47], v[2:3], v[38:39]
	v_pk_fma_f32 v[148:149], v[56:57], v[4:5], v[148:149]
	v_pk_fma_f32 v[150:151], v[58:59], v[6:7], v[150:151]
	v_pk_fma_f32 v[152:153], v[60:61], v[4:5], v[152:153]
	v_pk_fma_f32 v[154:155], v[62:63], v[6:7], v[154:155]
	v_pk_fma_f32 v[148:149], v[72:73], v[8:9], v[148:149]
	v_pk_fma_f32 v[150:151], v[74:75], v[10:11], v[150:151]
	v_pk_fma_f32 v[152:153], v[76:77], v[8:9], v[152:153]
	v_pk_fma_f32 v[154:155], v[78:79], v[10:11], v[154:155]
	v_pk_fma_f32 v[148:149], v[44:45], v[12:13], v[148:149]
	v_pk_fma_f32 v[150:151], v[46:47], v[14:15], v[150:151]
	v_pk_fma_f32 v[152:153], v[48:49], v[12:13], v[152:153]
	v_pk_fma_f32 v[154:155], v[50:51], v[14:15], v[154:155]
	v_pk_fma_f32 v[148:149], v[60:61], v[16:17], v[148:149]
	v_pk_fma_f32 v[150:151], v[62:63], v[18:19], v[150:151]
	v_pk_fma_f32 v[152:153], v[64:65], v[16:17], v[152:153]
	v_pk_fma_f32 v[154:155], v[66:67], v[18:19], v[154:155]
	v_pk_fma_f32 v[148:149], v[76:77], v[20:21], v[148:149]
	v_pk_fma_f32 v[150:151], v[78:79], v[22:23], v[150:151]
	v_pk_fma_f32 v[152:153], v[80:81], v[20:21], v[152:153]
	v_pk_fma_f32 v[154:155], v[82:83], v[22:23], v[154:155]
	v_pk_fma_f32 v[148:149], v[48:49], v[24:25], v[148:149]
	v_pk_fma_f32 v[150:151], v[50:51], v[26:27], v[150:151]
	v_pk_fma_f32 v[152:153], v[52:53], v[24:25], v[152:153]
	v_pk_fma_f32 v[154:155], v[54:55], v[26:27], v[154:155]
	v_pk_fma_f32 v[148:149], v[64:65], v[28:29], v[148:149]
	v_pk_fma_f32 v[150:151], v[66:67], v[30:31], v[150:151]
	v_pk_fma_f32 v[152:153], v[68:69], v[28:29], v[152:153]
	v_pk_fma_f32 v[154:155], v[70:71], v[30:31], v[154:155]
	v_pk_fma_f32 v[148:149], v[80:81], v[32:33], v[148:149]
	v_pk_fma_f32 v[150:151], v[82:83], v[34:35], v[150:151]
	v_pk_fma_f32 v[152:153], v[84:85], v[32:33], v[152:153]
	v_pk_fma_f32 v[154:155], v[86:87], v[34:35], v[154:155]
	v_and_b32_e32 v156, 0x7fffffff, v148
	v_and_b32_e32 v157, 0x7fffffff, v149
	v_and_b32_e32 v158, 0x7fffffff, v150
	v_and_b32_e32 v159, 0x7fffffff, v151
	v_and_b32_e32 v160, 0x7fffffff, v152
	v_and_b32_e32 v161, 0x7fffffff, v153
	v_and_b32_e32 v162, 0x7fffffff, v154
	v_and_b32_e32 v163, 0x7fffffff, v155
	v_pk_fma_f32 v[164:165], v[156:157], v[184:185], v[186:187]
	v_pk_fma_f32 v[166:167], v[158:159], v[184:185], v[186:187]
	v_pk_fma_f32 v[168:169], v[160:161], v[184:185], v[186:187]
	v_pk_fma_f32 v[170:171], v[162:163], v[184:185], v[186:187]
	v_rcp_f32_e32 v164, v164
	v_rcp_f32_e32 v165, v165
	v_rcp_f32_e32 v166, v166
	v_rcp_f32_e32 v167, v167
	v_rcp_f32_e32 v168, v168
	v_rcp_f32_e32 v169, v169
	v_rcp_f32_e32 v170, v170
	v_rcp_f32_e32 v171, v171
	v_pk_fma_f32 v[172:173], v[164:165], v[188:189], v[190:191]
	v_pk_fma_f32 v[174:175], v[166:167], v[188:189], v[190:191]
	v_pk_fma_f32 v[176:177], v[168:169], v[188:189], v[190:191]
	v_pk_fma_f32 v[178:179], v[170:171], v[188:189], v[190:191]
	v_pk_fma_f32 v[172:173], v[172:173], v[164:165], v[192:193]
	v_pk_fma_f32 v[174:175], v[174:175], v[166:167], v[192:193]
	v_pk_fma_f32 v[176:177], v[176:177], v[168:169], v[192:193]
	v_pk_fma_f32 v[178:179], v[178:179], v[170:171], v[192:193]
	v_pk_fma_f32 v[172:173], v[172:173], v[164:165], v[194:195]
	v_pk_fma_f32 v[174:175], v[174:175], v[166:167], v[194:195]
	v_pk_fma_f32 v[176:177], v[176:177], v[168:169], v[194:195]
	v_pk_fma_f32 v[178:179], v[178:179], v[170:171], v[194:195]
	v_pk_fma_f32 v[172:173], v[172:173], v[164:165], v[196:197]
	v_pk_fma_f32 v[174:175], v[174:175], v[166:167], v[196:197]
	v_pk_fma_f32 v[176:177], v[176:177], v[168:169], v[196:197]
	v_pk_fma_f32 v[178:179], v[178:179], v[170:171], v[196:197]
	v_pk_mul_f32 v[172:173], v[172:173], v[164:165]
	v_pk_mul_f32 v[174:175], v[174:175], v[166:167]
	v_pk_mul_f32 v[176:177], v[176:177], v[168:169]
	v_pk_mul_f32 v[178:179], v[178:179], v[170:171]
	v_pk_mul_f32 v[164:165], v[148:149], v[148:149]
	v_pk_mul_f32 v[166:167], v[150:151], v[150:151]
	v_pk_mul_f32 v[168:169], v[152:153], v[152:153]
	v_pk_mul_f32 v[170:171], v[154:155], v[154:155]
	v_pk_mul_f32 v[164:165], v[164:165], v[198:199]
	v_pk_mul_f32 v[166:167], v[166:167], v[198:199]
	v_pk_mul_f32 v[168:169], v[168:169], v[198:199]
	v_pk_mul_f32 v[170:171], v[170:171], v[198:199]
	v_exp_f32_e32 v164, v164
	v_exp_f32_e32 v165, v165
	v_exp_f32_e32 v166, v166
	v_exp_f32_e32 v167, v167
	v_exp_f32_e32 v168, v168
	v_exp_f32_e32 v169, v169
	v_exp_f32_e32 v170, v170
	v_exp_f32_e32 v171, v171
	v_pk_mul_f32 v[172:173], v[172:173], v[164:165]
	v_pk_mul_f32 v[174:175], v[174:175], v[166:167]
; __device__ __forceinline__ unsigned cvt_pk_bf16(float lo, float hi) { unsigned r; asm volatile("v_cvt_pk_bf16_f32 %0, %1, %2" : "=v"(r) : "v"(lo), "v"(hi)); return r; }
; __device__ __forceinline__ float gelu_as(float v) {
;   const float av = fabsf(v); const float t = __builtin_amdgcn_rcpf(av * 0.2316418882f + 1.0f);
;   float q = t * 0.5307027145f + (-0.7265760135f); q = q * t + 0.7107068705f; q = q * t + (-0.142248368f); q = q * t + 0.127414796f; q = q * t;
;   const float e = __builtin_amdgcn_exp2f((v * v) * (-0.72134752044f));
;   const float m = v * (q * e);
;   return v < 0.f ? m : v - m;
; }
; __device__ __forceinline__ void phase_conv(KP p, int l, int tid) {
;     ...
;     for (int jb = j0; jb < j0 + 16; jb += CB) {
;       u32x2 an[CB][RB + 2], ur[CB][RB];
; #pragma unroll
;       for (int q = 0; q < CB; ++q) { const int col = jb + q + 1; const int cl = col > 63 ? 63 : col;
; #pragma unroll
;         for (int di = 0; di < RB + 2; ++di) an[q][di] = *(const u32x2*)(rowp[di] + (size_t)cl * DFF);
; #pragma unroll
;         for (int rr = 0; rr < RB; ++rr) ur[q][rr] = *(const u32x2*)(U + (size_t)((r0 + rr) * 64 + jb + q) * DFF + c0); }
;       __builtin_amdgcn_sched_barrier(0);
; #pragma unroll
;       for (int q = 0; q < CB; ++q) {
;         const int col = jb + q + 1;
; #pragma unroll
;         for (int di = 0; di < RB + 2; ++di) { const bool ok = rv[di] && (col < 64); unpack4(an[q][di], win[2][di]);
; #pragma unroll
;           for (int k = 0; k < 4; ++k) win[2][di][k] = ok ? win[2][di][k] : 0.f; }
; #pragma unroll
;         for (int rr = 0; rr < RB; ++rr) {
;           float uv[4]; unpack4(ur[q][rr], uv);
;           float o[4];
; #pragma unroll
;           for (int k = 0; k < 4; ++k) {
;             float a = bsv[k];
; #pragma unroll
;             for (int di = 0; di < 3; ++di)
; #pragma unroll
;               for (int dj = 0; dj < 3; ++dj) a += win[dj][rr + di][k] * w[di * 3 + dj][k];
;             o[k] = gelu_as(a) * uv[k];
;           }
;           u32x2 ow; ow.x = cvt_pk_bf16(o[0], o[1]); ow.y = cvt_pk_bf16(o[2], o[3]);
;           *(u32x2*)(G + (size_t)((r0 + rr) * 64 + jb + q) * DFF + c0) = ow;
	v_pk_mul_f32 v[176:177], v[176:177], v[168:169]
	v_pk_mul_f32 v[178:179], v[178:179], v[170:171]
	v_pk_mul_f32 v[172:173], v[156:157], v[172:173]
	v_pk_mul_f32 v[174:175], v[158:159], v[174:175]
	v_pk_mul_f32 v[176:177], v[160:161], v[176:177]
	v_pk_mul_f32 v[178:179], v[162:163], v[178:179]
	v_max_f32_e32 v164, 0, v148
	v_max_f32_e32 v165, 0, v149
	v_max_f32_e32 v166, 0, v150
	v_max_f32_e32 v167, 0, v151
	v_max_f32_e32 v168, 0, v152
	v_max_f32_e32 v169, 0, v153
	v_max_f32_e32 v170, 0, v154
	v_max_f32_e32 v171, 0, v155
	v_pk_add_f32 v[164:165], v[164:165], v[172:173] neg_lo:[0,1] neg_hi:[0,1]
	v_pk_add_f32 v[166:167], v[166:167], v[174:175] neg_lo:[0,1] neg_hi:[0,1]
	v_pk_add_f32 v[168:169], v[168:169], v[176:177] neg_lo:[0,1] neg_hi:[0,1]
	v_pk_add_f32 v[170:171], v[170:171], v[178:179] neg_lo:[0,1] neg_hi:[0,1]
	v_pk_mul_f32 v[164:165], v[164:165], v[124:125]
	v_pk_mul_f32 v[166:167], v[166:167], v[126:127]
	v_pk_mul_f32 v[168:169], v[168:169], v[128:129]
	v_pk_mul_f32 v[170:171], v[170:171], v[130:131]
	v_cvt_pk_bf16_f32 v156, v164, v165
	v_cvt_pk_bf16_f32 v157, v166, v167
	v_cvt_pk_bf16_f32 v158, v168, v169
	v_cvt_pk_bf16_f32 v159, v170, v171
	global_store_dwordx2 v216, v[156:157], s[10:11]
	global_store_dwordx2 v217, v[158:159], s[10:11]
	v_add_u32_e32 v210, 0x2c00, v210
	v_add_u32_e32 v211, 0x2c00, v210
	v_add_u32_e32 v212, v206, v211
	global_load_dwordx2 v[88:89], v212, s[6:7]
	v_add_u32_e32 v213, v207, v211
	global_load_dwordx2 v[90:91], v213, s[6:7]
	v_add_u32_e32 v214, v208, v211
	global_load_dwordx2 v[92:93], v214, s[6:7]
	v_add_u32_e32 v215, v209, v211
	global_load_dwordx2 v[94:95], v215, s[6:7]
	v_add_u32_e32 v216, v207, v210
	global_load_dwordx2 v[112:113], v216, s[8:9]
	v_add_u32_e32 v217, v208, v210
	global_load_dwordx2 v[114:115], v217, s[8:9]
	s_waitcnt vmcnt(14)
	v_lshlrev_b32_e32 v40, 16, v96
	v_and_b32_e32 v41, 0xffff0000, v96
	v_lshlrev_b32_e32 v42, 16, v97
	v_and_b32_e32 v43, 0xffff0000, v97
	v_lshlrev_b32_e32 v44, 16, v98
	v_and_b32_e32 v45, 0xffff0000, v98
	v_lshlrev_b32_e32 v46, 16, v99
	v_and_b32_e32 v47, 0xffff0000, v99
	v_lshlrev_b32_e32 v48, 16, v100
	v_and_b32_e32 v49, 0xffff0000, v100
	v_lshlrev_b32_e32 v50, 16, v101
	v_and_b32_e32 v51, 0xffff0000, v101
	v_lshlrev_b32_e32 v52, 16, v102
	v_and_b32_e32 v53, 0xffff0000, v102
	v_lshlrev_b32_e32 v54, 16, v103
	v_and_b32_e32 v55, 0xffff0000, v103
	v_pk_mul_f32 v[40:41], v[40:41], v[200:201]
	v_pk_mul_f32 v[42:43], v[42:43], v[200:201]
	v_pk_mul_f32 v[52:53], v[52:53], v[202:203]
	v_pk_mul_f32 v[54:55], v[54:55], v[202:203]
	v_lshlrev_b32_e32 v124, 16, v116
	v_and_b32_e32 v125, 0xffff0000, v116
	v_lshlrev_b32_e32 v126, 16, v117
	v_and_b32_e32 v127, 0xffff0000, v117
	v_lshlrev_b32_e32 v128, 16, v118
	v_and_b32_e32 v129, 0xffff0000, v118
	v_lshlrev_b32_e32 v130, 16, v119
	v_and_b32_e32 v131, 0xffff0000, v119
	v_pk_fma_f32 v[148:149], v[56:57], v[0:1], v[36:37]
	v_pk_fma_f32 v[150:151], v[58:59], v[2:3], v[38:39]
	v_pk_fma_f32 v[152:153], v[60:61], v[0:1], v[36:37]
	v_pk_fma_f32 v[154:155], v[62:63], v[2:3], v[38:39]
	v_pk_fma_f32 v[148:149], v[72:73], v[4:5], v[148:149]
	v_pk_fma_f32 v[150:151], v[74:75], v[6:7], v[150:151]
	v_pk_fma_f32 v[152:153], v[76:77], v[4:5], v[152:153]
	v_pk_fma_f32 v[154:155], v[78:79], v[6:7], v[154:155]
	v_pk_fma_f32 v[148:149], v[40:41], v[8:9], v[148:149]
	v_pk_fma_f32 v[150:151], v[42:43], v[10:11], v[150:151]
	v_pk_fma_f32 v[152:153], v[44:45], v[8:9], v[152:153]
	v_pk_fma_f32 v[154:155], v[46:47], v[10:11], v[154:155]
	v_pk_fma_f32 v[148:149], v[60:61], v[12:13], v[148:149]
	v_pk_fma_f32 v[150:151], v[62:63], v[14:15], v[150:151]
	v_pk_fma_f32 v[152:153], v[64:65], v[12:13], v[152:153]
	v_pk_fma_f32 v[154:155], v[66:67], v[14:15], v[154:155]
	v_pk_fma_f32 v[148:149], v[76:77], v[16:17], v[148:149]
	v_pk_fma_f32 v[150:151], v[78:79], v[18:19], v[150:151]
	v_pk_fma_f32 v[152:153], v[80:81], v[16:17], v[152:153]
	v_pk_fma_f32 v[154:155], v[82:83], v[18:19], v[154:155]
	v_pk_fma_f32 v[148:149], v[44:45], v[20:21], v[148:149]
	v_pk_fma_f32 v[150:151], v[46:47], v[22:23], v[150:151]
	v_pk_fma_f32 v[152:153], v[48:49], v[20:21], v[152:153]
	v_pk_fma_f32 v[154:155], v[50:51], v[22:23], v[154:155]
	v_pk_fma_f32 v[148:149], v[64:65], v[24:25], v[148:149]
	v_pk_fma_f32 v[150:151], v[66:67], v[26:27], v[150:151]
	v_pk_fma_f32 v[152:153], v[68:69], v[24:25], v[152:153]
	v_pk_fma_f32 v[154:155], v[70:71], v[26:27], v[154:155]
	v_pk_fma_f32 v[148:149], v[80:81], v[28:29], v[148:149]
	v_pk_fma_f32 v[150:151], v[82:83], v[30:31], v[150:151]
	v_pk_fma_f32 v[152:153], v[84:85], v[28:29], v[152:153]
	v_pk_fma_f32 v[154:155], v[86:87], v[30:31], v[154:155]
	v_pk_fma_f32 v[148:149], v[48:49], v[32:33], v[148:149]
	v_pk_fma_f32 v[150:151], v[50:51], v[34:35], v[150:151]
	v_pk_fma_f32 v[152:153], v[52:53], v[32:33], v[152:153]
	v_pk_fma_f32 v[154:155], v[54:55], v[34:35], v[154:155]
	v_and_b32_e32 v156, 0x7fffffff, v148
	v_and_b32_e32 v157, 0x7fffffff, v149
	v_and_b32_e32 v158, 0x7fffffff, v150
	v_and_b32_e32 v159, 0x7fffffff, v151
	v_and_b32_e32 v160, 0x7fffffff, v152
	v_and_b32_e32 v161, 0x7fffffff, v153
	v_and_b32_e32 v162, 0x7fffffff, v154
	v_and_b32_e32 v163, 0x7fffffff, v155
	v_pk_fma_f32 v[164:165], v[156:157], v[184:185], v[186:187]
	v_pk_fma_f32 v[166:167], v[158:159], v[184:185], v[186:187]
	v_pk_fma_f32 v[168:169], v[160:161], v[184:185], v[186:187]
	v_pk_fma_f32 v[170:171], v[162:163], v[184:185], v[186:187]
	v_rcp_f32_e32 v164, v164
	v_rcp_f32_e32 v165, v165
	v_rcp_f32_e32 v166, v166
	v_rcp_f32_e32 v167, v167
	v_rcp_f32_e32 v168, v168
	v_rcp_f32_e32 v169, v169
	v_rcp_f32_e32 v170, v170
	v_rcp_f32_e32 v171, v171
; __device__ __forceinline__ unsigned cvt_pk_bf16(float lo, float hi) { unsigned r; asm volatile("v_cvt_pk_bf16_f32 %0, %1, %2" : "=v"(r) : "v"(lo), "v"(hi)); return r; }
; __device__ __forceinline__ float gelu_as(float v) {
;   const float av = fabsf(v); const float t = __builtin_amdgcn_rcpf(av * 0.2316418882f + 1.0f);
;   float q = t * 0.5307027145f + (-0.7265760135f); q = q * t + 0.7107068705f; q = q * t + (-0.142248368f); q = q * t + 0.127414796f; q = q * t;
;   const float e = __builtin_amdgcn_exp2f((v * v) * (-0.72134752044f));
;   const float m = v * (q * e);
;   return v < 0.f ? m : v - m;
; }
; __device__ __forceinline__ void phase_conv(KP p, int l, int tid) {
;     ...
;     for (int jb = j0; jb < j0 + 16; jb += CB) {
;       u32x2 an[CB][RB + 2], ur[CB][RB];
; #pragma unroll
;       for (int q = 0; q < CB; ++q) { const int col = jb + q + 1; const int cl = col > 63 ? 63 : col;
; #pragma unroll
;         for (int di = 0; di < RB + 2; ++di) an[q][di] = *(const u32x2*)(rowp[di] + (size_t)cl * DFF);
; #pragma unroll
;         for (int rr = 0; rr < RB; ++rr) ur[q][rr] = *(const u32x2*)(U + (size_t)((r0 + rr) * 64 + jb + q) * DFF + c0); }
;       __builtin_amdgcn_sched_barrier(0);
; #pragma unroll
;       for (int q = 0; q < CB; ++q) {
;         const int col = jb + q + 1;
; #pragma unroll
;         for (int di = 0; di < RB + 2; ++di) { const bool ok = rv[di] && (col < 64); unpack4(an[q][di], win[2][di]);
; #pragma unroll
;           for (int k = 0; k < 4; ++k) win[2][di][k] = ok ? win[2][di][k] : 0.f; }
; #pragma unroll
;         for (int rr = 0; rr < RB; ++rr) {
;           float uv[4]; unpack4(ur[q][rr], uv);
;           float o[4];
; #pragma unroll
;           for (int k = 0; k < 4; ++k) {
;             float a = bsv[k];
; #pragma unroll
;             for (int di = 0; di < 3; ++di)
; #pragma unroll
;               for (int dj = 0; dj < 3; ++dj) a += win[dj][rr + di][k] * w[di * 3 + dj][k];
;             o[k] = gelu_as(a) * uv[k];
;           }
;           u32x2 ow; ow.x = cvt_pk_bf16(o[0], o[1]); ow.y = cvt_pk_bf16(o[2], o[3]);
;           *(u32x2*)(G + (size_t)((r0 + rr) * 64 + jb + q) * DFF + c0) = ow;
	v_pk_fma_f32 v[172:173], v[164:165], v[188:189], v[190:191]
	v_pk_fma_f32 v[174:175], v[166:167], v[188:189], v[190:191]
	v_pk_fma_f32 v[176:177], v[168:169], v[188:189], v[190:191]
	v_pk_fma_f32 v[178:179], v[170:171], v[188:189], v[190:191]
	v_pk_fma_f32 v[172:173], v[172:173], v[164:165], v[192:193]
	v_pk_fma_f32 v[174:175], v[174:175], v[166:167], v[192:193]
	v_pk_fma_f32 v[176:177], v[176:177], v[168:169], v[192:193]
	v_pk_fma_f32 v[178:179], v[178:179], v[170:171], v[192:193]
	v_pk_fma_f32 v[172:173], v[172:173], v[164:165], v[194:195]
	v_pk_fma_f32 v[174:175], v[174:175], v[166:167], v[194:195]
	v_pk_fma_f32 v[176:177], v[176:177], v[168:169], v[194:195]
	v_pk_fma_f32 v[178:179], v[178:179], v[170:171], v[194:195]
	v_pk_fma_f32 v[172:173], v[172:173], v[164:165], v[196:197]
	v_pk_fma_f32 v[174:175], v[174:175], v[166:167], v[196:197]
	v_pk_fma_f32 v[176:177], v[176:177], v[168:169], v[196:197]
	v_pk_fma_f32 v[178:179], v[178:179], v[170:171], v[196:197]
	v_pk_mul_f32 v[172:173], v[172:173], v[164:165]
	v_pk_mul_f32 v[174:175], v[174:175], v[166:167]
	v_pk_mul_f32 v[176:177], v[176:177], v[168:169]
	v_pk_mul_f32 v[178:179], v[178:179], v[170:171]
	v_pk_mul_f32 v[164:165], v[148:149], v[148:149]
	v_pk_mul_f32 v[166:167], v[150:151], v[150:151]
	v_pk_mul_f32 v[168:169], v[152:153], v[152:153]
	v_pk_mul_f32 v[170:171], v[154:155], v[154:155]
	v_pk_mul_f32 v[164:165], v[164:165], v[198:199]
	v_pk_mul_f32 v[166:167], v[166:167], v[198:199]
	v_pk_mul_f32 v[168:169], v[168:169], v[198:199]
	v_pk_mul_f32 v[170:171], v[170:171], v[198:199]
	v_exp_f32_e32 v164, v164
	v_exp_f32_e32 v165, v165
	v_exp_f32_e32 v166, v166
	v_exp_f32_e32 v167, v167
	v_exp_f32_e32 v168, v168
	v_exp_f32_e32 v169, v169
	v_exp_f32_e32 v170, v170
	v_exp_f32_e32 v171, v171
	v_pk_mul_f32 v[172:173], v[172:173], v[164:165]
	v_pk_mul_f32 v[174:175], v[174:175], v[166:167]
	v_pk_mul_f32 v[176:177], v[176:177], v[168:169]
	v_pk_mul_f32 v[178:179], v[178:179], v[170:171]
	v_pk_mul_f32 v[172:173], v[156:157], v[172:173]
	v_pk_mul_f32 v[174:175], v[158:159], v[174:175]
	v_pk_mul_f32 v[176:177], v[160:161], v[176:177]
	v_pk_mul_f32 v[178:179], v[162:163], v[178:179]
	v_max_f32_e32 v164, 0, v148
	v_max_f32_e32 v165, 0, v149
	v_max_f32_e32 v166, 0, v150
	v_max_f32_e32 v167, 0, v151
	v_max_f32_e32 v168, 0, v152
	v_max_f32_e32 v169, 0, v153
	v_max_f32_e32 v170, 0, v154
	v_max_f32_e32 v171, 0, v155
	v_pk_add_f32 v[164:165], v[164:165], v[172:173] neg_lo:[0,1] neg_hi:[0,1]
	v_pk_add_f32 v[166:167], v[166:167], v[174:175] neg_lo:[0,1] neg_hi:[0,1]
	v_pk_add_f32 v[168:169], v[168:169], v[176:177] neg_lo:[0,1] neg_hi:[0,1]
	v_pk_add_f32 v[170:171], v[170:171], v[178:179] neg_lo:[0,1] neg_hi:[0,1]
	v_pk_mul_f32 v[164:165], v[164:165], v[124:125]
	v_pk_mul_f32 v[166:167], v[166:167], v[126:127]
	v_pk_mul_f32 v[168:169], v[168:169], v[128:129]
	v_pk_mul_f32 v[170:171], v[170:171], v[130:131]
	v_cvt_pk_bf16_f32 v156, v164, v165
	v_cvt_pk_bf16_f32 v157, v166, v167
	v_cvt_pk_bf16_f32 v158, v168, v169
	v_cvt_pk_bf16_f32 v159, v170, v171
	global_store_dwordx2 v218, v[156:157], s[10:11]
	global_store_dwordx2 v219, v[158:159], s[10:11]
	v_add_u32_e32 v210, 0x2c00, v210
	v_add_u32_e32 v211, 0x2c00, v210
	v_add_u32_e32 v212, v206, v211
	global_load_dwordx2 v[96:97], v212, s[6:7]
	v_add_u32_e32 v213, v207, v211
	global_load_dwordx2 v[98:99], v213, s[6:7]
	v_add_u32_e32 v214, v208, v211
	global_load_dwordx2 v[100:101], v214, s[6:7]
	v_add_u32_e32 v215, v209, v211
	global_load_dwordx2 v[102:103], v215, s[6:7]
	v_add_u32_e32 v218, v207, v210
	global_load_dwordx2 v[116:117], v218, s[8:9]
	v_add_u32_e32 v219, v208, v210
	global_load_dwordx2 v[118:119], v219, s[8:9]
	s_waitcnt vmcnt(16)
	v_lshlrev_b32_e32 v56, 16, v104
	v_and_b32_e32 v57, 0xffff0000, v104
	v_lshlrev_b32_e32 v58, 16, v105
	v_and_b32_e32 v59, 0xffff0000, v105
	v_lshlrev_b32_e32 v60, 16, v106
	v_and_b32_e32 v61, 0xffff0000, v106
	v_lshlrev_b32_e32 v62, 16, v107
	v_and_b32_e32 v63, 0xffff0000, v107
	v_lshlrev_b32_e32 v64, 16, v108
	v_and_b32_e32 v65, 0xffff0000, v108
	v_lshlrev_b32_e32 v66, 16, v109
	v_and_b32_e32 v67, 0xffff0000, v109
	v_lshlrev_b32_e32 v68, 16, v110
	v_and_b32_e32 v69, 0xffff0000, v110
	v_lshlrev_b32_e32 v70, 16, v111
	v_and_b32_e32 v71, 0xffff0000, v111
	v_pk_mul_f32 v[56:57], v[56:57], v[200:201]
	v_pk_mul_f32 v[58:59], v[58:59], v[200:201]
	v_pk_mul_f32 v[68:69], v[68:69], v[202:203]
	v_pk_mul_f32 v[70:71], v[70:71], v[202:203]
	v_lshlrev_b32_e32 v124, 16, v120
	v_and_b32_e32 v125, 0xffff0000, v120
	v_lshlrev_b32_e32 v126, 16, v121
	v_and_b32_e32 v127, 0xffff0000, v121
	v_lshlrev_b32_e32 v128, 16, v122
	v_and_b32_e32 v129, 0xffff0000, v122
	v_lshlrev_b32_e32 v130, 16, v123
	v_and_b32_e32 v131, 0xffff0000, v123
	v_pk_fma_f32 v[148:149], v[72:73], v[0:1], v[36:37]
	v_pk_fma_f32 v[150:151], v[74:75], v[2:3], v[38:39]
	v_pk_fma_f32 v[152:153], v[76:77], v[0:1], v[36:37]
	v_pk_fma_f32 v[154:155], v[78:79], v[2:3], v[38:39]
	v_pk_fma_f32 v[148:149], v[40:41], v[4:5], v[148:149]
	v_pk_fma_f32 v[150:151], v[42:43], v[6:7], v[150:151]
	v_pk_fma_f32 v[152:153], v[44:45], v[4:5], v[152:153]
	v_pk_fma_f32 v[154:155], v[46:47], v[6:7], v[154:155]
	v_pk_fma_f32 v[148:149], v[56:57], v[8:9], v[148:149]
	v_pk_fma_f32 v[150:151], v[58:59], v[10:11], v[150:151]
	v_pk_fma_f32 v[152:153], v[60:61], v[8:9], v[152:153]
	v_pk_fma_f32 v[154:155], v[62:63], v[10:11], v[154:155]
	v_pk_fma_f32 v[148:149], v[76:77], v[12:13], v[148:149]
	v_pk_fma_f32 v[150:151], v[78:79], v[14:15], v[150:151]
	v_pk_fma_f32 v[152:153], v[80:81], v[12:13], v[152:153]
	v_pk_fma_f32 v[154:155], v[82:83], v[14:15], v[154:155]
	v_pk_fma_f32 v[148:149], v[44:45], v[16:17], v[148:149]
; __device__ __forceinline__ unsigned cvt_pk_bf16(float lo, float hi) { unsigned r; asm volatile("v_cvt_pk_bf16_f32 %0, %1, %2" : "=v"(r) : "v"(lo), "v"(hi)); return r; }
; __device__ __forceinline__ float gelu_as(float v) {
;   const float av = fabsf(v); const float t = __builtin_amdgcn_rcpf(av * 0.2316418882f + 1.0f);
;   float q = t * 0.5307027145f + (-0.7265760135f); q = q * t + 0.7107068705f; q = q * t + (-0.142248368f); q = q * t + 0.127414796f; q = q * t;
;   const float e = __builtin_amdgcn_exp2f((v * v) * (-0.72134752044f));
;   const float m = v * (q * e);
;   return v < 0.f ? m : v - m;
; }
; __device__ __forceinline__ void phase_conv(KP p, int l, int tid) {
;     ...
;     for (int jb = j0; jb < j0 + 16; jb += CB) {
;       u32x2 an[CB][RB + 2], ur[CB][RB];
; #pragma unroll
;       for (int q = 0; q < CB; ++q) { const int col = jb + q + 1; const int cl = col > 63 ? 63 : col;
; #pragma unroll
;         for (int di = 0; di < RB + 2; ++di) an[q][di] = *(const u32x2*)(rowp[di] + (size_t)cl * DFF);
; #pragma unroll
;         for (int rr = 0; rr < RB; ++rr) ur[q][rr] = *(const u32x2*)(U + (size_t)((r0 + rr) * 64 + jb + q) * DFF + c0); }
;       __builtin_amdgcn_sched_barrier(0);
; #pragma unroll
;       for (int q = 0; q < CB; ++q) {
;         const int col = jb + q + 1;
; #pragma unroll
;         for (int di = 0; di < RB + 2; ++di) { const bool ok = rv[di] && (col < 64); unpack4(an[q][di], win[2][di]);
; #pragma unroll
;           for (int k = 0; k < 4; ++k) win[2][di][k] = ok ? win[2][di][k] : 0.f; }
; #pragma unroll
;         for (int rr = 0; rr < RB; ++rr) {
;           float uv[4]; unpack4(ur[q][rr], uv);
;           float o[4];
; #pragma unroll
;           for (int k = 0; k < 4; ++k) {
;             float a = bsv[k];
; #pragma unroll
;             for (int di = 0; di < 3; ++di)
; #pragma unroll
;               for (int dj = 0; dj < 3; ++dj) a += win[dj][rr + di][k] * w[di * 3 + dj][k];
;             o[k] = gelu_as(a) * uv[k];
;           }
;           u32x2 ow; ow.x = cvt_pk_bf16(o[0], o[1]); ow.y = cvt_pk_bf16(o[2], o[3]);
;           *(u32x2*)(G + (size_t)((r0 + rr) * 64 + jb + q) * DFF + c0) = ow;
	v_pk_fma_f32 v[150:151], v[46:47], v[18:19], v[150:151]
	v_pk_fma_f32 v[152:153], v[48:49], v[16:17], v[152:153]
	v_pk_fma_f32 v[154:155], v[50:51], v[18:19], v[154:155]
	v_pk_fma_f32 v[148:149], v[60:61], v[20:21], v[148:149]
	v_pk_fma_f32 v[150:151], v[62:63], v[22:23], v[150:151]
	v_pk_fma_f32 v[152:153], v[64:65], v[20:21], v[152:153]
	v_pk_fma_f32 v[154:155], v[66:67], v[22:23], v[154:155]
	v_pk_fma_f32 v[148:149], v[80:81], v[24:25], v[148:149]
	v_pk_fma_f32 v[150:151], v[82:83], v[26:27], v[150:151]
	v_pk_fma_f32 v[152:153], v[84:85], v[24:25], v[152:153]
	v_pk_fma_f32 v[154:155], v[86:87], v[26:27], v[154:155]
	v_pk_fma_f32 v[148:149], v[48:49], v[28:29], v[148:149]
	v_pk_fma_f32 v[150:151], v[50:51], v[30:31], v[150:151]
	v_pk_fma_f32 v[152:153], v[52:53], v[28:29], v[152:153]
	v_pk_fma_f32 v[154:155], v[54:55], v[30:31], v[154:155]
	v_pk_fma_f32 v[148:149], v[64:65], v[32:33], v[148:149]
	v_pk_fma_f32 v[150:151], v[66:67], v[34:35], v[150:151]
	v_pk_fma_f32 v[152:153], v[68:69], v[32:33], v[152:153]
	v_pk_fma_f32 v[154:155], v[70:71], v[34:35], v[154:155]
	v_and_b32_e32 v156, 0x7fffffff, v148
	v_and_b32_e32 v157, 0x7fffffff, v149
	v_and_b32_e32 v158, 0x7fffffff, v150
	v_and_b32_e32 v159, 0x7fffffff, v151
	v_and_b32_e32 v160, 0x7fffffff, v152
	v_and_b32_e32 v161, 0x7fffffff, v153
	v_and_b32_e32 v162, 0x7fffffff, v154
	v_and_b32_e32 v163, 0x7fffffff, v155
	v_pk_fma_f32 v[164:165], v[156:157], v[184:185], v[186:187]
	v_pk_fma_f32 v[166:167], v[158:159], v[184:185], v[186:187]
	v_pk_fma_f32 v[168:169], v[160:161], v[184:185], v[186:187]
	v_pk_fma_f32 v[170:171], v[162:163], v[184:185], v[186:187]
	v_rcp_f32_e32 v164, v164
	v_rcp_f32_e32 v165, v165
	v_rcp_f32_e32 v166, v166
	v_rcp_f32_e32 v167, v167
	v_rcp_f32_e32 v168, v168
	v_rcp_f32_e32 v169, v169
	v_rcp_f32_e32 v170, v170
	v_rcp_f32_e32 v171, v171
	v_pk_fma_f32 v[172:173], v[164:165], v[188:189], v[190:191]
	v_pk_fma_f32 v[174:175], v[166:167], v[188:189], v[190:191]
	v_pk_fma_f32 v[176:177], v[168:169], v[188:189], v[190:191]
	v_pk_fma_f32 v[178:179], v[170:171], v[188:189], v[190:191]
	v_pk_fma_f32 v[172:173], v[172:173], v[164:165], v[192:193]
	v_pk_fma_f32 v[174:175], v[174:175], v[166:167], v[192:193]
	v_pk_fma_f32 v[176:177], v[176:177], v[168:169], v[192:193]
	v_pk_fma_f32 v[178:179], v[178:179], v[170:171], v[192:193]
	v_pk_fma_f32 v[172:173], v[172:173], v[164:165], v[194:195]
	v_pk_fma_f32 v[174:175], v[174:175], v[166:167], v[194:195]
	v_pk_fma_f32 v[176:177], v[176:177], v[168:169], v[194:195]
	v_pk_fma_f32 v[178:179], v[178:179], v[170:171], v[194:195]
	v_pk_fma_f32 v[172:173], v[172:173], v[164:165], v[196:197]
	v_pk_fma_f32 v[174:175], v[174:175], v[166:167], v[196:197]
	v_pk_fma_f32 v[176:177], v[176:177], v[168:169], v[196:197]
	v_pk_fma_f32 v[178:179], v[178:179], v[170:171], v[196:197]
	v_pk_mul_f32 v[172:173], v[172:173], v[164:165]
	v_pk_mul_f32 v[174:175], v[174:175], v[166:167]
	v_pk_mul_f32 v[176:177], v[176:177], v[168:169]
	v_pk_mul_f32 v[178:179], v[178:179], v[170:171]
	v_pk_mul_f32 v[164:165], v[148:149], v[148:149]
	v_pk_mul_f32 v[166:167], v[150:151], v[150:151]
	v_pk_mul_f32 v[168:169], v[152:153], v[152:153]
	v_pk_mul_f32 v[170:171], v[154:155], v[154:155]
	v_pk_mul_f32 v[164:165], v[164:165], v[198:199]
	v_pk_mul_f32 v[166:167], v[166:167], v[198:199]
	v_pk_mul_f32 v[168:169], v[168:169], v[198:199]
	v_pk_mul_f32 v[170:171], v[170:171], v[198:199]
	v_exp_f32_e32 v164, v164
	v_exp_f32_e32 v165, v165
	v_exp_f32_e32 v166, v166
	v_exp_f32_e32 v167, v167
	v_exp_f32_e32 v168, v168
	v_exp_f32_e32 v169, v169
	v_exp_f32_e32 v170, v170
	v_exp_f32_e32 v171, v171
	v_pk_mul_f32 v[172:173], v[172:173], v[164:165]
	v_pk_mul_f32 v[174:175], v[174:175], v[166:167]
	v_pk_mul_f32 v[176:177], v[176:177], v[168:169]
	v_pk_mul_f32 v[178:179], v[178:179], v[170:171]
	v_pk_mul_f32 v[172:173], v[156:157], v[172:173]
	v_pk_mul_f32 v[174:175], v[158:159], v[174:175]
	v_pk_mul_f32 v[176:177], v[160:161], v[176:177]
	v_pk_mul_f32 v[178:179], v[162:163], v[178:179]
	v_max_f32_e32 v164, 0, v148
	v_max_f32_e32 v165, 0, v149
	v_max_f32_e32 v166, 0, v150
	v_max_f32_e32 v167, 0, v151
	v_max_f32_e32 v168, 0, v152
	v_max_f32_e32 v169, 0, v153
	v_max_f32_e32 v170, 0, v154
	v_max_f32_e32 v171, 0, v155
	v_pk_add_f32 v[164:165], v[164:165], v[172:173] neg_lo:[0,1] neg_hi:[0,1]
	v_pk_add_f32 v[166:167], v[166:167], v[174:175] neg_lo:[0,1] neg_hi:[0,1]
	v_pk_add_f32 v[168:169], v[168:169], v[176:177] neg_lo:[0,1] neg_hi:[0,1]
	v_pk_add_f32 v[170:171], v[170:171], v[178:179] neg_lo:[0,1] neg_hi:[0,1]
	v_pk_mul_f32 v[164:165], v[164:165], v[124:125]
	v_pk_mul_f32 v[166:167], v[166:167], v[126:127]
	v_pk_mul_f32 v[168:169], v[168:169], v[128:129]
	v_pk_mul_f32 v[170:171], v[170:171], v[130:131]
	v_cvt_pk_bf16_f32 v156, v164, v165
	v_cvt_pk_bf16_f32 v157, v166, v167
	v_cvt_pk_bf16_f32 v158, v168, v169
	v_cvt_pk_bf16_f32 v159, v170, v171
	global_store_dwordx2 v220, v[156:157], s[10:11]
	global_store_dwordx2 v221, v[158:159], s[10:11]
	v_add_u32_e32 v210, 0x2c00, v210
	v_add_u32_e32 v211, 0x2c00, v210
	v_add_u32_e32 v212, v206, v211
	global_load_dwordx2 v[104:105], v212, s[6:7]
	v_add_u32_e32 v213, v207, v211
	global_load_dwordx2 v[106:107], v213, s[6:7]
	v_add_u32_e32 v214, v208, v211
	global_load_dwordx2 v[108:109], v214, s[6:7]
	v_add_u32_e32 v215, v209, v211
	global_load_dwordx2 v[110:111], v215, s[6:7]
	v_add_u32_e32 v220, v207, v210
	global_load_dwordx2 v[120:121], v220, s[8:9]
	v_add_u32_e32 v221, v208, v210
	global_load_dwordx2 v[122:123], v221, s[8:9]
	s_waitcnt vmcnt(16)
; __device__ __forceinline__ unsigned cvt_pk_bf16(float lo, float hi) { unsigned r; asm volatile("v_cvt_pk_bf16_f32 %0, %1, %2" : "=v"(r) : "v"(lo), "v"(hi)); return r; }
; __device__ __forceinline__ float gelu_as(float v) {
;   const float av = fabsf(v); const float t = __builtin_amdgcn_rcpf(av * 0.2316418882f + 1.0f);
;   float q = t * 0.5307027145f + (-0.7265760135f); q = q * t + 0.7107068705f; q = q * t + (-0.142248368f); q = q * t + 0.127414796f; q = q * t;
;   const float e = __builtin_amdgcn_exp2f((v * v) * (-0.72134752044f));
;   const float m = v * (q * e);
;   return v < 0.f ? m : v - m;
; }
; __device__ __forceinline__ void phase_conv(KP p, int l, int tid) {
;     ...
;     for (int jb = j0; jb < j0 + 16; jb += CB) {
;       u32x2 an[CB][RB + 2], ur[CB][RB];
; #pragma unroll
;       for (int q = 0; q < CB; ++q) { const int col = jb + q + 1; const int cl = col > 63 ? 63 : col;
; #pragma unroll
;         for (int di = 0; di < RB + 2; ++di) an[q][di] = *(const u32x2*)(rowp[di] + (size_t)cl * DFF);
; #pragma unroll
;         for (int rr = 0; rr < RB; ++rr) ur[q][rr] = *(const u32x2*)(U + (size_t)((r0 + rr) * 64 + jb + q) * DFF + c0); }
;       __builtin_amdgcn_sched_barrier(0);
; #pragma unroll
;       for (int q = 0; q < CB; ++q) {
;         const int col = jb + q + 1;
; #pragma unroll
;         for (int di = 0; di < RB + 2; ++di) { const bool ok = rv[di] && (col < 64); unpack4(an[q][di], win[2][di]);
; #pragma unroll
;           for (int k = 0; k < 4; ++k) win[2][di][k] = ok ? win[2][di][k] : 0.f; }
; #pragma unroll
;         for (int rr = 0; rr < RB; ++rr) {
;           float uv[4]; unpack4(ur[q][rr], uv);
;           float o[4];
; #pragma unroll
;           for (int k = 0; k < 4; ++k) {
;             float a = bsv[k];
; #pragma unroll
;             for (int di = 0; di < 3; ++di)
; #pragma unroll
;               for (int dj = 0; dj < 3; ++dj) a += win[dj][rr + di][k] * w[di * 3 + dj][k];
;             o[k] = gelu_as(a) * uv[k];
;           }
;           u32x2 ow; ow.x = cvt_pk_bf16(o[0], o[1]); ow.y = cvt_pk_bf16(o[2], o[3]);
;           *(u32x2*)(G + (size_t)((r0 + rr) * 64 + jb + q) * DFF + c0) = ow;
	v_lshlrev_b32_e32 v72, 16, v88
	v_and_b32_e32 v73, 0xffff0000, v88
	v_lshlrev_b32_e32 v74, 16, v89
	v_and_b32_e32 v75, 0xffff0000, v89
	v_lshlrev_b32_e32 v76, 16, v90
	v_and_b32_e32 v77, 0xffff0000, v90
	v_lshlrev_b32_e32 v78, 16, v91
	v_and_b32_e32 v79, 0xffff0000, v91
	v_lshlrev_b32_e32 v80, 16, v92
	v_and_b32_e32 v81, 0xffff0000, v92
	v_lshlrev_b32_e32 v82, 16, v93
	v_and_b32_e32 v83, 0xffff0000, v93
	v_lshlrev_b32_e32 v84, 16, v94
	v_and_b32_e32 v85, 0xffff0000, v94
	v_lshlrev_b32_e32 v86, 16, v95
	v_and_b32_e32 v87, 0xffff0000, v95
	v_pk_mul_f32 v[72:73], v[72:73], v[200:201]
	v_pk_mul_f32 v[74:75], v[74:75], v[200:201]
	v_pk_mul_f32 v[84:85], v[84:85], v[202:203]
	v_pk_mul_f32 v[86:87], v[86:87], v[202:203]
	v_lshlrev_b32_e32 v124, 16, v112
	v_and_b32_e32 v125, 0xffff0000, v112
	v_lshlrev_b32_e32 v126, 16, v113
	v_and_b32_e32 v127, 0xffff0000, v113
	v_lshlrev_b32_e32 v128, 16, v114
	v_and_b32_e32 v129, 0xffff0000, v114
	v_lshlrev_b32_e32 v130, 16, v115
	v_and_b32_e32 v131, 0xffff0000, v115
	v_pk_fma_f32 v[148:149], v[40:41], v[0:1], v[36:37]
	v_pk_fma_f32 v[150:151], v[42:43], v[2:3], v[38:39]
	v_pk_fma_f32 v[152:153], v[44:45], v[0:1], v[36:37]
	v_pk_fma_f32 v[154:155], v[46:47], v[2:3], v[38:39]
	v_pk_fma_f32 v[148:149], v[56:57], v[4:5], v[148:149]
	v_pk_fma_f32 v[150:151], v[58:59], v[6:7], v[150:151]
	v_pk_fma_f32 v[152:153], v[60:61], v[4:5], v[152:153]
	v_pk_fma_f32 v[154:155], v[62:63], v[6:7], v[154:155]
	v_pk_fma_f32 v[148:149], v[72:73], v[8:9], v[148:149]
	v_pk_fma_f32 v[150:151], v[74:75], v[10:11], v[150:151]
	v_pk_fma_f32 v[152:153], v[76:77], v[8:9], v[152:153]
	v_pk_fma_f32 v[154:155], v[78:79], v[10:11], v[154:155]
	v_pk_fma_f32 v[148:149], v[44:45], v[12:13], v[148:149]
	v_pk_fma_f32 v[150:151], v[46:47], v[14:15], v[150:151]
	v_pk_fma_f32 v[152:153], v[48:49], v[12:13], v[152:153]
	v_pk_fma_f32 v[154:155], v[50:51], v[14:15], v[154:155]
	v_pk_fma_f32 v[148:149], v[60:61], v[16:17], v[148:149]
	v_pk_fma_f32 v[150:151], v[62:63], v[18:19], v[150:151]
	v_pk_fma_f32 v[152:153], v[64:65], v[16:17], v[152:153]
	v_pk_fma_f32 v[154:155], v[66:67], v[18:19], v[154:155]
	v_pk_fma_f32 v[148:149], v[76:77], v[20:21], v[148:149]
	v_pk_fma_f32 v[150:151], v[78:79], v[22:23], v[150:151]
	v_pk_fma_f32 v[152:153], v[80:81], v[20:21], v[152:153]
	v_pk_fma_f32 v[154:155], v[82:83], v[22:23], v[154:155]
	v_pk_fma_f32 v[148:149], v[48:49], v[24:25], v[148:149]
	v_pk_fma_f32 v[150:151], v[50:51], v[26:27], v[150:151]
	v_pk_fma_f32 v[152:153], v[52:53], v[24:25], v[152:153]
	v_pk_fma_f32 v[154:155], v[54:55], v[26:27], v[154:155]
	v_pk_fma_f32 v[148:149], v[64:65], v[28:29], v[148:149]
	v_pk_fma_f32 v[150:151], v[66:67], v[30:31], v[150:151]
	v_pk_fma_f32 v[152:153], v[68:69], v[28:29], v[152:153]
	v_pk_fma_f32 v[154:155], v[70:71], v[30:31], v[154:155]
	v_pk_fma_f32 v[148:149], v[80:81], v[32:33], v[148:149]
	v_pk_fma_f32 v[150:151], v[82:83], v[34:35], v[150:151]
	v_pk_fma_f32 v[152:153], v[84:85], v[32:33], v[152:153]
	v_pk_fma_f32 v[154:155], v[86:87], v[34:35], v[154:155]
	v_and_b32_e32 v156, 0x7fffffff, v148
	v_and_b32_e32 v157, 0x7fffffff, v149
	v_and_b32_e32 v158, 0x7fffffff, v150
	v_and_b32_e32 v159, 0x7fffffff, v151
	v_and_b32_e32 v160, 0x7fffffff, v152
	v_and_b32_e32 v161, 0x7fffffff, v153
	v_and_b32_e32 v162, 0x7fffffff, v154
	v_and_b32_e32 v163, 0x7fffffff, v155
	v_pk_fma_f32 v[164:165], v[156:157], v[184:185], v[186:187]
	v_pk_fma_f32 v[166:167], v[158:159], v[184:185], v[186:187]
	v_pk_fma_f32 v[168:169], v[160:161], v[184:185], v[186:187]
	v_pk_fma_f32 v[170:171], v[162:163], v[184:185], v[186:187]
	v_rcp_f32_e32 v164, v164
	v_rcp_f32_e32 v165, v165
	v_rcp_f32_e32 v166, v166
	v_rcp_f32_e32 v167, v167
	v_rcp_f32_e32 v168, v168
	v_rcp_f32_e32 v169, v169
	v_rcp_f32_e32 v170, v170
	v_rcp_f32_e32 v171, v171
	v_pk_fma_f32 v[172:173], v[164:165], v[188:189], v[190:191]
	v_pk_fma_f32 v[174:175], v[166:167], v[188:189], v[190:191]
	v_pk_fma_f32 v[176:177], v[168:169], v[188:189], v[190:191]
	v_pk_fma_f32 v[178:179], v[170:171], v[188:189], v[190:191]
	v_pk_fma_f32 v[172:173], v[172:173], v[164:165], v[192:193]
	v_pk_fma_f32 v[174:175], v[174:175], v[166:167], v[192:193]
	v_pk_fma_f32 v[176:177], v[176:177], v[168:169], v[192:193]
	v_pk_fma_f32 v[178:179], v[178:179], v[170:171], v[192:193]
	v_pk_fma_f32 v[172:173], v[172:173], v[164:165], v[194:195]
	v_pk_fma_f32 v[174:175], v[174:175], v[166:167], v[194:195]
	v_pk_fma_f32 v[176:177], v[176:177], v[168:169], v[194:195]
	v_pk_fma_f32 v[178:179], v[178:179], v[170:171], v[194:195]
	v_pk_fma_f32 v[172:173], v[172:173], v[164:165], v[196:197]
	v_pk_fma_f32 v[174:175], v[174:175], v[166:167], v[196:197]
	v_pk_fma_f32 v[176:177], v[176:177], v[168:169], v[196:197]
	v_pk_fma_f32 v[178:179], v[178:179], v[170:171], v[196:197]
	v_pk_mul_f32 v[172:173], v[172:173], v[164:165]
	v_pk_mul_f32 v[174:175], v[174:175], v[166:167]
	v_pk_mul_f32 v[176:177], v[176:177], v[168:169]
	v_pk_mul_f32 v[178:179], v[178:179], v[170:171]
	v_pk_mul_f32 v[164:165], v[148:149], v[148:149]
	v_pk_mul_f32 v[166:167], v[150:151], v[150:151]
	v_pk_mul_f32 v[168:169], v[152:153], v[152:153]
	v_pk_mul_f32 v[170:171], v[154:155], v[154:155]
	v_pk_mul_f32 v[164:165], v[164:165], v[198:199]
	v_pk_mul_f32 v[166:167], v[166:167], v[198:199]
	v_pk_mul_f32 v[168:169], v[168:169], v[198:199]
	v_pk_mul_f32 v[170:171], v[170:171], v[198:199]
	v_exp_f32_e32 v164, v164
	v_exp_f32_e32 v165, v165
	v_exp_f32_e32 v166, v166
	v_exp_f32_e32 v167, v167
	v_exp_f32_e32 v168, v168
	v_exp_f32_e32 v169, v169
	v_exp_f32_e32 v170, v170
	v_exp_f32_e32 v171, v171
	v_pk_mul_f32 v[172:173], v[172:173], v[164:165]
	v_pk_mul_f32 v[174:175], v[174:175], v[166:167]
; __device__ __forceinline__ unsigned cvt_pk_bf16(float lo, float hi) { unsigned r; asm volatile("v_cvt_pk_bf16_f32 %0, %1, %2" : "=v"(r) : "v"(lo), "v"(hi)); return r; }
; __device__ __forceinline__ float gelu_as(float v) {
;   const float av = fabsf(v); const float t = __builtin_amdgcn_rcpf(av * 0.2316418882f + 1.0f);
;   float q = t * 0.5307027145f + (-0.7265760135f); q = q * t + 0.7107068705f; q = q * t + (-0.142248368f); q = q * t + 0.127414796f; q = q * t;
;   const float e = __builtin_amdgcn_exp2f((v * v) * (-0.72134752044f));
;   const float m = v * (q * e);
;   return v < 0.f ? m : v - m;
; }
; __device__ __forceinline__ void phase_conv(KP p, int l, int tid) {
;     ...
;     for (int jb = j0; jb < j0 + 16; jb += CB) {
;       u32x2 an[CB][RB + 2], ur[CB][RB];
; #pragma unroll
;       for (int q = 0; q < CB; ++q) { const int col = jb + q + 1; const int cl = col > 63 ? 63 : col;
; #pragma unroll
;         for (int di = 0; di < RB + 2; ++di) an[q][di] = *(const u32x2*)(rowp[di] + (size_t)cl * DFF);
; #pragma unroll
;         for (int rr = 0; rr < RB; ++rr) ur[q][rr] = *(const u32x2*)(U + (size_t)((r0 + rr) * 64 + jb + q) * DFF + c0); }
;       __builtin_amdgcn_sched_barrier(0);
; #pragma unroll
;       for (int q = 0; q < CB; ++q) {
;         const int col = jb + q + 1;
; #pragma unroll
;         for (int di = 0; di < RB + 2; ++di) { const bool ok = rv[di] && (col < 64); unpack4(an[q][di], win[2][di]);
; #pragma unroll
;           for (int k = 0; k < 4; ++k) win[2][di][k] = ok ? win[2][di][k] : 0.f; }
; #pragma unroll
;         for (int rr = 0; rr < RB; ++rr) {
;           float uv[4]; unpack4(ur[q][rr], uv);
;           float o[4];
; #pragma unroll
;           for (int k = 0; k < 4; ++k) {
;             float a = bsv[k];
; #pragma unroll
;             for (int di = 0; di < 3; ++di)
; #pragma unroll
;               for (int dj = 0; dj < 3; ++dj) a += win[dj][rr + di][k] * w[di * 3 + dj][k];
;             o[k] = gelu_as(a) * uv[k];
;           }
;           u32x2 ow; ow.x = cvt_pk_bf16(o[0], o[1]); ow.y = cvt_pk_bf16(o[2], o[3]);
;           *(u32x2*)(G + (size_t)((r0 + rr) * 64 + jb + q) * DFF + c0) = ow;
;         }
; #pragma unroll
;         for (int di = 0; di < RB + 2; ++di)
; #pragma unroll
;           for (int k = 0; k < 4; ++k) { win[0][di][k] = win[1][di][k]; win[1][di][k] = win[2][di][k]; }
;       }
	v_pk_mul_f32 v[176:177], v[176:177], v[168:169]
	v_pk_mul_f32 v[178:179], v[178:179], v[170:171]
	v_pk_mul_f32 v[172:173], v[156:157], v[172:173]
	v_pk_mul_f32 v[174:175], v[158:159], v[174:175]
	v_pk_mul_f32 v[176:177], v[160:161], v[176:177]
	v_pk_mul_f32 v[178:179], v[162:163], v[178:179]
	v_max_f32_e32 v164, 0, v148
	v_max_f32_e32 v165, 0, v149
	v_max_f32_e32 v166, 0, v150
	v_max_f32_e32 v167, 0, v151
	v_max_f32_e32 v168, 0, v152
	v_max_f32_e32 v169, 0, v153
	v_max_f32_e32 v170, 0, v154
	v_max_f32_e32 v171, 0, v155
	v_pk_add_f32 v[164:165], v[164:165], v[172:173] neg_lo:[0,1] neg_hi:[0,1]
	v_pk_add_f32 v[166:167], v[166:167], v[174:175] neg_lo:[0,1] neg_hi:[0,1]
	v_pk_add_f32 v[168:169], v[168:169], v[176:177] neg_lo:[0,1] neg_hi:[0,1]
	v_pk_add_f32 v[170:171], v[170:171], v[178:179] neg_lo:[0,1] neg_hi:[0,1]
	v_pk_mul_f32 v[164:165], v[164:165], v[124:125]
	v_pk_mul_f32 v[166:167], v[166:167], v[126:127]
	v_pk_mul_f32 v[168:169], v[168:169], v[128:129]
	v_pk_mul_f32 v[170:171], v[170:171], v[130:131]
	v_cvt_pk_bf16_f32 v156, v164, v165
	v_cvt_pk_bf16_f32 v157, v166, v167
	v_cvt_pk_bf16_f32 v158, v168, v169
	v_cvt_pk_bf16_f32 v159, v170, v171
	global_store_dwordx2 v216, v[156:157], s[10:11]
	global_store_dwordx2 v217, v[158:159], s[10:11]
	v_add_u32_e32 v210, 0x2c00, v210
	v_add_u32_e32 v211, 0x2c00, v210
	v_add_u32_e32 v212, v206, v211
	global_load_dwordx2 v[88:89], v212, s[6:7]
	v_add_u32_e32 v213, v207, v211
	global_load_dwordx2 v[90:91], v213, s[6:7]
	v_add_u32_e32 v214, v208, v211
	global_load_dwordx2 v[92:93], v214, s[6:7]
	v_add_u32_e32 v215, v209, v211
	global_load_dwordx2 v[94:95], v215, s[6:7]
	v_add_u32_e32 v216, v207, v210
	global_load_dwordx2 v[112:113], v216, s[8:9]
	v_add_u32_e32 v217, v208, v210
	global_load_dwordx2 v[114:115], v217, s[8:9]
	s_waitcnt vmcnt(16)
	v_lshlrev_b32_e32 v40, 16, v96
	v_and_b32_e32 v41, 0xffff0000, v96
	v_lshlrev_b32_e32 v42, 16, v97
	v_and_b32_e32 v43, 0xffff0000, v97
	v_lshlrev_b32_e32 v44, 16, v98
	v_and_b32_e32 v45, 0xffff0000, v98
	v_lshlrev_b32_e32 v46, 16, v99
	v_and_b32_e32 v47, 0xffff0000, v99
	v_lshlrev_b32_e32 v48, 16, v100
	v_and_b32_e32 v49, 0xffff0000, v100
	v_lshlrev_b32_e32 v50, 16, v101
	v_and_b32_e32 v51, 0xffff0000, v101
	v_lshlrev_b32_e32 v52, 16, v102
	v_and_b32_e32 v53, 0xffff0000, v102
	v_lshlrev_b32_e32 v54, 16, v103
	v_and_b32_e32 v55, 0xffff0000, v103
	v_pk_mul_f32 v[40:41], v[40:41], v[200:201]
	v_pk_mul_f32 v[42:43], v[42:43], v[200:201]
	v_pk_mul_f32 v[52:53], v[52:53], v[202:203]
	v_pk_mul_f32 v[54:55], v[54:55], v[202:203]
	v_lshlrev_b32_e32 v124, 16, v116
	v_and_b32_e32 v125, 0xffff0000, v116
	v_lshlrev_b32_e32 v126, 16, v117
	v_and_b32_e32 v127, 0xffff0000, v117
	v_lshlrev_b32_e32 v128, 16, v118
	v_and_b32_e32 v129, 0xffff0000, v118
	v_lshlrev_b32_e32 v130, 16, v119
	v_and_b32_e32 v131, 0xffff0000, v119
	v_pk_fma_f32 v[148:149], v[56:57], v[0:1], v[36:37]
	v_pk_fma_f32 v[150:151], v[58:59], v[2:3], v[38:39]
	v_pk_fma_f32 v[152:153], v[60:61], v[0:1], v[36:37]
	v_pk_fma_f32 v[154:155], v[62:63], v[2:3], v[38:39]
	v_pk_fma_f32 v[148:149], v[72:73], v[4:5], v[148:149]
	v_pk_fma_f32 v[150:151], v[74:75], v[6:7], v[150:151]
	v_pk_fma_f32 v[152:153], v[76:77], v[4:5], v[152:153]
	v_pk_fma_f32 v[154:155], v[78:79], v[6:7], v[154:155]
	v_pk_fma_f32 v[148:149], v[40:41], v[8:9], v[148:149]
	v_pk_fma_f32 v[150:151], v[42:43], v[10:11], v[150:151]
	v_pk_fma_f32 v[152:153], v[44:45], v[8:9], v[152:153]
	v_pk_fma_f32 v[154:155], v[46:47], v[10:11], v[154:155]
	v_pk_fma_f32 v[148:149], v[60:61], v[12:13], v[148:149]
	v_pk_fma_f32 v[150:151], v[62:63], v[14:15], v[150:151]
	v_pk_fma_f32 v[152:153], v[64:65], v[12:13], v[152:153]
	v_pk_fma_f32 v[154:155], v[66:67], v[14:15], v[154:155]
	v_pk_fma_f32 v[148:149], v[76:77], v[16:17], v[148:149]
	v_pk_fma_f32 v[150:151], v[78:79], v[18:19], v[150:151]
	v_pk_fma_f32 v[152:153], v[80:81], v[16:17], v[152:153]
	v_pk_fma_f32 v[154:155], v[82:83], v[18:19], v[154:155]
	v_pk_fma_f32 v[148:149], v[44:45], v[20:21], v[148:149]
	v_pk_fma_f32 v[150:151], v[46:47], v[22:23], v[150:151]
	v_pk_fma_f32 v[152:153], v[48:49], v[20:21], v[152:153]
	v_pk_fma_f32 v[154:155], v[50:51], v[22:23], v[154:155]
	v_pk_fma_f32 v[148:149], v[64:65], v[24:25], v[148:149]
	v_pk_fma_f32 v[150:151], v[66:67], v[26:27], v[150:151]
	v_pk_fma_f32 v[152:153], v[68:69], v[24:25], v[152:153]
	v_pk_fma_f32 v[154:155], v[70:71], v[26:27], v[154:155]
	v_pk_fma_f32 v[148:149], v[80:81], v[28:29], v[148:149]
	v_pk_fma_f32 v[150:151], v[82:83], v[30:31], v[150:151]
	v_pk_fma_f32 v[152:153], v[84:85], v[28:29], v[152:153]
	v_pk_fma_f32 v[154:155], v[86:87], v[30:31], v[154:155]
	v_pk_fma_f32 v[148:149], v[48:49], v[32:33], v[148:149]
	v_pk_fma_f32 v[150:151], v[50:51], v[34:35], v[150:151]
	v_pk_fma_f32 v[152:153], v[52:53], v[32:33], v[152:153]
	v_pk_fma_f32 v[154:155], v[54:55], v[34:35], v[154:155]
	v_and_b32_e32 v156, 0x7fffffff, v148
	v_and_b32_e32 v157, 0x7fffffff, v149
	v_and_b32_e32 v158, 0x7fffffff, v150
	v_and_b32_e32 v159, 0x7fffffff, v151
	v_and_b32_e32 v160, 0x7fffffff, v152
	v_and_b32_e32 v161, 0x7fffffff, v153
	v_and_b32_e32 v162, 0x7fffffff, v154
	v_and_b32_e32 v163, 0x7fffffff, v155
	v_pk_fma_f32 v[164:165], v[156:157], v[184:185], v[186:187]
	v_pk_fma_f32 v[166:167], v[158:159], v[184:185], v[186:187]
	v_pk_fma_f32 v[168:169], v[160:161], v[184:185], v[186:187]
	v_pk_fma_f32 v[170:171], v[162:163], v[184:185], v[186:187]
	v_rcp_f32_e32 v164, v164
	v_rcp_f32_e32 v165, v165
	v_rcp_f32_e32 v166, v166
	v_rcp_f32_e32 v167, v167
	v_rcp_f32_e32 v168, v168
	v_rcp_f32_e32 v169, v169
	v_rcp_f32_e32 v170, v170
	v_rcp_f32_e32 v171, v171
; __device__ __forceinline__ unsigned cvt_pk_bf16(float lo, float hi) { unsigned r; asm volatile("v_cvt_pk_bf16_f32 %0, %1, %2" : "=v"(r) : "v"(lo), "v"(hi)); return r; }
; __device__ __forceinline__ float gelu_as(float v) {
;   const float av = fabsf(v); const float t = __builtin_amdgcn_rcpf(av * 0.2316418882f + 1.0f);
;   float q = t * 0.5307027145f + (-0.7265760135f); q = q * t + 0.7107068705f; q = q * t + (-0.142248368f); q = q * t + 0.127414796f; q = q * t;
;   const float e = __builtin_amdgcn_exp2f((v * v) * (-0.72134752044f));
;   const float m = v * (q * e);
;   return v < 0.f ? m : v - m;
; }
; __device__ __forceinline__ void phase_conv(KP p, int l, int tid) {
;     ...
;     for (int jb = j0; jb < j0 + 16; jb += CB) {
;       u32x2 an[CB][RB + 2], ur[CB][RB];
; #pragma unroll
;       for (int q = 0; q < CB; ++q) { const int col = jb + q + 1; const int cl = col > 63 ? 63 : col;
; #pragma unroll
;         for (int di = 0; di < RB + 2; ++di) an[q][di] = *(const u32x2*)(rowp[di] + (size_t)cl * DFF);
; #pragma unroll
;         for (int rr = 0; rr < RB; ++rr) ur[q][rr] = *(const u32x2*)(U + (size_t)((r0 + rr) * 64 + jb + q) * DFF + c0); }
;       __builtin_amdgcn_sched_barrier(0);
; #pragma unroll
;       for (int q = 0; q < CB; ++q) {
;         const int col = jb + q + 1;
; #pragma unroll
;         for (int di = 0; di < RB + 2; ++di) { const bool ok = rv[di] && (col < 64); unpack4(an[q][di], win[2][di]);
; #pragma unroll
;           for (int k = 0; k < 4; ++k) win[2][di][k] = ok ? win[2][di][k] : 0.f; }
; #pragma unroll
;         for (int rr = 0; rr < RB; ++rr) {
;           float uv[4]; unpack4(ur[q][rr], uv);
;           float o[4];
; #pragma unroll
;           for (int k = 0; k < 4; ++k) {
;             float a = bsv[k];
; #pragma unroll
;             for (int di = 0; di < 3; ++di)
; #pragma unroll
;               for (int dj = 0; dj < 3; ++dj) a += win[dj][rr + di][k] * w[di * 3 + dj][k];
;             o[k] = gelu_as(a) * uv[k];
;           }
;           u32x2 ow; ow.x = cvt_pk_bf16(o[0], o[1]); ow.y = cvt_pk_bf16(o[2], o[3]);
;           *(u32x2*)(G + (size_t)((r0 + rr) * 64 + jb + q) * DFF + c0) = ow;
;         }
; #pragma unroll
;         for (int di = 0; di < RB + 2; ++di)
; #pragma unroll
;           for (int k = 0; k < 4; ++k) { win[0][di][k] = win[1][di][k]; win[1][di][k] = win[2][di][k]; }
;       }
	v_pk_fma_f32 v[172:173], v[164:165], v[188:189], v[190:191]
	v_pk_fma_f32 v[174:175], v[166:167], v[188:189], v[190:191]
	v_pk_fma_f32 v[176:177], v[168:169], v[188:189], v[190:191]
	v_pk_fma_f32 v[178:179], v[170:171], v[188:189], v[190:191]
	v_pk_fma_f32 v[172:173], v[172:173], v[164:165], v[192:193]
	v_pk_fma_f32 v[174:175], v[174:175], v[166:167], v[192:193]
	v_pk_fma_f32 v[176:177], v[176:177], v[168:169], v[192:193]
	v_pk_fma_f32 v[178:179], v[178:179], v[170:171], v[192:193]
	v_pk_fma_f32 v[172:173], v[172:173], v[164:165], v[194:195]
	v_pk_fma_f32 v[174:175], v[174:175], v[166:167], v[194:195]
	v_pk_fma_f32 v[176:177], v[176:177], v[168:169], v[194:195]
	v_pk_fma_f32 v[178:179], v[178:179], v[170:171], v[194:195]
	v_pk_fma_f32 v[172:173], v[172:173], v[164:165], v[196:197]
	v_pk_fma_f32 v[174:175], v[174:175], v[166:167], v[196:197]
	v_pk_fma_f32 v[176:177], v[176:177], v[168:169], v[196:197]
	v_pk_fma_f32 v[178:179], v[178:179], v[170:171], v[196:197]
	v_pk_mul_f32 v[172:173], v[172:173], v[164:165]
	v_pk_mul_f32 v[174:175], v[174:175], v[166:167]
	v_pk_mul_f32 v[176:177], v[176:177], v[168:169]
	v_pk_mul_f32 v[178:179], v[178:179], v[170:171]
	v_pk_mul_f32 v[164:165], v[148:149], v[148:149]
	v_pk_mul_f32 v[166:167], v[150:151], v[150:151]
	v_pk_mul_f32 v[168:169], v[152:153], v[152:153]
	v_pk_mul_f32 v[170:171], v[154:155], v[154:155]
	v_pk_mul_f32 v[164:165], v[164:165], v[198:199]
	v_pk_mul_f32 v[166:167], v[166:167], v[198:199]
	v_pk_mul_f32 v[168:169], v[168:169], v[198:199]
	v_pk_mul_f32 v[170:171], v[170:171], v[198:199]
	v_exp_f32_e32 v164, v164
	v_exp_f32_e32 v165, v165
	v_exp_f32_e32 v166, v166
	v_exp_f32_e32 v167, v167
	v_exp_f32_e32 v168, v168
	v_exp_f32_e32 v169, v169
	v_exp_f32_e32 v170, v170
	v_exp_f32_e32 v171, v171
	v_pk_mul_f32 v[172:173], v[172:173], v[164:165]
	v_pk_mul_f32 v[174:175], v[174:175], v[166:167]
	v_pk_mul_f32 v[176:177], v[176:177], v[168:169]
	v_pk_mul_f32 v[178:179], v[178:179], v[170:171]
	v_pk_mul_f32 v[172:173], v[156:157], v[172:173]
	v_pk_mul_f32 v[174:175], v[158:159], v[174:175]
	v_pk_mul_f32 v[176:177], v[160:161], v[176:177]
	v_pk_mul_f32 v[178:179], v[162:163], v[178:179]
	v_max_f32_e32 v164, 0, v148
	v_max_f32_e32 v165, 0, v149
	v_max_f32_e32 v166, 0, v150
	v_max_f32_e32 v167, 0, v151
	v_max_f32_e32 v168, 0, v152
	v_max_f32_e32 v169, 0, v153
	v_max_f32_e32 v170, 0, v154
	v_max_f32_e32 v171, 0, v155
	v_pk_add_f32 v[164:165], v[164:165], v[172:173] neg_lo:[0,1] neg_hi:[0,1]
	v_pk_add_f32 v[166:167], v[166:167], v[174:175] neg_lo:[0,1] neg_hi:[0,1]
	v_pk_add_f32 v[168:169], v[168:169], v[176:177] neg_lo:[0,1] neg_hi:[0,1]
	v_pk_add_f32 v[170:171], v[170:171], v[178:179] neg_lo:[0,1] neg_hi:[0,1]
	v_pk_mul_f32 v[164:165], v[164:165], v[124:125]
	v_pk_mul_f32 v[166:167], v[166:167], v[126:127]
	v_pk_mul_f32 v[168:169], v[168:169], v[128:129]
	v_pk_mul_f32 v[170:171], v[170:171], v[130:131]
	v_cvt_pk_bf16_f32 v156, v164, v165
	v_cvt_pk_bf16_f32 v157, v166, v167
	v_cvt_pk_bf16_f32 v158, v168, v169
	v_cvt_pk_bf16_f32 v159, v170, v171
	global_store_dwordx2 v218, v[156:157], s[10:11]
	global_store_dwordx2 v219, v[158:159], s[10:11]
	v_add_u32_e32 v210, 0x2c00, v210
	v_add_u32_e32 v211, 0x2c00, v210
	v_add_u32_e32 v212, v206, v211
	global_load_dwordx2 v[96:97], v212, s[6:7]
	v_add_u32_e32 v213, v207, v211
	global_load_dwordx2 v[98:99], v213, s[6:7]
	v_add_u32_e32 v214, v208, v211
	global_load_dwordx2 v[100:101], v214, s[6:7]
	v_add_u32_e32 v215, v209, v211
	global_load_dwordx2 v[102:103], v215, s[6:7]
	v_add_u32_e32 v218, v207, v210
	global_load_dwordx2 v[116:117], v218, s[8:9]
	v_add_u32_e32 v219, v208, v210
	global_load_dwordx2 v[118:119], v219, s[8:9]
	s_waitcnt vmcnt(16)
	v_lshlrev_b32_e32 v56, 16, v104
	v_and_b32_e32 v57, 0xffff0000, v104
	v_lshlrev_b32_e32 v58, 16, v105
	v_and_b32_e32 v59, 0xffff0000, v105
	v_lshlrev_b32_e32 v60, 16, v106
	v_and_b32_e32 v61, 0xffff0000, v106
	v_lshlrev_b32_e32 v62, 16, v107
	v_and_b32_e32 v63, 0xffff0000, v107
	v_lshlrev_b32_e32 v64, 16, v108
	v_and_b32_e32 v65, 0xffff0000, v108
	v_lshlrev_b32_e32 v66, 16, v109
	v_and_b32_e32 v67, 0xffff0000, v109
	v_lshlrev_b32_e32 v68, 16, v110
	v_and_b32_e32 v69, 0xffff0000, v110
	v_lshlrev_b32_e32 v70, 16, v111
	v_and_b32_e32 v71, 0xffff0000, v111
	v_pk_mul_f32 v[56:57], v[56:57], v[200:201]
	v_pk_mul_f32 v[58:59], v[58:59], v[200:201]
	v_pk_mul_f32 v[68:69], v[68:69], v[202:203]
	v_pk_mul_f32 v[70:71], v[70:71], v[202:203]
	v_lshlrev_b32_e32 v124, 16, v120
	v_and_b32_e32 v125, 0xffff0000, v120
	v_lshlrev_b32_e32 v126, 16, v121
	v_and_b32_e32 v127, 0xffff0000, v121
	v_lshlrev_b32_e32 v128, 16, v122
	v_and_b32_e32 v129, 0xffff0000, v122
	v_lshlrev_b32_e32 v130, 16, v123
	v_and_b32_e32 v131, 0xffff0000, v123
	v_pk_fma_f32 v[148:149], v[72:73], v[0:1], v[36:37]
	v_pk_fma_f32 v[150:151], v[74:75], v[2:3], v[38:39]
	v_pk_fma_f32 v[152:153], v[76:77], v[0:1], v[36:37]
	v_pk_fma_f32 v[154:155], v[78:79], v[2:3], v[38:39]
	v_pk_fma_f32 v[148:149], v[40:41], v[4:5], v[148:149]
	v_pk_fma_f32 v[150:151], v[42:43], v[6:7], v[150:151]
	v_pk_fma_f32 v[152:153], v[44:45], v[4:5], v[152:153]
	v_pk_fma_f32 v[154:155], v[46:47], v[6:7], v[154:155]
	v_pk_fma_f32 v[148:149], v[56:57], v[8:9], v[148:149]
	v_pk_fma_f32 v[150:151], v[58:59], v[10:11], v[150:151]
	v_pk_fma_f32 v[152:153], v[60:61], v[8:9], v[152:153]
	v_pk_fma_f32 v[154:155], v[62:63], v[10:11], v[154:155]
	v_pk_fma_f32 v[148:149], v[76:77], v[12:13], v[148:149]
	v_pk_fma_f32 v[150:151], v[78:79], v[14:15], v[150:151]
	v_pk_fma_f32 v[152:153], v[80:81], v[12:13], v[152:153]
	v_pk_fma_f32 v[154:155], v[82:83], v[14:15], v[154:155]
	v_pk_fma_f32 v[148:149], v[44:45], v[16:17], v[148:149]
; __device__ __forceinline__ unsigned cvt_pk_bf16(float lo, float hi) { unsigned r; asm volatile("v_cvt_pk_bf16_f32 %0, %1, %2" : "=v"(r) : "v"(lo), "v"(hi)); return r; }
; __device__ __forceinline__ float gelu_as(float v) {
;   const float av = fabsf(v); const float t = __builtin_amdgcn_rcpf(av * 0.2316418882f + 1.0f);
;   float q = t * 0.5307027145f + (-0.7265760135f); q = q * t + 0.7107068705f; q = q * t + (-0.142248368f); q = q * t + 0.127414796f; q = q * t;
;   const float e = __builtin_amdgcn_exp2f((v * v) * (-0.72134752044f));
;   const float m = v * (q * e);
;   return v < 0.f ? m : v - m;
; }
; __device__ __forceinline__ void phase_conv(KP p, int l, int tid) {
;     ...
;     for (int jb = j0; jb < j0 + 16; jb += CB) {
;       u32x2 an[CB][RB + 2], ur[CB][RB];
; #pragma unroll
;       for (int q = 0; q < CB; ++q) { const int col = jb + q + 1; const int cl = col > 63 ? 63 : col;
; #pragma unroll
;         for (int di = 0; di < RB + 2; ++di) an[q][di] = *(const u32x2*)(rowp[di] + (size_t)cl * DFF);
; #pragma unroll
;         for (int rr = 0; rr < RB; ++rr) ur[q][rr] = *(const u32x2*)(U + (size_t)((r0 + rr) * 64 + jb + q) * DFF + c0); }
;       __builtin_amdgcn_sched_barrier(0);
; #pragma unroll
;       for (int q = 0; q < CB; ++q) {
;         const int col = jb + q + 1;
; #pragma unroll
;         for (int di = 0; di < RB + 2; ++di) { const bool ok = rv[di] && (col < 64); unpack4(an[q][di], win[2][di]);
; #pragma unroll
;           for (int k = 0; k < 4; ++k) win[2][di][k] = ok ? win[2][di][k] : 0.f; }
; #pragma unroll
;         for (int rr = 0; rr < RB; ++rr) {
;           float uv[4]; unpack4(ur[q][rr], uv);
;           float o[4];
; #pragma unroll
;           for (int k = 0; k < 4; ++k) {
;             float a = bsv[k];
; #pragma unroll
;             for (int di = 0; di < 3; ++di)
; #pragma unroll
;               for (int dj = 0; dj < 3; ++dj) a += win[dj][rr + di][k] * w[di * 3 + dj][k];
;             o[k] = gelu_as(a) * uv[k];
;           }
;           u32x2 ow; ow.x = cvt_pk_bf16(o[0], o[1]); ow.y = cvt_pk_bf16(o[2], o[3]);
;           *(u32x2*)(G + (size_t)((r0 + rr) * 64 + jb + q) * DFF + c0) = ow;
;         }
; #pragma unroll
;         for (int di = 0; di < RB + 2; ++di)
; #pragma unroll
;           for (int k = 0; k < 4; ++k) { win[0][di][k] = win[1][di][k]; win[1][di][k] = win[2][di][k]; }
;       }
	v_pk_fma_f32 v[150:151], v[46:47], v[18:19], v[150:151]
	v_pk_fma_f32 v[152:153], v[48:49], v[16:17], v[152:153]
	v_pk_fma_f32 v[154:155], v[50:51], v[18:19], v[154:155]
	v_pk_fma_f32 v[148:149], v[60:61], v[20:21], v[148:149]
	v_pk_fma_f32 v[150:151], v[62:63], v[22:23], v[150:151]
	v_pk_fma_f32 v[152:153], v[64:65], v[20:21], v[152:153]
	v_pk_fma_f32 v[154:155], v[66:67], v[22:23], v[154:155]
	v_pk_fma_f32 v[148:149], v[80:81], v[24:25], v[148:149]
	v_pk_fma_f32 v[150:151], v[82:83], v[26:27], v[150:151]
	v_pk_fma_f32 v[152:153], v[84:85], v[24:25], v[152:153]
	v_pk_fma_f32 v[154:155], v[86:87], v[26:27], v[154:155]
	v_pk_fma_f32 v[148:149], v[48:49], v[28:29], v[148:149]
	v_pk_fma_f32 v[150:151], v[50:51], v[30:31], v[150:151]
	v_pk_fma_f32 v[152:153], v[52:53], v[28:29], v[152:153]
	v_pk_fma_f32 v[154:155], v[54:55], v[30:31], v[154:155]
	v_pk_fma_f32 v[148:149], v[64:65], v[32:33], v[148:149]
	v_pk_fma_f32 v[150:151], v[66:67], v[34:35], v[150:151]
	v_pk_fma_f32 v[152:153], v[68:69], v[32:33], v[152:153]
	v_pk_fma_f32 v[154:155], v[70:71], v[34:35], v[154:155]
	v_and_b32_e32 v156, 0x7fffffff, v148
	v_and_b32_e32 v157, 0x7fffffff, v149
	v_and_b32_e32 v158, 0x7fffffff, v150
	v_and_b32_e32 v159, 0x7fffffff, v151
	v_and_b32_e32 v160, 0x7fffffff, v152
	v_and_b32_e32 v161, 0x7fffffff, v153
	v_and_b32_e32 v162, 0x7fffffff, v154
	v_and_b32_e32 v163, 0x7fffffff, v155
	v_pk_fma_f32 v[164:165], v[156:157], v[184:185], v[186:187]
	v_pk_fma_f32 v[166:167], v[158:159], v[184:185], v[186:187]
	v_pk_fma_f32 v[168:169], v[160:161], v[184:185], v[186:187]
	v_pk_fma_f32 v[170:171], v[162:163], v[184:185], v[186:187]
	v_rcp_f32_e32 v164, v164
	v_rcp_f32_e32 v165, v165
	v_rcp_f32_e32 v166, v166
	v_rcp_f32_e32 v167, v167
	v_rcp_f32_e32 v168, v168
	v_rcp_f32_e32 v169, v169
	v_rcp_f32_e32 v170, v170
	v_rcp_f32_e32 v171, v171
	v_pk_fma_f32 v[172:173], v[164:165], v[188:189], v[190:191]
	v_pk_fma_f32 v[174:175], v[166:167], v[188:189], v[190:191]
	v_pk_fma_f32 v[176:177], v[168:169], v[188:189], v[190:191]
	v_pk_fma_f32 v[178:179], v[170:171], v[188:189], v[190:191]
	v_pk_fma_f32 v[172:173], v[172:173], v[164:165], v[192:193]
	v_pk_fma_f32 v[174:175], v[174:175], v[166:167], v[192:193]
	v_pk_fma_f32 v[176:177], v[176:177], v[168:169], v[192:193]
	v_pk_fma_f32 v[178:179], v[178:179], v[170:171], v[192:193]
	v_pk_fma_f32 v[172:173], v[172:173], v[164:165], v[194:195]
	v_pk_fma_f32 v[174:175], v[174:175], v[166:167], v[194:195]
	v_pk_fma_f32 v[176:177], v[176:177], v[168:169], v[194:195]
	v_pk_fma_f32 v[178:179], v[178:179], v[170:171], v[194:195]
	v_pk_fma_f32 v[172:173], v[172:173], v[164:165], v[196:197]
	v_pk_fma_f32 v[174:175], v[174:175], v[166:167], v[196:197]
	v_pk_fma_f32 v[176:177], v[176:177], v[168:169], v[196:197]
	v_pk_fma_f32 v[178:179], v[178:179], v[170:171], v[196:197]
	v_pk_mul_f32 v[172:173], v[172:173], v[164:165]
	v_pk_mul_f32 v[174:175], v[174:175], v[166:167]
	v_pk_mul_f32 v[176:177], v[176:177], v[168:169]
	v_pk_mul_f32 v[178:179], v[178:179], v[170:171]
	v_pk_mul_f32 v[164:165], v[148:149], v[148:149]
	v_pk_mul_f32 v[166:167], v[150:151], v[150:151]
	v_pk_mul_f32 v[168:169], v[152:153], v[152:153]
	v_pk_mul_f32 v[170:171], v[154:155], v[154:155]
	v_pk_mul_f32 v[164:165], v[164:165], v[198:199]
	v_pk_mul_f32 v[166:167], v[166:167], v[198:199]
	v_pk_mul_f32 v[168:169], v[168:169], v[198:199]
	v_pk_mul_f32 v[170:171], v[170:171], v[198:199]
	v_exp_f32_e32 v164, v164
	v_exp_f32_e32 v165, v165
	v_exp_f32_e32 v166, v166
	v_exp_f32_e32 v167, v167
	v_exp_f32_e32 v168, v168
	v_exp_f32_e32 v169, v169
	v_exp_f32_e32 v170, v170
	v_exp_f32_e32 v171, v171
	v_pk_mul_f32 v[172:173], v[172:173], v[164:165]
	v_pk_mul_f32 v[174:175], v[174:175], v[166:167]
	v_pk_mul_f32 v[176:177], v[176:177], v[168:169]
	v_pk_mul_f32 v[178:179], v[178:179], v[170:171]
	v_pk_mul_f32 v[172:173], v[156:157], v[172:173]
	v_pk_mul_f32 v[174:175], v[158:159], v[174:175]
	v_pk_mul_f32 v[176:177], v[160:161], v[176:177]
	v_pk_mul_f32 v[178:179], v[162:163], v[178:179]
	v_max_f32_e32 v164, 0, v148
	v_max_f32_e32 v165, 0, v149
	v_max_f32_e32 v166, 0, v150
	v_max_f32_e32 v167, 0, v151
	v_max_f32_e32 v168, 0, v152
	v_max_f32_e32 v169, 0, v153
	v_max_f32_e32 v170, 0, v154
	v_max_f32_e32 v171, 0, v155
	v_pk_add_f32 v[164:165], v[164:165], v[172:173] neg_lo:[0,1] neg_hi:[0,1]
	v_pk_add_f32 v[166:167], v[166:167], v[174:175] neg_lo:[0,1] neg_hi:[0,1]
	v_pk_add_f32 v[168:169], v[168:169], v[176:177] neg_lo:[0,1] neg_hi:[0,1]
	v_pk_add_f32 v[170:171], v[170:171], v[178:179] neg_lo:[0,1] neg_hi:[0,1]
	v_pk_mul_f32 v[164:165], v[164:165], v[124:125]
	v_pk_mul_f32 v[166:167], v[166:167], v[126:127]
	v_pk_mul_f32 v[168:169], v[168:169], v[128:129]
	v_pk_mul_f32 v[170:171], v[170:171], v[130:131]
	v_cvt_pk_bf16_f32 v156, v164, v165
	v_cvt_pk_bf16_f32 v157, v166, v167
	v_cvt_pk_bf16_f32 v158, v168, v169
	v_cvt_pk_bf16_f32 v159, v170, v171
	global_store_dwordx2 v220, v[156:157], s[10:11]
	global_store_dwordx2 v221, v[158:159], s[10:11]
	v_add_u32_e32 v210, 0x2c00, v210
	v_add_u32_e32 v211, 0x2c00, v210
	v_add_u32_e32 v212, v206, v211
	global_load_dwordx2 v[104:105], v212, s[6:7]
	v_add_u32_e32 v213, v207, v211
	global_load_dwordx2 v[106:107], v213, s[6:7]
	v_add_u32_e32 v214, v208, v211
	global_load_dwordx2 v[108:109], v214, s[6:7]
	v_add_u32_e32 v215, v209, v211
	global_load_dwordx2 v[110:111], v215, s[6:7]
	v_add_u32_e32 v220, v207, v210
	global_load_dwordx2 v[120:121], v220, s[8:9]
	v_add_u32_e32 v221, v208, v210
	global_load_dwordx2 v[122:123], v221, s[8:9]
	s_waitcnt vmcnt(16)
; __device__ __forceinline__ unsigned cvt_pk_bf16(float lo, float hi) { unsigned r; asm volatile("v_cvt_pk_bf16_f32 %0, %1, %2" : "=v"(r) : "v"(lo), "v"(hi)); return r; }
; __device__ __forceinline__ float gelu_as(float v) {
;   const float av = fabsf(v); const float t = __builtin_amdgcn_rcpf(av * 0.2316418882f + 1.0f);
;   float q = t * 0.5307027145f + (-0.7265760135f); q = q * t + 0.7107068705f; q = q * t + (-0.142248368f); q = q * t + 0.127414796f; q = q * t;
;   const float e = __builtin_amdgcn_exp2f((v * v) * (-0.72134752044f));
;   const float m = v * (q * e);
;   return v < 0.f ? m : v - m;
; }
; __device__ __forceinline__ void phase_conv(KP p, int l, int tid) {
;     ...
;     for (int jb = j0; jb < j0 + 16; jb += CB) {
;       u32x2 an[CB][RB + 2], ur[CB][RB];
; #pragma unroll
;       for (int q = 0; q < CB; ++q) { const int col = jb + q + 1; const int cl = col > 63 ? 63 : col;
; #pragma unroll
;         for (int di = 0; di < RB + 2; ++di) an[q][di] = *(const u32x2*)(rowp[di] + (size_t)cl * DFF);
; #pragma unroll
;         for (int rr = 0; rr < RB; ++rr) ur[q][rr] = *(const u32x2*)(U + (size_t)((r0 + rr) * 64 + jb + q) * DFF + c0); }
;       __builtin_amdgcn_sched_barrier(0);
; #pragma unroll
;       for (int q = 0; q < CB; ++q) {
;         const int col = jb + q + 1;
; #pragma unroll
;         for (int di = 0; di < RB + 2; ++di) { const bool ok = rv[di] && (col < 64); unpack4(an[q][di], win[2][di]);
; #pragma unroll
;           for (int k = 0; k < 4; ++k) win[2][di][k] = ok ? win[2][di][k] : 0.f; }
; #pragma unroll
;         for (int rr = 0; rr < RB; ++rr) {
;           float uv[4]; unpack4(ur[q][rr], uv);
;           float o[4];
; #pragma unroll
;           for (int k = 0; k < 4; ++k) {
;             float a = bsv[k];
; #pragma unroll
;             for (int di = 0; di < 3; ++di)
; #pragma unroll
;               for (int dj = 0; dj < 3; ++dj) a += win[dj][rr + di][k] * w[di * 3 + dj][k];
;             o[k] = gelu_as(a) * uv[k];
;           }
;           u32x2 ow; ow.x = cvt_pk_bf16(o[0], o[1]); ow.y = cvt_pk_bf16(o[2], o[3]);
;           *(u32x2*)(G + (size_t)((r0 + rr) * 64 + jb + q) * DFF + c0) = ow;
;         }
; #pragma unroll
;         for (int di = 0; di < RB + 2; ++di)
; #pragma unroll
;           for (int k = 0; k < 4; ++k) { win[0][di][k] = win[1][di][k]; win[1][di][k] = win[2][di][k]; }
;       }
	v_lshlrev_b32_e32 v72, 16, v88
	v_and_b32_e32 v73, 0xffff0000, v88
	v_lshlrev_b32_e32 v74, 16, v89
	v_and_b32_e32 v75, 0xffff0000, v89
	v_lshlrev_b32_e32 v76, 16, v90
	v_and_b32_e32 v77, 0xffff0000, v90
	v_lshlrev_b32_e32 v78, 16, v91
	v_and_b32_e32 v79, 0xffff0000, v91
	v_lshlrev_b32_e32 v80, 16, v92
	v_and_b32_e32 v81, 0xffff0000, v92
	v_lshlrev_b32_e32 v82, 16, v93
	v_and_b32_e32 v83, 0xffff0000, v93
	v_lshlrev_b32_e32 v84, 16, v94
	v_and_b32_e32 v85, 0xffff0000, v94
	v_lshlrev_b32_e32 v86, 16, v95
	v_and_b32_e32 v87, 0xffff0000, v95
	v_pk_mul_f32 v[72:73], v[72:73], v[200:201]
	v_pk_mul_f32 v[74:75], v[74:75], v[200:201]
	v_pk_mul_f32 v[84:85], v[84:85], v[202:203]
	v_pk_mul_f32 v[86:87], v[86:87], v[202:203]
	v_lshlrev_b32_e32 v124, 16, v112
	v_and_b32_e32 v125, 0xffff0000, v112
	v_lshlrev_b32_e32 v126, 16, v113
	v_and_b32_e32 v127, 0xffff0000, v113
	v_lshlrev_b32_e32 v128, 16, v114
	v_and_b32_e32 v129, 0xffff0000, v114
	v_lshlrev_b32_e32 v130, 16, v115
	v_and_b32_e32 v131, 0xffff0000, v115
	v_pk_fma_f32 v[148:149], v[40:41], v[0:1], v[36:37]
	v_pk_fma_f32 v[150:151], v[42:43], v[2:3], v[38:39]
	v_pk_fma_f32 v[152:153], v[44:45], v[0:1], v[36:37]
	v_pk_fma_f32 v[154:155], v[46:47], v[2:3], v[38:39]
	v_pk_fma_f32 v[148:149], v[56:57], v[4:5], v[148:149]
	v_pk_fma_f32 v[150:151], v[58:59], v[6:7], v[150:151]
	v_pk_fma_f32 v[152:153], v[60:61], v[4:5], v[152:153]
	v_pk_fma_f32 v[154:155], v[62:63], v[6:7], v[154:155]
	v_pk_fma_f32 v[148:149], v[72:73], v[8:9], v[148:149]
	v_pk_fma_f32 v[150:151], v[74:75], v[10:11], v[150:151]
	v_pk_fma_f32 v[152:153], v[76:77], v[8:9], v[152:153]
	v_pk_fma_f32 v[154:155], v[78:79], v[10:11], v[154:155]
	v_pk_fma_f32 v[148:149], v[44:45], v[12:13], v[148:149]
	v_pk_fma_f32 v[150:151], v[46:47], v[14:15], v[150:151]
	v_pk_fma_f32 v[152:153], v[48:49], v[12:13], v[152:153]
	v_pk_fma_f32 v[154:155], v[50:51], v[14:15], v[154:155]
	v_pk_fma_f32 v[148:149], v[60:61], v[16:17], v[148:149]
	v_pk_fma_f32 v[150:151], v[62:63], v[18:19], v[150:151]
	v_pk_fma_f32 v[152:153], v[64:65], v[16:17], v[152:153]
	v_pk_fma_f32 v[154:155], v[66:67], v[18:19], v[154:155]
	v_pk_fma_f32 v[148:149], v[76:77], v[20:21], v[148:149]
	v_pk_fma_f32 v[150:151], v[78:79], v[22:23], v[150:151]
	v_pk_fma_f32 v[152:153], v[80:81], v[20:21], v[152:153]
	v_pk_fma_f32 v[154:155], v[82:83], v[22:23], v[154:155]
	v_pk_fma_f32 v[148:149], v[48:49], v[24:25], v[148:149]
	v_pk_fma_f32 v[150:151], v[50:51], v[26:27], v[150:151]
	v_pk_fma_f32 v[152:153], v[52:53], v[24:25], v[152:153]
	v_pk_fma_f32 v[154:155], v[54:55], v[26:27], v[154:155]
	v_pk_fma_f32 v[148:149], v[64:65], v[28:29], v[148:149]
	v_pk_fma_f32 v[150:151], v[66:67], v[30:31], v[150:151]
	v_pk_fma_f32 v[152:153], v[68:69], v[28:29], v[152:153]
	v_pk_fma_f32 v[154:155], v[70:71], v[30:31], v[154:155]
	v_pk_fma_f32 v[148:149], v[80:81], v[32:33], v[148:149]
	v_pk_fma_f32 v[150:151], v[82:83], v[34:35], v[150:151]
	v_pk_fma_f32 v[152:153], v[84:85], v[32:33], v[152:153]
	v_pk_fma_f32 v[154:155], v[86:87], v[34:35], v[154:155]
	v_and_b32_e32 v156, 0x7fffffff, v148
	v_and_b32_e32 v157, 0x7fffffff, v149
	v_and_b32_e32 v158, 0x7fffffff, v150
	v_and_b32_e32 v159, 0x7fffffff, v151
	v_and_b32_e32 v160, 0x7fffffff, v152
	v_and_b32_e32 v161, 0x7fffffff, v153
	v_and_b32_e32 v162, 0x7fffffff, v154
	v_and_b32_e32 v163, 0x7fffffff, v155
	v_pk_fma_f32 v[164:165], v[156:157], v[184:185], v[186:187]
	v_pk_fma_f32 v[166:167], v[158:159], v[184:185], v[186:187]
	v_pk_fma_f32 v[168:169], v[160:161], v[184:185], v[186:187]
	v_pk_fma_f32 v[170:171], v[162:163], v[184:185], v[186:187]
	v_rcp_f32_e32 v164, v164
	v_rcp_f32_e32 v165, v165
	v_rcp_f32_e32 v166, v166
	v_rcp_f32_e32 v167, v167
	v_rcp_f32_e32 v168, v168
	v_rcp_f32_e32 v169, v169
	v_rcp_f32_e32 v170, v170
	v_rcp_f32_e32 v171, v171
	v_pk_fma_f32 v[172:173], v[164:165], v[188:189], v[190:191]
	v_pk_fma_f32 v[174:175], v[166:167], v[188:189], v[190:191]
	v_pk_fma_f32 v[176:177], v[168:169], v[188:189], v[190:191]
	v_pk_fma_f32 v[178:179], v[170:171], v[188:189], v[190:191]
	v_pk_fma_f32 v[172:173], v[172:173], v[164:165], v[192:193]
	v_pk_fma_f32 v[174:175], v[174:175], v[166:167], v[192:193]
	v_pk_fma_f32 v[176:177], v[176:177], v[168:169], v[192:193]
	v_pk_fma_f32 v[178:179], v[178:179], v[170:171], v[192:193]
	v_pk_fma_f32 v[172:173], v[172:173], v[164:165], v[194:195]
	v_pk_fma_f32 v[174:175], v[174:175], v[166:167], v[194:195]
	v_pk_fma_f32 v[176:177], v[176:177], v[168:169], v[194:195]
	v_pk_fma_f32 v[178:179], v[178:179], v[170:171], v[194:195]
	v_pk_fma_f32 v[172:173], v[172:173], v[164:165], v[196:197]
	v_pk_fma_f32 v[174:175], v[174:175], v[166:167], v[196:197]
	v_pk_fma_f32 v[176:177], v[176:177], v[168:169], v[196:197]
	v_pk_fma_f32 v[178:179], v[178:179], v[170:171], v[196:197]
	v_pk_mul_f32 v[172:173], v[172:173], v[164:165]
	v_pk_mul_f32 v[174:175], v[174:175], v[166:167]
	v_pk_mul_f32 v[176:177], v[176:177], v[168:169]
	v_pk_mul_f32 v[178:179], v[178:179], v[170:171]
	v_pk_mul_f32 v[164:165], v[148:149], v[148:149]
	v_pk_mul_f32 v[166:167], v[150:151], v[150:151]
	v_pk_mul_f32 v[168:169], v[152:153], v[152:153]
	v_pk_mul_f32 v[170:171], v[154:155], v[154:155]
	v_pk_mul_f32 v[164:165], v[164:165], v[198:199]
	v_pk_mul_f32 v[166:167], v[166:167], v[198:199]
	v_pk_mul_f32 v[168:169], v[168:169], v[198:199]
	v_pk_mul_f32 v[170:171], v[170:171], v[198:199]
	v_exp_f32_e32 v164, v164
	v_exp_f32_e32 v165, v165
	v_exp_f32_e32 v166, v166
	v_exp_f32_e32 v167, v167
	v_exp_f32_e32 v168, v168
	v_exp_f32_e32 v169, v169
	v_exp_f32_e32 v170, v170
	v_exp_f32_e32 v171, v171
	v_pk_mul_f32 v[172:173], v[172:173], v[164:165]
	v_pk_mul_f32 v[174:175], v[174:175], v[166:167]
; __device__ __forceinline__ unsigned cvt_pk_bf16(float lo, float hi) { unsigned r; asm volatile("v_cvt_pk_bf16_f32 %0, %1, %2" : "=v"(r) : "v"(lo), "v"(hi)); return r; }
; __device__ __forceinline__ float gelu_as(float v) {
;   const float av = fabsf(v); const float t = __builtin_amdgcn_rcpf(av * 0.2316418882f + 1.0f);
;   float q = t * 0.5307027145f + (-0.7265760135f); q = q * t + 0.7107068705f; q = q * t + (-0.142248368f); q = q * t + 0.127414796f; q = q * t;
;   const float e = __builtin_amdgcn_exp2f((v * v) * (-0.72134752044f));
;   const float m = v * (q * e);
;   return v < 0.f ? m : v - m;
; }
; __device__ __forceinline__ void phase_conv(KP p, int l, int tid) {
;     ...
;     for (int jb = j0; jb < j0 + 16; jb += CB) {
;       u32x2 an[CB][RB + 2], ur[CB][RB];
; #pragma unroll
;       for (int q = 0; q < CB; ++q) { const int col = jb + q + 1; const int cl = col > 63 ? 63 : col;
; #pragma unroll
;         for (int di = 0; di < RB + 2; ++di) an[q][di] = *(const u32x2*)(rowp[di] + (size_t)cl * DFF);
; #pragma unroll
;         for (int rr = 0; rr < RB; ++rr) ur[q][rr] = *(const u32x2*)(U + (size_t)((r0 + rr) * 64 + jb + q) * DFF + c0); }
;       __builtin_amdgcn_sched_barrier(0);
; #pragma unroll
;       for (int q = 0; q < CB; ++q) {
;         const int col = jb + q + 1;
; #pragma unroll
;         for (int di = 0; di < RB + 2; ++di) { const bool ok = rv[di] && (col < 64); unpack4(an[q][di], win[2][di]);
; #pragma unroll
;           for (int k = 0; k < 4; ++k) win[2][di][k] = ok ? win[2][di][k] : 0.f; }
; #pragma unroll
;         for (int rr = 0; rr < RB; ++rr) {
;           float uv[4]; unpack4(ur[q][rr], uv);
;           float o[4];
; #pragma unroll
;           for (int k = 0; k < 4; ++k) {
;             float a = bsv[k];
; #pragma unroll
;             for (int di = 0; di < 3; ++di)
; #pragma unroll
;               for (int dj = 0; dj < 3; ++dj) a += win[dj][rr + di][k] * w[di * 3 + dj][k];
;             o[k] = gelu_as(a) * uv[k];
;           }
;           u32x2 ow; ow.x = cvt_pk_bf16(o[0], o[1]); ow.y = cvt_pk_bf16(o[2], o[3]);
;           *(u32x2*)(G + (size_t)((r0 + rr) * 64 + jb + q) * DFF + c0) = ow;
;         }
; #pragma unroll
;         for (int di = 0; di < RB + 2; ++di)
; #pragma unroll
;           for (int k = 0; k < 4; ++k) { win[0][di][k] = win[1][di][k]; win[1][di][k] = win[2][di][k]; }
;       }
	v_pk_mul_f32 v[176:177], v[176:177], v[168:169]
	v_pk_mul_f32 v[178:179], v[178:179], v[170:171]
	v_pk_mul_f32 v[172:173], v[156:157], v[172:173]
	v_pk_mul_f32 v[174:175], v[158:159], v[174:175]
	v_pk_mul_f32 v[176:177], v[160:161], v[176:177]
	v_pk_mul_f32 v[178:179], v[162:163], v[178:179]
	v_max_f32_e32 v164, 0, v148
	v_max_f32_e32 v165, 0, v149
	v_max_f32_e32 v166, 0, v150
	v_max_f32_e32 v167, 0, v151
	v_max_f32_e32 v168, 0, v152
	v_max_f32_e32 v169, 0, v153
	v_max_f32_e32 v170, 0, v154
	v_max_f32_e32 v171, 0, v155
	v_pk_add_f32 v[164:165], v[164:165], v[172:173] neg_lo:[0,1] neg_hi:[0,1]
	v_pk_add_f32 v[166:167], v[166:167], v[174:175] neg_lo:[0,1] neg_hi:[0,1]
	v_pk_add_f32 v[168:169], v[168:169], v[176:177] neg_lo:[0,1] neg_hi:[0,1]
	v_pk_add_f32 v[170:171], v[170:171], v[178:179] neg_lo:[0,1] neg_hi:[0,1]
	v_pk_mul_f32 v[164:165], v[164:165], v[124:125]
	v_pk_mul_f32 v[166:167], v[166:167], v[126:127]
	v_pk_mul_f32 v[168:169], v[168:169], v[128:129]
	v_pk_mul_f32 v[170:171], v[170:171], v[130:131]
	v_cvt_pk_bf16_f32 v156, v164, v165
	v_cvt_pk_bf16_f32 v157, v166, v167
	v_cvt_pk_bf16_f32 v158, v168, v169
	v_cvt_pk_bf16_f32 v159, v170, v171
	global_store_dwordx2 v216, v[156:157], s[10:11]
	global_store_dwordx2 v217, v[158:159], s[10:11]
	v_add_u32_e32 v210, 0x2c00, v210
	v_add_u32_e32 v211, 0x2c00, v210
	v_add_u32_e32 v212, v206, v211
	global_load_dwordx2 v[88:89], v212, s[6:7]
	v_add_u32_e32 v213, v207, v211
	global_load_dwordx2 v[90:91], v213, s[6:7]
	v_add_u32_e32 v214, v208, v211
	global_load_dwordx2 v[92:93], v214, s[6:7]
	v_add_u32_e32 v215, v209, v211
	global_load_dwordx2 v[94:95], v215, s[6:7]
	v_add_u32_e32 v216, v207, v210
	global_load_dwordx2 v[112:113], v216, s[8:9]
	v_add_u32_e32 v217, v208, v210
	global_load_dwordx2 v[114:115], v217, s[8:9]
	s_waitcnt vmcnt(16)
	v_lshlrev_b32_e32 v40, 16, v96
	v_and_b32_e32 v41, 0xffff0000, v96
	v_lshlrev_b32_e32 v42, 16, v97
	v_and_b32_e32 v43, 0xffff0000, v97
	v_lshlrev_b32_e32 v44, 16, v98
	v_and_b32_e32 v45, 0xffff0000, v98
	v_lshlrev_b32_e32 v46, 16, v99
	v_and_b32_e32 v47, 0xffff0000, v99
	v_lshlrev_b32_e32 v48, 16, v100
	v_and_b32_e32 v49, 0xffff0000, v100
	v_lshlrev_b32_e32 v50, 16, v101
	v_and_b32_e32 v51, 0xffff0000, v101
	v_lshlrev_b32_e32 v52, 16, v102
	v_and_b32_e32 v53, 0xffff0000, v102
	v_lshlrev_b32_e32 v54, 16, v103
	v_and_b32_e32 v55, 0xffff0000, v103
	v_pk_mul_f32 v[40:41], v[40:41], v[200:201]
	v_pk_mul_f32 v[42:43], v[42:43], v[200:201]
	v_pk_mul_f32 v[52:53], v[52:53], v[202:203]
	v_pk_mul_f32 v[54:55], v[54:55], v[202:203]
	v_lshlrev_b32_e32 v124, 16, v116
	v_and_b32_e32 v125, 0xffff0000, v116
	v_lshlrev_b32_e32 v126, 16, v117
	v_and_b32_e32 v127, 0xffff0000, v117
	v_lshlrev_b32_e32 v128, 16, v118
	v_and_b32_e32 v129, 0xffff0000, v118
	v_lshlrev_b32_e32 v130, 16, v119
	v_and_b32_e32 v131, 0xffff0000, v119
	v_pk_fma_f32 v[148:149], v[56:57], v[0:1], v[36:37]
	v_pk_fma_f32 v[150:151], v[58:59], v[2:3], v[38:39]
	v_pk_fma_f32 v[152:153], v[60:61], v[0:1], v[36:37]
	v_pk_fma_f32 v[154:155], v[62:63], v[2:3], v[38:39]
	v_pk_fma_f32 v[148:149], v[72:73], v[4:5], v[148:149]
	v_pk_fma_f32 v[150:151], v[74:75], v[6:7], v[150:151]
	v_pk_fma_f32 v[152:153], v[76:77], v[4:5], v[152:153]
	v_pk_fma_f32 v[154:155], v[78:79], v[6:7], v[154:155]
	v_pk_fma_f32 v[148:149], v[40:41], v[8:9], v[148:149]
	v_pk_fma_f32 v[150:151], v[42:43], v[10:11], v[150:151]
	v_pk_fma_f32 v[152:153], v[44:45], v[8:9], v[152:153]
	v_pk_fma_f32 v[154:155], v[46:47], v[10:11], v[154:155]
	v_pk_fma_f32 v[148:149], v[60:61], v[12:13], v[148:149]
	v_pk_fma_f32 v[150:151], v[62:63], v[14:15], v[150:151]
	v_pk_fma_f32 v[152:153], v[64:65], v[12:13], v[152:153]
	v_pk_fma_f32 v[154:155], v[66:67], v[14:15], v[154:155]
	v_pk_fma_f32 v[148:149], v[76:77], v[16:17], v[148:149]
	v_pk_fma_f32 v[150:151], v[78:79], v[18:19], v[150:151]
	v_pk_fma_f32 v[152:153], v[80:81], v[16:17], v[152:153]
	v_pk_fma_f32 v[154:155], v[82:83], v[18:19], v[154:155]
	v_pk_fma_f32 v[148:149], v[44:45], v[20:21], v[148:149]
	v_pk_fma_f32 v[150:151], v[46:47], v[22:23], v[150:151]
	v_pk_fma_f32 v[152:153], v[48:49], v[20:21], v[152:153]
	v_pk_fma_f32 v[154:155], v[50:51], v[22:23], v[154:155]
	v_pk_fma_f32 v[148:149], v[64:65], v[24:25], v[148:149]
	v_pk_fma_f32 v[150:151], v[66:67], v[26:27], v[150:151]
	v_pk_fma_f32 v[152:153], v[68:69], v[24:25], v[152:153]
	v_pk_fma_f32 v[154:155], v[70:71], v[26:27], v[154:155]
	v_pk_fma_f32 v[148:149], v[80:81], v[28:29], v[148:149]
	v_pk_fma_f32 v[150:151], v[82:83], v[30:31], v[150:151]
	v_pk_fma_f32 v[152:153], v[84:85], v[28:29], v[152:153]
	v_pk_fma_f32 v[154:155], v[86:87], v[30:31], v[154:155]
	v_pk_fma_f32 v[148:149], v[48:49], v[32:33], v[148:149]
	v_pk_fma_f32 v[150:151], v[50:51], v[34:35], v[150:151]
	v_pk_fma_f32 v[152:153], v[52:53], v[32:33], v[152:153]
	v_pk_fma_f32 v[154:155], v[54:55], v[34:35], v[154:155]
	v_and_b32_e32 v156, 0x7fffffff, v148
	v_and_b32_e32 v157, 0x7fffffff, v149
	v_and_b32_e32 v158, 0x7fffffff, v150
	v_and_b32_e32 v159, 0x7fffffff, v151
	v_and_b32_e32 v160, 0x7fffffff, v152
	v_and_b32_e32 v161, 0x7fffffff, v153
	v_and_b32_e32 v162, 0x7fffffff, v154
	v_and_b32_e32 v163, 0x7fffffff, v155
	v_pk_fma_f32 v[164:165], v[156:157], v[184:185], v[186:187]
	v_pk_fma_f32 v[166:167], v[158:159], v[184:185], v[186:187]
	v_pk_fma_f32 v[168:169], v[160:161], v[184:185], v[186:187]
	v_pk_fma_f32 v[170:171], v[162:163], v[184:185], v[186:187]
	v_rcp_f32_e32 v164, v164
	v_rcp_f32_e32 v165, v165
	v_rcp_f32_e32 v166, v166
	v_rcp_f32_e32 v167, v167
	v_rcp_f32_e32 v168, v168
	v_rcp_f32_e32 v169, v169
	v_rcp_f32_e32 v170, v170
	v_rcp_f32_e32 v171, v171
; __device__ __forceinline__ unsigned cvt_pk_bf16(float lo, float hi) { unsigned r; asm volatile("v_cvt_pk_bf16_f32 %0, %1, %2" : "=v"(r) : "v"(lo), "v"(hi)); return r; }
; __device__ __forceinline__ float gelu_as(float v) {
;   const float av = fabsf(v); const float t = __builtin_amdgcn_rcpf(av * 0.2316418882f + 1.0f);
;   float q = t * 0.5307027145f + (-0.7265760135f); q = q * t + 0.7107068705f; q = q * t + (-0.142248368f); q = q * t + 0.127414796f; q = q * t;
;   const float e = __builtin_amdgcn_exp2f((v * v) * (-0.72134752044f));
;   const float m = v * (q * e);
;   return v < 0.f ? m : v - m;
; }
; __device__ __forceinline__ void phase_conv(KP p, int l, int tid) {
;     ...
;     for (int jb = j0; jb < j0 + 16; jb += CB) {
;       u32x2 an[CB][RB + 2], ur[CB][RB];
; #pragma unroll
;       for (int q = 0; q < CB; ++q) { const int col = jb + q + 1; const int cl = col > 63 ? 63 : col;
; #pragma unroll
;         for (int di = 0; di < RB + 2; ++di) an[q][di] = *(const u32x2*)(rowp[di] + (size_t)cl * DFF);
; #pragma unroll
;         for (int rr = 0; rr < RB; ++rr) ur[q][rr] = *(const u32x2*)(U + (size_t)((r0 + rr) * 64 + jb + q) * DFF + c0); }
;       __builtin_amdgcn_sched_barrier(0);
; #pragma unroll
;       for (int q = 0; q < CB; ++q) {
;         const int col = jb + q + 1;
; #pragma unroll
;         for (int di = 0; di < RB + 2; ++di) { const bool ok = rv[di] && (col < 64); unpack4(an[q][di], win[2][di]);
; #pragma unroll
;           for (int k = 0; k < 4; ++k) win[2][di][k] = ok ? win[2][di][k] : 0.f; }
; #pragma unroll
;         for (int rr = 0; rr < RB; ++rr) {
;           float uv[4]; unpack4(ur[q][rr], uv);
;           float o[4];
; #pragma unroll
;           for (int k = 0; k < 4; ++k) {
;             float a = bsv[k];
; #pragma unroll
;             for (int di = 0; di < 3; ++di)
; #pragma unroll
;               for (int dj = 0; dj < 3; ++dj) a += win[dj][rr + di][k] * w[di * 3 + dj][k];
;             o[k] = gelu_as(a) * uv[k];
;           }
;           u32x2 ow; ow.x = cvt_pk_bf16(o[0], o[1]); ow.y = cvt_pk_bf16(o[2], o[3]);
;           *(u32x2*)(G + (size_t)((r0 + rr) * 64 + jb + q) * DFF + c0) = ow;
;         }
; #pragma unroll
;         for (int di = 0; di < RB + 2; ++di)
; #pragma unroll
;           for (int k = 0; k < 4; ++k) { win[0][di][k] = win[1][di][k]; win[1][di][k] = win[2][di][k]; }
;       }
	v_pk_fma_f32 v[172:173], v[164:165], v[188:189], v[190:191]
	v_pk_fma_f32 v[174:175], v[166:167], v[188:189], v[190:191]
	v_pk_fma_f32 v[176:177], v[168:169], v[188:189], v[190:191]
	v_pk_fma_f32 v[178:179], v[170:171], v[188:189], v[190:191]
	v_pk_fma_f32 v[172:173], v[172:173], v[164:165], v[192:193]
	v_pk_fma_f32 v[174:175], v[174:175], v[166:167], v[192:193]
	v_pk_fma_f32 v[176:177], v[176:177], v[168:169], v[192:193]
	v_pk_fma_f32 v[178:179], v[178:179], v[170:171], v[192:193]
	v_pk_fma_f32 v[172:173], v[172:173], v[164:165], v[194:195]
	v_pk_fma_f32 v[174:175], v[174:175], v[166:167], v[194:195]
	v_pk_fma_f32 v[176:177], v[176:177], v[168:169], v[194:195]
	v_pk_fma_f32 v[178:179], v[178:179], v[170:171], v[194:195]
	v_pk_fma_f32 v[172:173], v[172:173], v[164:165], v[196:197]
	v_pk_fma_f32 v[174:175], v[174:175], v[166:167], v[196:197]
	v_pk_fma_f32 v[176:177], v[176:177], v[168:169], v[196:197]
	v_pk_fma_f32 v[178:179], v[178:179], v[170:171], v[196:197]
	v_pk_mul_f32 v[172:173], v[172:173], v[164:165]
	v_pk_mul_f32 v[174:175], v[174:175], v[166:167]
	v_pk_mul_f32 v[176:177], v[176:177], v[168:169]
	v_pk_mul_f32 v[178:179], v[178:179], v[170:171]
	v_pk_mul_f32 v[164:165], v[148:149], v[148:149]
	v_pk_mul_f32 v[166:167], v[150:151], v[150:151]
	v_pk_mul_f32 v[168:169], v[152:153], v[152:153]
	v_pk_mul_f32 v[170:171], v[154:155], v[154:155]
	v_pk_mul_f32 v[164:165], v[164:165], v[198:199]
	v_pk_mul_f32 v[166:167], v[166:167], v[198:199]
	v_pk_mul_f32 v[168:169], v[168:169], v[198:199]
	v_pk_mul_f32 v[170:171], v[170:171], v[198:199]
	v_exp_f32_e32 v164, v164
	v_exp_f32_e32 v165, v165
	v_exp_f32_e32 v166, v166
	v_exp_f32_e32 v167, v167
	v_exp_f32_e32 v168, v168
	v_exp_f32_e32 v169, v169
	v_exp_f32_e32 v170, v170
	v_exp_f32_e32 v171, v171
	v_pk_mul_f32 v[172:173], v[172:173], v[164:165]
	v_pk_mul_f32 v[174:175], v[174:175], v[166:167]
	v_pk_mul_f32 v[176:177], v[176:177], v[168:169]
	v_pk_mul_f32 v[178:179], v[178:179], v[170:171]
	v_pk_mul_f32 v[172:173], v[156:157], v[172:173]
	v_pk_mul_f32 v[174:175], v[158:159], v[174:175]
	v_pk_mul_f32 v[176:177], v[160:161], v[176:177]
	v_pk_mul_f32 v[178:179], v[162:163], v[178:179]
	v_max_f32_e32 v164, 0, v148
	v_max_f32_e32 v165, 0, v149
	v_max_f32_e32 v166, 0, v150
	v_max_f32_e32 v167, 0, v151
	v_max_f32_e32 v168, 0, v152
	v_max_f32_e32 v169, 0, v153
	v_max_f32_e32 v170, 0, v154
	v_max_f32_e32 v171, 0, v155
	v_pk_add_f32 v[164:165], v[164:165], v[172:173] neg_lo:[0,1] neg_hi:[0,1]
	v_pk_add_f32 v[166:167], v[166:167], v[174:175] neg_lo:[0,1] neg_hi:[0,1]
	v_pk_add_f32 v[168:169], v[168:169], v[176:177] neg_lo:[0,1] neg_hi:[0,1]
	v_pk_add_f32 v[170:171], v[170:171], v[178:179] neg_lo:[0,1] neg_hi:[0,1]
	v_pk_mul_f32 v[164:165], v[164:165], v[124:125]
	v_pk_mul_f32 v[166:167], v[166:167], v[126:127]
	v_pk_mul_f32 v[168:169], v[168:169], v[128:129]
	v_pk_mul_f32 v[170:171], v[170:171], v[130:131]
	v_cvt_pk_bf16_f32 v156, v164, v165
	v_cvt_pk_bf16_f32 v157, v166, v167
	v_cvt_pk_bf16_f32 v158, v168, v169
	v_cvt_pk_bf16_f32 v159, v170, v171
	global_store_dwordx2 v218, v[156:157], s[10:11]
	global_store_dwordx2 v219, v[158:159], s[10:11]
	v_add_u32_e32 v210, 0x2c00, v210
	v_add_u32_e32 v211, 0x2c00, v210
	v_add_u32_e32 v212, v206, v211
	global_load_dwordx2 v[96:97], v212, s[6:7]
	v_add_u32_e32 v213, v207, v211
	global_load_dwordx2 v[98:99], v213, s[6:7]
	v_add_u32_e32 v214, v208, v211
	global_load_dwordx2 v[100:101], v214, s[6:7]
	v_add_u32_e32 v215, v209, v211
	global_load_dwordx2 v[102:103], v215, s[6:7]
	v_add_u32_e32 v218, v207, v210
	global_load_dwordx2 v[116:117], v218, s[8:9]
	v_add_u32_e32 v219, v208, v210
	global_load_dwordx2 v[118:119], v219, s[8:9]
	s_waitcnt vmcnt(16)
	v_lshlrev_b32_e32 v56, 16, v104
	v_and_b32_e32 v57, 0xffff0000, v104
	v_lshlrev_b32_e32 v58, 16, v105
	v_and_b32_e32 v59, 0xffff0000, v105
	v_lshlrev_b32_e32 v60, 16, v106
	v_and_b32_e32 v61, 0xffff0000, v106
	v_lshlrev_b32_e32 v62, 16, v107
	v_and_b32_e32 v63, 0xffff0000, v107
	v_lshlrev_b32_e32 v64, 16, v108
	v_and_b32_e32 v65, 0xffff0000, v108
	v_lshlrev_b32_e32 v66, 16, v109
	v_and_b32_e32 v67, 0xffff0000, v109
	v_lshlrev_b32_e32 v68, 16, v110
	v_and_b32_e32 v69, 0xffff0000, v110
	v_lshlrev_b32_e32 v70, 16, v111
	v_and_b32_e32 v71, 0xffff0000, v111
	v_pk_mul_f32 v[56:57], v[56:57], v[200:201]
	v_pk_mul_f32 v[58:59], v[58:59], v[200:201]
	v_pk_mul_f32 v[68:69], v[68:69], v[202:203]
	v_pk_mul_f32 v[70:71], v[70:71], v[202:203]
	v_lshlrev_b32_e32 v124, 16, v120
	v_and_b32_e32 v125, 0xffff0000, v120
	v_lshlrev_b32_e32 v126, 16, v121
	v_and_b32_e32 v127, 0xffff0000, v121
	v_lshlrev_b32_e32 v128, 16, v122
	v_and_b32_e32 v129, 0xffff0000, v122
	v_lshlrev_b32_e32 v130, 16, v123
	v_and_b32_e32 v131, 0xffff0000, v123
	v_pk_fma_f32 v[148:149], v[72:73], v[0:1], v[36:37]
	v_pk_fma_f32 v[150:151], v[74:75], v[2:3], v[38:39]
	v_pk_fma_f32 v[152:153], v[76:77], v[0:1], v[36:37]
	v_pk_fma_f32 v[154:155], v[78:79], v[2:3], v[38:39]
	v_pk_fma_f32 v[148:149], v[40:41], v[4:5], v[148:149]
	v_pk_fma_f32 v[150:151], v[42:43], v[6:7], v[150:151]
	v_pk_fma_f32 v[152:153], v[44:45], v[4:5], v[152:153]
	v_pk_fma_f32 v[154:155], v[46:47], v[6:7], v[154:155]
	v_pk_fma_f32 v[148:149], v[56:57], v[8:9], v[148:149]
	v_pk_fma_f32 v[150:151], v[58:59], v[10:11], v[150:151]
	v_pk_fma_f32 v[152:153], v[60:61], v[8:9], v[152:153]
	v_pk_fma_f32 v[154:155], v[62:63], v[10:11], v[154:155]
	v_pk_fma_f32 v[148:149], v[76:77], v[12:13], v[148:149]
	v_pk_fma_f32 v[150:151], v[78:79], v[14:15], v[150:151]
	v_pk_fma_f32 v[152:153], v[80:81], v[12:13], v[152:153]
	v_pk_fma_f32 v[154:155], v[82:83], v[14:15], v[154:155]
	v_pk_fma_f32 v[148:149], v[44:45], v[16:17], v[148:149]
; __device__ __forceinline__ unsigned cvt_pk_bf16(float lo, float hi) { unsigned r; asm volatile("v_cvt_pk_bf16_f32 %0, %1, %2" : "=v"(r) : "v"(lo), "v"(hi)); return r; }
; __device__ __forceinline__ float gelu_as(float v) {
;   const float av = fabsf(v); const float t = __builtin_amdgcn_rcpf(av * 0.2316418882f + 1.0f);
;   float q = t * 0.5307027145f + (-0.7265760135f); q = q * t + 0.7107068705f; q = q * t + (-0.142248368f); q = q * t + 0.127414796f; q = q * t;
;   const float e = __builtin_amdgcn_exp2f((v * v) * (-0.72134752044f));
;   const float m = v * (q * e);
;   return v < 0.f ? m : v - m;
; }
; __device__ __forceinline__ void phase_conv(KP p, int l, int tid) {
;     ...
;     for (int jb = j0; jb < j0 + 16; jb += CB) {
;       u32x2 an[CB][RB + 2], ur[CB][RB];
; #pragma unroll
;       for (int q = 0; q < CB; ++q) { const int col = jb + q + 1; const int cl = col > 63 ? 63 : col;
; #pragma unroll
;         for (int di = 0; di < RB + 2; ++di) an[q][di] = *(const u32x2*)(rowp[di] + (size_t)cl * DFF);
; #pragma unroll
;         for (int rr = 0; rr < RB; ++rr) ur[q][rr] = *(const u32x2*)(U + (size_t)((r0 + rr) * 64 + jb + q) * DFF + c0); }
;       __builtin_amdgcn_sched_barrier(0);
; #pragma unroll
;       for (int q = 0; q < CB; ++q) {
;         const int col = jb + q + 1;
; #pragma unroll
;         for (int di = 0; di < RB + 2; ++di) { const bool ok = rv[di] && (col < 64); unpack4(an[q][di], win[2][di]);
; #pragma unroll
;           for (int k = 0; k < 4; ++k) win[2][di][k] = ok ? win[2][di][k] : 0.f; }
; #pragma unroll
;         for (int rr = 0; rr < RB; ++rr) {
;           float uv[4]; unpack4(ur[q][rr], uv);
;           float o[4];
; #pragma unroll
;           for (int k = 0; k < 4; ++k) {
;             float a = bsv[k];
; #pragma unroll
;             for (int di = 0; di < 3; ++di)
; #pragma unroll
;               for (int dj = 0; dj < 3; ++dj) a += win[dj][rr + di][k] * w[di * 3 + dj][k];
;             o[k] = gelu_as(a) * uv[k];
;           }
;           u32x2 ow; ow.x = cvt_pk_bf16(o[0], o[1]); ow.y = cvt_pk_bf16(o[2], o[3]);
;           *(u32x2*)(G + (size_t)((r0 + rr) * 64 + jb + q) * DFF + c0) = ow;
;         }
; #pragma unroll
;         for (int di = 0; di < RB + 2; ++di)
; #pragma unroll
;           for (int k = 0; k < 4; ++k) { win[0][di][k] = win[1][di][k]; win[1][di][k] = win[2][di][k]; }
;       }
	v_pk_fma_f32 v[150:151], v[46:47], v[18:19], v[150:151]
	v_pk_fma_f32 v[152:153], v[48:49], v[16:17], v[152:153]
	v_pk_fma_f32 v[154:155], v[50:51], v[18:19], v[154:155]
	v_pk_fma_f32 v[148:149], v[60:61], v[20:21], v[148:149]
	v_pk_fma_f32 v[150:151], v[62:63], v[22:23], v[150:151]
	v_pk_fma_f32 v[152:153], v[64:65], v[20:21], v[152:153]
	v_pk_fma_f32 v[154:155], v[66:67], v[22:23], v[154:155]
	v_pk_fma_f32 v[148:149], v[80:81], v[24:25], v[148:149]
	v_pk_fma_f32 v[150:151], v[82:83], v[26:27], v[150:151]
	v_pk_fma_f32 v[152:153], v[84:85], v[24:25], v[152:153]
	v_pk_fma_f32 v[154:155], v[86:87], v[26:27], v[154:155]
	v_pk_fma_f32 v[148:149], v[48:49], v[28:29], v[148:149]
	v_pk_fma_f32 v[150:151], v[50:51], v[30:31], v[150:151]
	v_pk_fma_f32 v[152:153], v[52:53], v[28:29], v[152:153]
	v_pk_fma_f32 v[154:155], v[54:55], v[30:31], v[154:155]
	v_pk_fma_f32 v[148:149], v[64:65], v[32:33], v[148:149]
	v_pk_fma_f32 v[150:151], v[66:67], v[34:35], v[150:151]
	v_pk_fma_f32 v[152:153], v[68:69], v[32:33], v[152:153]
	v_pk_fma_f32 v[154:155], v[70:71], v[34:35], v[154:155]
	v_and_b32_e32 v156, 0x7fffffff, v148
	v_and_b32_e32 v157, 0x7fffffff, v149
	v_and_b32_e32 v158, 0x7fffffff, v150
	v_and_b32_e32 v159, 0x7fffffff, v151
	v_and_b32_e32 v160, 0x7fffffff, v152
	v_and_b32_e32 v161, 0x7fffffff, v153
	v_and_b32_e32 v162, 0x7fffffff, v154
	v_and_b32_e32 v163, 0x7fffffff, v155
	v_pk_fma_f32 v[164:165], v[156:157], v[184:185], v[186:187]
	v_pk_fma_f32 v[166:167], v[158:159], v[184:185], v[186:187]
	v_pk_fma_f32 v[168:169], v[160:161], v[184:185], v[186:187]
	v_pk_fma_f32 v[170:171], v[162:163], v[184:185], v[186:187]
	v_rcp_f32_e32 v164, v164
	v_rcp_f32_e32 v165, v165
	v_rcp_f32_e32 v166, v166
	v_rcp_f32_e32 v167, v167
	v_rcp_f32_e32 v168, v168
	v_rcp_f32_e32 v169, v169
	v_rcp_f32_e32 v170, v170
	v_rcp_f32_e32 v171, v171
	v_pk_fma_f32 v[172:173], v[164:165], v[188:189], v[190:191]
	v_pk_fma_f32 v[174:175], v[166:167], v[188:189], v[190:191]
	v_pk_fma_f32 v[176:177], v[168:169], v[188:189], v[190:191]
	v_pk_fma_f32 v[178:179], v[170:171], v[188:189], v[190:191]
	v_pk_fma_f32 v[172:173], v[172:173], v[164:165], v[192:193]
	v_pk_fma_f32 v[174:175], v[174:175], v[166:167], v[192:193]
	v_pk_fma_f32 v[176:177], v[176:177], v[168:169], v[192:193]
	v_pk_fma_f32 v[178:179], v[178:179], v[170:171], v[192:193]
	v_pk_fma_f32 v[172:173], v[172:173], v[164:165], v[194:195]
	v_pk_fma_f32 v[174:175], v[174:175], v[166:167], v[194:195]
	v_pk_fma_f32 v[176:177], v[176:177], v[168:169], v[194:195]
	v_pk_fma_f32 v[178:179], v[178:179], v[170:171], v[194:195]
	v_pk_fma_f32 v[172:173], v[172:173], v[164:165], v[196:197]
	v_pk_fma_f32 v[174:175], v[174:175], v[166:167], v[196:197]
	v_pk_fma_f32 v[176:177], v[176:177], v[168:169], v[196:197]
	v_pk_fma_f32 v[178:179], v[178:179], v[170:171], v[196:197]
	v_pk_mul_f32 v[172:173], v[172:173], v[164:165]
	v_pk_mul_f32 v[174:175], v[174:175], v[166:167]
	v_pk_mul_f32 v[176:177], v[176:177], v[168:169]
	v_pk_mul_f32 v[178:179], v[178:179], v[170:171]
	v_pk_mul_f32 v[164:165], v[148:149], v[148:149]
	v_pk_mul_f32 v[166:167], v[150:151], v[150:151]
	v_pk_mul_f32 v[168:169], v[152:153], v[152:153]
	v_pk_mul_f32 v[170:171], v[154:155], v[154:155]
	v_pk_mul_f32 v[164:165], v[164:165], v[198:199]
	v_pk_mul_f32 v[166:167], v[166:167], v[198:199]
	v_pk_mul_f32 v[168:169], v[168:169], v[198:199]
	v_pk_mul_f32 v[170:171], v[170:171], v[198:199]
	v_exp_f32_e32 v164, v164
	v_exp_f32_e32 v165, v165
	v_exp_f32_e32 v166, v166
	v_exp_f32_e32 v167, v167
	v_exp_f32_e32 v168, v168
	v_exp_f32_e32 v169, v169
	v_exp_f32_e32 v170, v170
	v_exp_f32_e32 v171, v171
	v_pk_mul_f32 v[172:173], v[172:173], v[164:165]
	v_pk_mul_f32 v[174:175], v[174:175], v[166:167]
	v_pk_mul_f32 v[176:177], v[176:177], v[168:169]
	v_pk_mul_f32 v[178:179], v[178:179], v[170:171]
	v_pk_mul_f32 v[172:173], v[156:157], v[172:173]
	v_pk_mul_f32 v[174:175], v[158:159], v[174:175]
	v_pk_mul_f32 v[176:177], v[160:161], v[176:177]
	v_pk_mul_f32 v[178:179], v[162:163], v[178:179]
	v_max_f32_e32 v164, 0, v148
	v_max_f32_e32 v165, 0, v149
	v_max_f32_e32 v166, 0, v150
	v_max_f32_e32 v167, 0, v151
	v_max_f32_e32 v168, 0, v152
	v_max_f32_e32 v169, 0, v153
	v_max_f32_e32 v170, 0, v154
	v_max_f32_e32 v171, 0, v155
	v_pk_add_f32 v[164:165], v[164:165], v[172:173] neg_lo:[0,1] neg_hi:[0,1]
	v_pk_add_f32 v[166:167], v[166:167], v[174:175] neg_lo:[0,1] neg_hi:[0,1]
	v_pk_add_f32 v[168:169], v[168:169], v[176:177] neg_lo:[0,1] neg_hi:[0,1]
	v_pk_add_f32 v[170:171], v[170:171], v[178:179] neg_lo:[0,1] neg_hi:[0,1]
	v_pk_mul_f32 v[164:165], v[164:165], v[124:125]
	v_pk_mul_f32 v[166:167], v[166:167], v[126:127]
	v_pk_mul_f32 v[168:169], v[168:169], v[128:129]
	v_pk_mul_f32 v[170:171], v[170:171], v[130:131]
	v_cvt_pk_bf16_f32 v156, v164, v165
	v_cvt_pk_bf16_f32 v157, v166, v167
	v_cvt_pk_bf16_f32 v158, v168, v169
	v_cvt_pk_bf16_f32 v159, v170, v171
	global_store_dwordx2 v220, v[156:157], s[10:11]
	global_store_dwordx2 v221, v[158:159], s[10:11]
	v_add_u32_e32 v210, 0x2c00, v210
	v_add_u32_e32 v211, 0x2c00, v210
	v_add_u32_e32 v212, v206, v211
	global_load_dwordx2 v[104:105], v212, s[6:7]
	v_add_u32_e32 v213, v207, v211
	global_load_dwordx2 v[106:107], v213, s[6:7]
	v_add_u32_e32 v214, v208, v211
	global_load_dwordx2 v[108:109], v214, s[6:7]
	v_add_u32_e32 v215, v209, v211
	global_load_dwordx2 v[110:111], v215, s[6:7]
	v_add_u32_e32 v220, v207, v210
	global_load_dwordx2 v[120:121], v220, s[8:9]
	v_add_u32_e32 v221, v208, v210
	global_load_dwordx2 v[122:123], v221, s[8:9]
	s_waitcnt vmcnt(16)
; __device__ __forceinline__ unsigned cvt_pk_bf16(float lo, float hi) { unsigned r; asm volatile("v_cvt_pk_bf16_f32 %0, %1, %2" : "=v"(r) : "v"(lo), "v"(hi)); return r; }
; __device__ __forceinline__ float gelu_as(float v) {
;   const float av = fabsf(v); const float t = __builtin_amdgcn_rcpf(av * 0.2316418882f + 1.0f);
;   float q = t * 0.5307027145f + (-0.7265760135f); q = q * t + 0.7107068705f; q = q * t + (-0.142248368f); q = q * t + 0.127414796f; q = q * t;
;   const float e = __builtin_amdgcn_exp2f((v * v) * (-0.72134752044f));
;   const float m = v * (q * e);
;   return v < 0.f ? m : v - m;
; }
; __device__ __forceinline__ void phase_conv(KP p, int l, int tid) {
;     ...
;     for (int jb = j0; jb < j0 + 16; jb += CB) {
;       u32x2 an[CB][RB + 2], ur[CB][RB];
; #pragma unroll
;       for (int q = 0; q < CB; ++q) { const int col = jb + q + 1; const int cl = col > 63 ? 63 : col;
; #pragma unroll
;         for (int di = 0; di < RB + 2; ++di) an[q][di] = *(const u32x2*)(rowp[di] + (size_t)cl * DFF);
; #pragma unroll
;         for (int rr = 0; rr < RB; ++rr) ur[q][rr] = *(const u32x2*)(U + (size_t)((r0 + rr) * 64 + jb + q) * DFF + c0); }
;       __builtin_amdgcn_sched_barrier(0);
; #pragma unroll
;       for (int q = 0; q < CB; ++q) {
;         const int col = jb + q + 1;
; #pragma unroll
;         for (int di = 0; di < RB + 2; ++di) { const bool ok = rv[di] && (col < 64); unpack4(an[q][di], win[2][di]);
; #pragma unroll
;           for (int k = 0; k < 4; ++k) win[2][di][k] = ok ? win[2][di][k] : 0.f; }
; #pragma unroll
;         for (int rr = 0; rr < RB; ++rr) {
;           float uv[4]; unpack4(ur[q][rr], uv);
;           float o[4];
; #pragma unroll
;           for (int k = 0; k < 4; ++k) {
;             float a = bsv[k];
; #pragma unroll
;             for (int di = 0; di < 3; ++di)
; #pragma unroll
;               for (int dj = 0; dj < 3; ++dj) a += win[dj][rr + di][k] * w[di * 3 + dj][k];
;             o[k] = gelu_as(a) * uv[k];
;           }
;           u32x2 ow; ow.x = cvt_pk_bf16(o[0], o[1]); ow.y = cvt_pk_bf16(o[2], o[3]);
;           *(u32x2*)(G + (size_t)((r0 + rr) * 64 + jb + q) * DFF + c0) = ow;
;         }
; #pragma unroll
;         for (int di = 0; di < RB + 2; ++di)
; #pragma unroll
;           for (int k = 0; k < 4; ++k) { win[0][di][k] = win[1][di][k]; win[1][di][k] = win[2][di][k]; }
;       }
	v_lshlrev_b32_e32 v72, 16, v88
	v_and_b32_e32 v73, 0xffff0000, v88
	v_lshlrev_b32_e32 v74, 16, v89
	v_and_b32_e32 v75, 0xffff0000, v89
	v_lshlrev_b32_e32 v76, 16, v90
	v_and_b32_e32 v77, 0xffff0000, v90
	v_lshlrev_b32_e32 v78, 16, v91
	v_and_b32_e32 v79, 0xffff0000, v91
	v_lshlrev_b32_e32 v80, 16, v92
	v_and_b32_e32 v81, 0xffff0000, v92
	v_lshlrev_b32_e32 v82, 16, v93
	v_and_b32_e32 v83, 0xffff0000, v93
	v_lshlrev_b32_e32 v84, 16, v94
	v_and_b32_e32 v85, 0xffff0000, v94
	v_lshlrev_b32_e32 v86, 16, v95
	v_and_b32_e32 v87, 0xffff0000, v95
	v_pk_mul_f32 v[72:73], v[72:73], v[200:201]
	v_pk_mul_f32 v[74:75], v[74:75], v[200:201]
	v_pk_mul_f32 v[84:85], v[84:85], v[202:203]
	v_pk_mul_f32 v[86:87], v[86:87], v[202:203]
	v_lshlrev_b32_e32 v124, 16, v112
	v_and_b32_e32 v125, 0xffff0000, v112
	v_lshlrev_b32_e32 v126, 16, v113
	v_and_b32_e32 v127, 0xffff0000, v113
	v_lshlrev_b32_e32 v128, 16, v114
	v_and_b32_e32 v129, 0xffff0000, v114
	v_lshlrev_b32_e32 v130, 16, v115
	v_and_b32_e32 v131, 0xffff0000, v115
	v_pk_fma_f32 v[148:149], v[40:41], v[0:1], v[36:37]
	v_pk_fma_f32 v[150:151], v[42:43], v[2:3], v[38:39]
	v_pk_fma_f32 v[152:153], v[44:45], v[0:1], v[36:37]
	v_pk_fma_f32 v[154:155], v[46:47], v[2:3], v[38:39]
	v_pk_fma_f32 v[148:149], v[56:57], v[4:5], v[148:149]
	v_pk_fma_f32 v[150:151], v[58:59], v[6:7], v[150:151]
	v_pk_fma_f32 v[152:153], v[60:61], v[4:5], v[152:153]
	v_pk_fma_f32 v[154:155], v[62:63], v[6:7], v[154:155]
	v_pk_fma_f32 v[148:149], v[72:73], v[8:9], v[148:149]
	v_pk_fma_f32 v[150:151], v[74:75], v[10:11], v[150:151]
	v_pk_fma_f32 v[152:153], v[76:77], v[8:9], v[152:153]
	v_pk_fma_f32 v[154:155], v[78:79], v[10:11], v[154:155]
	v_pk_fma_f32 v[148:149], v[44:45], v[12:13], v[148:149]
	v_pk_fma_f32 v[150:151], v[46:47], v[14:15], v[150:151]
	v_pk_fma_f32 v[152:153], v[48:49], v[12:13], v[152:153]
	v_pk_fma_f32 v[154:155], v[50:51], v[14:15], v[154:155]
	v_pk_fma_f32 v[148:149], v[60:61], v[16:17], v[148:149]
	v_pk_fma_f32 v[150:151], v[62:63], v[18:19], v[150:151]
	v_pk_fma_f32 v[152:153], v[64:65], v[16:17], v[152:153]
	v_pk_fma_f32 v[154:155], v[66:67], v[18:19], v[154:155]
	v_pk_fma_f32 v[148:149], v[76:77], v[20:21], v[148:149]
	v_pk_fma_f32 v[150:151], v[78:79], v[22:23], v[150:151]
	v_pk_fma_f32 v[152:153], v[80:81], v[20:21], v[152:153]
	v_pk_fma_f32 v[154:155], v[82:83], v[22:23], v[154:155]
	v_pk_fma_f32 v[148:149], v[48:49], v[24:25], v[148:149]
	v_pk_fma_f32 v[150:151], v[50:51], v[26:27], v[150:151]
	v_pk_fma_f32 v[152:153], v[52:53], v[24:25], v[152:153]
	v_pk_fma_f32 v[154:155], v[54:55], v[26:27], v[154:155]
	v_pk_fma_f32 v[148:149], v[64:65], v[28:29], v[148:149]
	v_pk_fma_f32 v[150:151], v[66:67], v[30:31], v[150:151]
	v_pk_fma_f32 v[152:153], v[68:69], v[28:29], v[152:153]
	v_pk_fma_f32 v[154:155], v[70:71], v[30:31], v[154:155]
	v_pk_fma_f32 v[148:149], v[80:81], v[32:33], v[148:149]
	v_pk_fma_f32 v[150:151], v[82:83], v[34:35], v[150:151]
	v_pk_fma_f32 v[152:153], v[84:85], v[32:33], v[152:153]
	v_pk_fma_f32 v[154:155], v[86:87], v[34:35], v[154:155]
	v_and_b32_e32 v156, 0x7fffffff, v148
	v_and_b32_e32 v157, 0x7fffffff, v149
	v_and_b32_e32 v158, 0x7fffffff, v150
	v_and_b32_e32 v159, 0x7fffffff, v151
	v_and_b32_e32 v160, 0x7fffffff, v152
	v_and_b32_e32 v161, 0x7fffffff, v153
	v_and_b32_e32 v162, 0x7fffffff, v154
	v_and_b32_e32 v163, 0x7fffffff, v155
	v_pk_fma_f32 v[164:165], v[156:157], v[184:185], v[186:187]
	v_pk_fma_f32 v[166:167], v[158:159], v[184:185], v[186:187]
	v_pk_fma_f32 v[168:169], v[160:161], v[184:185], v[186:187]
	v_pk_fma_f32 v[170:171], v[162:163], v[184:185], v[186:187]
	v_rcp_f32_e32 v164, v164
	v_rcp_f32_e32 v165, v165
	v_rcp_f32_e32 v166, v166
	v_rcp_f32_e32 v167, v167
	v_rcp_f32_e32 v168, v168
	v_rcp_f32_e32 v169, v169
	v_rcp_f32_e32 v170, v170
	v_rcp_f32_e32 v171, v171
	v_pk_fma_f32 v[172:173], v[164:165], v[188:189], v[190:191]
	v_pk_fma_f32 v[174:175], v[166:167], v[188:189], v[190:191]
	v_pk_fma_f32 v[176:177], v[168:169], v[188:189], v[190:191]
	v_pk_fma_f32 v[178:179], v[170:171], v[188:189], v[190:191]
	v_pk_fma_f32 v[172:173], v[172:173], v[164:165], v[192:193]
	v_pk_fma_f32 v[174:175], v[174:175], v[166:167], v[192:193]
	v_pk_fma_f32 v[176:177], v[176:177], v[168:169], v[192:193]
	v_pk_fma_f32 v[178:179], v[178:179], v[170:171], v[192:193]
	v_pk_fma_f32 v[172:173], v[172:173], v[164:165], v[194:195]
	v_pk_fma_f32 v[174:175], v[174:175], v[166:167], v[194:195]
	v_pk_fma_f32 v[176:177], v[176:177], v[168:169], v[194:195]
	v_pk_fma_f32 v[178:179], v[178:179], v[170:171], v[194:195]
	v_pk_fma_f32 v[172:173], v[172:173], v[164:165], v[196:197]
	v_pk_fma_f32 v[174:175], v[174:175], v[166:167], v[196:197]
	v_pk_fma_f32 v[176:177], v[176:177], v[168:169], v[196:197]
	v_pk_fma_f32 v[178:179], v[178:179], v[170:171], v[196:197]
	v_pk_mul_f32 v[172:173], v[172:173], v[164:165]
	v_pk_mul_f32 v[174:175], v[174:175], v[166:167]
	v_pk_mul_f32 v[176:177], v[176:177], v[168:169]
	v_pk_mul_f32 v[178:179], v[178:179], v[170:171]
	v_pk_mul_f32 v[164:165], v[148:149], v[148:149]
	v_pk_mul_f32 v[166:167], v[150:151], v[150:151]
	v_pk_mul_f32 v[168:169], v[152:153], v[152:153]
	v_pk_mul_f32 v[170:171], v[154:155], v[154:155]
	v_pk_mul_f32 v[164:165], v[164:165], v[198:199]
	v_pk_mul_f32 v[166:167], v[166:167], v[198:199]
	v_pk_mul_f32 v[168:169], v[168:169], v[198:199]
	v_pk_mul_f32 v[170:171], v[170:171], v[198:199]
	v_exp_f32_e32 v164, v164
	v_exp_f32_e32 v165, v165
	v_exp_f32_e32 v166, v166
	v_exp_f32_e32 v167, v167
	v_exp_f32_e32 v168, v168
	v_exp_f32_e32 v169, v169
	v_exp_f32_e32 v170, v170
	v_exp_f32_e32 v171, v171
	v_pk_mul_f32 v[172:173], v[172:173], v[164:165]
	v_pk_mul_f32 v[174:175], v[174:175], v[166:167]
; __device__ __forceinline__ unsigned cvt_pk_bf16(float lo, float hi) { unsigned r; asm volatile("v_cvt_pk_bf16_f32 %0, %1, %2" : "=v"(r) : "v"(lo), "v"(hi)); return r; }
; __device__ __forceinline__ float gelu_as(float v) {
;   const float av = fabsf(v); const float t = __builtin_amdgcn_rcpf(av * 0.2316418882f + 1.0f);
;   float q = t * 0.5307027145f + (-0.7265760135f); q = q * t + 0.7107068705f; q = q * t + (-0.142248368f); q = q * t + 0.127414796f; q = q * t;
;   const float e = __builtin_amdgcn_exp2f((v * v) * (-0.72134752044f));
;   const float m = v * (q * e);
;   return v < 0.f ? m : v - m;
; }
; __device__ __forceinline__ void phase_conv(KP p, int l, int tid) {
;     ...
;     for (int jb = j0; jb < j0 + 16; jb += CB) {
;       u32x2 an[CB][RB + 2], ur[CB][RB];
; #pragma unroll
;       for (int q = 0; q < CB; ++q) { const int col = jb + q + 1; const int cl = col > 63 ? 63 : col;
; #pragma unroll
;         for (int di = 0; di < RB + 2; ++di) an[q][di] = *(const u32x2*)(rowp[di] + (size_t)cl * DFF);
; #pragma unroll
;         for (int rr = 0; rr < RB; ++rr) ur[q][rr] = *(const u32x2*)(U + (size_t)((r0 + rr) * 64 + jb + q) * DFF + c0); }
;       __builtin_amdgcn_sched_barrier(0);
; #pragma unroll
;       for (int q = 0; q < CB; ++q) {
;         const int col = jb + q + 1;
; #pragma unroll
;         for (int di = 0; di < RB + 2; ++di) { const bool ok = rv[di] && (col < 64); unpack4(an[q][di], win[2][di]);
; #pragma unroll
;           for (int k = 0; k < 4; ++k) win[2][di][k] = ok ? win[2][di][k] : 0.f; }
; #pragma unroll
;         for (int rr = 0; rr < RB; ++rr) {
;           float uv[4]; unpack4(ur[q][rr], uv);
;           float o[4];
; #pragma unroll
;           for (int k = 0; k < 4; ++k) {
;             float a = bsv[k];
; #pragma unroll
;             for (int di = 0; di < 3; ++di)
; #pragma unroll
;               for (int dj = 0; dj < 3; ++dj) a += win[dj][rr + di][k] * w[di * 3 + dj][k];
;             o[k] = gelu_as(a) * uv[k];
;           }
;           u32x2 ow; ow.x = cvt_pk_bf16(o[0], o[1]); ow.y = cvt_pk_bf16(o[2], o[3]);
;           *(u32x2*)(G + (size_t)((r0 + rr) * 64 + jb + q) * DFF + c0) = ow;
;         }
; #pragma unroll
;         for (int di = 0; di < RB + 2; ++di)
; #pragma unroll
;           for (int k = 0; k < 4; ++k) { win[0][di][k] = win[1][di][k]; win[1][di][k] = win[2][di][k]; }
;       }
	v_pk_mul_f32 v[176:177], v[176:177], v[168:169]
	v_pk_mul_f32 v[178:179], v[178:179], v[170:171]
	v_pk_mul_f32 v[172:173], v[156:157], v[172:173]
	v_pk_mul_f32 v[174:175], v[158:159], v[174:175]
	v_pk_mul_f32 v[176:177], v[160:161], v[176:177]
	v_pk_mul_f32 v[178:179], v[162:163], v[178:179]
	v_max_f32_e32 v164, 0, v148
	v_max_f32_e32 v165, 0, v149
	v_max_f32_e32 v166, 0, v150
	v_max_f32_e32 v167, 0, v151
	v_max_f32_e32 v168, 0, v152
	v_max_f32_e32 v169, 0, v153
	v_max_f32_e32 v170, 0, v154
	v_max_f32_e32 v171, 0, v155
	v_pk_add_f32 v[164:165], v[164:165], v[172:173] neg_lo:[0,1] neg_hi:[0,1]
	v_pk_add_f32 v[166:167], v[166:167], v[174:175] neg_lo:[0,1] neg_hi:[0,1]
	v_pk_add_f32 v[168:169], v[168:169], v[176:177] neg_lo:[0,1] neg_hi:[0,1]
	v_pk_add_f32 v[170:171], v[170:171], v[178:179] neg_lo:[0,1] neg_hi:[0,1]
	v_pk_mul_f32 v[164:165], v[164:165], v[124:125]
	v_pk_mul_f32 v[166:167], v[166:167], v[126:127]
	v_pk_mul_f32 v[168:169], v[168:169], v[128:129]
	v_pk_mul_f32 v[170:171], v[170:171], v[130:131]
	v_cvt_pk_bf16_f32 v156, v164, v165
	v_cvt_pk_bf16_f32 v157, v166, v167
	v_cvt_pk_bf16_f32 v158, v168, v169
	v_cvt_pk_bf16_f32 v159, v170, v171
	global_store_dwordx2 v216, v[156:157], s[10:11]
	global_store_dwordx2 v217, v[158:159], s[10:11]
	v_add_u32_e32 v210, 0x2c00, v210
	v_add_u32_e32 v211, 0x2c00, v210
	v_add_u32_e32 v212, v206, v211
	global_load_dwordx2 v[88:89], v212, s[6:7]
	v_add_u32_e32 v213, v207, v211
	global_load_dwordx2 v[90:91], v213, s[6:7]
	v_add_u32_e32 v214, v208, v211
	global_load_dwordx2 v[92:93], v214, s[6:7]
	v_add_u32_e32 v215, v209, v211
	global_load_dwordx2 v[94:95], v215, s[6:7]
	v_add_u32_e32 v216, v207, v210
	global_load_dwordx2 v[112:113], v216, s[8:9]
	v_add_u32_e32 v217, v208, v210
	global_load_dwordx2 v[114:115], v217, s[8:9]
	s_waitcnt vmcnt(16)
	v_lshlrev_b32_e32 v40, 16, v96
	v_and_b32_e32 v41, 0xffff0000, v96
	v_lshlrev_b32_e32 v42, 16, v97
	v_and_b32_e32 v43, 0xffff0000, v97
	v_lshlrev_b32_e32 v44, 16, v98
	v_and_b32_e32 v45, 0xffff0000, v98
	v_lshlrev_b32_e32 v46, 16, v99
	v_and_b32_e32 v47, 0xffff0000, v99
	v_lshlrev_b32_e32 v48, 16, v100
	v_and_b32_e32 v49, 0xffff0000, v100
	v_lshlrev_b32_e32 v50, 16, v101
	v_and_b32_e32 v51, 0xffff0000, v101
	v_lshlrev_b32_e32 v52, 16, v102
	v_and_b32_e32 v53, 0xffff0000, v102
	v_lshlrev_b32_e32 v54, 16, v103
	v_and_b32_e32 v55, 0xffff0000, v103
	v_pk_mul_f32 v[40:41], v[40:41], v[200:201]
	v_pk_mul_f32 v[42:43], v[42:43], v[200:201]
	v_pk_mul_f32 v[52:53], v[52:53], v[202:203]
	v_pk_mul_f32 v[54:55], v[54:55], v[202:203]
	v_lshlrev_b32_e32 v124, 16, v116
	v_and_b32_e32 v125, 0xffff0000, v116
	v_lshlrev_b32_e32 v126, 16, v117
	v_and_b32_e32 v127, 0xffff0000, v117
	v_lshlrev_b32_e32 v128, 16, v118
	v_and_b32_e32 v129, 0xffff0000, v118
	v_lshlrev_b32_e32 v130, 16, v119
	v_and_b32_e32 v131, 0xffff0000, v119
	v_pk_fma_f32 v[148:149], v[56:57], v[0:1], v[36:37]
	v_pk_fma_f32 v[150:151], v[58:59], v[2:3], v[38:39]
	v_pk_fma_f32 v[152:153], v[60:61], v[0:1], v[36:37]
	v_pk_fma_f32 v[154:155], v[62:63], v[2:3], v[38:39]
	v_pk_fma_f32 v[148:149], v[72:73], v[4:5], v[148:149]
	v_pk_fma_f32 v[150:151], v[74:75], v[6:7], v[150:151]
	v_pk_fma_f32 v[152:153], v[76:77], v[4:5], v[152:153]
	v_pk_fma_f32 v[154:155], v[78:79], v[6:7], v[154:155]
	v_pk_fma_f32 v[148:149], v[40:41], v[8:9], v[148:149]
	v_pk_fma_f32 v[150:151], v[42:43], v[10:11], v[150:151]
	v_pk_fma_f32 v[152:153], v[44:45], v[8:9], v[152:153]
	v_pk_fma_f32 v[154:155], v[46:47], v[10:11], v[154:155]
	v_pk_fma_f32 v[148:149], v[60:61], v[12:13], v[148:149]
	v_pk_fma_f32 v[150:151], v[62:63], v[14:15], v[150:151]
	v_pk_fma_f32 v[152:153], v[64:65], v[12:13], v[152:153]
	v_pk_fma_f32 v[154:155], v[66:67], v[14:15], v[154:155]
	v_pk_fma_f32 v[148:149], v[76:77], v[16:17], v[148:149]
	v_pk_fma_f32 v[150:151], v[78:79], v[18:19], v[150:151]
	v_pk_fma_f32 v[152:153], v[80:81], v[16:17], v[152:153]
	v_pk_fma_f32 v[154:155], v[82:83], v[18:19], v[154:155]
	v_pk_fma_f32 v[148:149], v[44:45], v[20:21], v[148:149]
	v_pk_fma_f32 v[150:151], v[46:47], v[22:23], v[150:151]
	v_pk_fma_f32 v[152:153], v[48:49], v[20:21], v[152:153]
	v_pk_fma_f32 v[154:155], v[50:51], v[22:23], v[154:155]
	v_pk_fma_f32 v[148:149], v[64:65], v[24:25], v[148:149]
	v_pk_fma_f32 v[150:151], v[66:67], v[26:27], v[150:151]
	v_pk_fma_f32 v[152:153], v[68:69], v[24:25], v[152:153]
	v_pk_fma_f32 v[154:155], v[70:71], v[26:27], v[154:155]
	v_pk_fma_f32 v[148:149], v[80:81], v[28:29], v[148:149]
	v_pk_fma_f32 v[150:151], v[82:83], v[30:31], v[150:151]
	v_pk_fma_f32 v[152:153], v[84:85], v[28:29], v[152:153]
	v_pk_fma_f32 v[154:155], v[86:87], v[30:31], v[154:155]
	v_pk_fma_f32 v[148:149], v[48:49], v[32:33], v[148:149]
	v_pk_fma_f32 v[150:151], v[50:51], v[34:35], v[150:151]
	v_pk_fma_f32 v[152:153], v[52:53], v[32:33], v[152:153]
	v_pk_fma_f32 v[154:155], v[54:55], v[34:35], v[154:155]
	v_and_b32_e32 v156, 0x7fffffff, v148
	v_and_b32_e32 v157, 0x7fffffff, v149
	v_and_b32_e32 v158, 0x7fffffff, v150
	v_and_b32_e32 v159, 0x7fffffff, v151
	v_and_b32_e32 v160, 0x7fffffff, v152
	v_and_b32_e32 v161, 0x7fffffff, v153
	v_and_b32_e32 v162, 0x7fffffff, v154
	v_and_b32_e32 v163, 0x7fffffff, v155
	v_pk_fma_f32 v[164:165], v[156:157], v[184:185], v[186:187]
	v_pk_fma_f32 v[166:167], v[158:159], v[184:185], v[186:187]
	v_pk_fma_f32 v[168:169], v[160:161], v[184:185], v[186:187]
	v_pk_fma_f32 v[170:171], v[162:163], v[184:185], v[186:187]
	v_rcp_f32_e32 v164, v164
	v_rcp_f32_e32 v165, v165
	v_rcp_f32_e32 v166, v166
	v_rcp_f32_e32 v167, v167
	v_rcp_f32_e32 v168, v168
	v_rcp_f32_e32 v169, v169
	v_rcp_f32_e32 v170, v170
	v_rcp_f32_e32 v171, v171
; __device__ __forceinline__ unsigned cvt_pk_bf16(float lo, float hi) { unsigned r; asm volatile("v_cvt_pk_bf16_f32 %0, %1, %2" : "=v"(r) : "v"(lo), "v"(hi)); return r; }
; __device__ __forceinline__ float gelu_as(float v) {
;   const float av = fabsf(v); const float t = __builtin_amdgcn_rcpf(av * 0.2316418882f + 1.0f);
;   float q = t * 0.5307027145f + (-0.7265760135f); q = q * t + 0.7107068705f; q = q * t + (-0.142248368f); q = q * t + 0.127414796f; q = q * t;
;   const float e = __builtin_amdgcn_exp2f((v * v) * (-0.72134752044f));
;   const float m = v * (q * e);
;   return v < 0.f ? m : v - m;
; }
; __device__ __forceinline__ void phase_conv(KP p, int l, int tid) {
;     ...
;     for (int jb = j0; jb < j0 + 16; jb += CB) {
;       u32x2 an[CB][RB + 2], ur[CB][RB];
; #pragma unroll
;       for (int q = 0; q < CB; ++q) { const int col = jb + q + 1; const int cl = col > 63 ? 63 : col;
; #pragma unroll
;         for (int di = 0; di < RB + 2; ++di) an[q][di] = *(const u32x2*)(rowp[di] + (size_t)cl * DFF);
; #pragma unroll
;         for (int rr = 0; rr < RB; ++rr) ur[q][rr] = *(const u32x2*)(U + (size_t)((r0 + rr) * 64 + jb + q) * DFF + c0); }
;       __builtin_amdgcn_sched_barrier(0);
; #pragma unroll
;       for (int q = 0; q < CB; ++q) {
;         const int col = jb + q + 1;
; #pragma unroll
;         for (int di = 0; di < RB + 2; ++di) { const bool ok = rv[di] && (col < 64); unpack4(an[q][di], win[2][di]);
; #pragma unroll
;           for (int k = 0; k < 4; ++k) win[2][di][k] = ok ? win[2][di][k] : 0.f; }
; #pragma unroll
;         for (int rr = 0; rr < RB; ++rr) {
;           float uv[4]; unpack4(ur[q][rr], uv);
;           float o[4];
; #pragma unroll
;           for (int k = 0; k < 4; ++k) {
;             float a = bsv[k];
; #pragma unroll
;             for (int di = 0; di < 3; ++di)
; #pragma unroll
;               for (int dj = 0; dj < 3; ++dj) a += win[dj][rr + di][k] * w[di * 3 + dj][k];
;             o[k] = gelu_as(a) * uv[k];
;           }
;           u32x2 ow; ow.x = cvt_pk_bf16(o[0], o[1]); ow.y = cvt_pk_bf16(o[2], o[3]);
;           *(u32x2*)(G + (size_t)((r0 + rr) * 64 + jb + q) * DFF + c0) = ow;
;         }
; #pragma unroll
;         for (int di = 0; di < RB + 2; ++di)
; #pragma unroll
;           for (int k = 0; k < 4; ++k) { win[0][di][k] = win[1][di][k]; win[1][di][k] = win[2][di][k]; }
;       }
	v_pk_fma_f32 v[172:173], v[164:165], v[188:189], v[190:191]
	v_pk_fma_f32 v[174:175], v[166:167], v[188:189], v[190:191]
	v_pk_fma_f32 v[176:177], v[168:169], v[188:189], v[190:191]
	v_pk_fma_f32 v[178:179], v[170:171], v[188:189], v[190:191]
	v_pk_fma_f32 v[172:173], v[172:173], v[164:165], v[192:193]
	v_pk_fma_f32 v[174:175], v[174:175], v[166:167], v[192:193]
	v_pk_fma_f32 v[176:177], v[176:177], v[168:169], v[192:193]
	v_pk_fma_f32 v[178:179], v[178:179], v[170:171], v[192:193]
	v_pk_fma_f32 v[172:173], v[172:173], v[164:165], v[194:195]
	v_pk_fma_f32 v[174:175], v[174:175], v[166:167], v[194:195]
	v_pk_fma_f32 v[176:177], v[176:177], v[168:169], v[194:195]
	v_pk_fma_f32 v[178:179], v[178:179], v[170:171], v[194:195]
	v_pk_fma_f32 v[172:173], v[172:173], v[164:165], v[196:197]
	v_pk_fma_f32 v[174:175], v[174:175], v[166:167], v[196:197]
	v_pk_fma_f32 v[176:177], v[176:177], v[168:169], v[196:197]
	v_pk_fma_f32 v[178:179], v[178:179], v[170:171], v[196:197]
	v_pk_mul_f32 v[172:173], v[172:173], v[164:165]
	v_pk_mul_f32 v[174:175], v[174:175], v[166:167]
	v_pk_mul_f32 v[176:177], v[176:177], v[168:169]
	v_pk_mul_f32 v[178:179], v[178:179], v[170:171]
	v_pk_mul_f32 v[164:165], v[148:149], v[148:149]
	v_pk_mul_f32 v[166:167], v[150:151], v[150:151]
	v_pk_mul_f32 v[168:169], v[152:153], v[152:153]
	v_pk_mul_f32 v[170:171], v[154:155], v[154:155]
	v_pk_mul_f32 v[164:165], v[164:165], v[198:199]
	v_pk_mul_f32 v[166:167], v[166:167], v[198:199]
	v_pk_mul_f32 v[168:169], v[168:169], v[198:199]
	v_pk_mul_f32 v[170:171], v[170:171], v[198:199]
	v_exp_f32_e32 v164, v164
	v_exp_f32_e32 v165, v165
	v_exp_f32_e32 v166, v166
	v_exp_f32_e32 v167, v167
	v_exp_f32_e32 v168, v168
	v_exp_f32_e32 v169, v169
	v_exp_f32_e32 v170, v170
	v_exp_f32_e32 v171, v171
	v_pk_mul_f32 v[172:173], v[172:173], v[164:165]
	v_pk_mul_f32 v[174:175], v[174:175], v[166:167]
	v_pk_mul_f32 v[176:177], v[176:177], v[168:169]
	v_pk_mul_f32 v[178:179], v[178:179], v[170:171]
	v_pk_mul_f32 v[172:173], v[156:157], v[172:173]
	v_pk_mul_f32 v[174:175], v[158:159], v[174:175]
	v_pk_mul_f32 v[176:177], v[160:161], v[176:177]
	v_pk_mul_f32 v[178:179], v[162:163], v[178:179]
	v_max_f32_e32 v164, 0, v148
	v_max_f32_e32 v165, 0, v149
	v_max_f32_e32 v166, 0, v150
	v_max_f32_e32 v167, 0, v151
	v_max_f32_e32 v168, 0, v152
	v_max_f32_e32 v169, 0, v153
	v_max_f32_e32 v170, 0, v154
	v_max_f32_e32 v171, 0, v155
	v_pk_add_f32 v[164:165], v[164:165], v[172:173] neg_lo:[0,1] neg_hi:[0,1]
	v_pk_add_f32 v[166:167], v[166:167], v[174:175] neg_lo:[0,1] neg_hi:[0,1]
	v_pk_add_f32 v[168:169], v[168:169], v[176:177] neg_lo:[0,1] neg_hi:[0,1]
	v_pk_add_f32 v[170:171], v[170:171], v[178:179] neg_lo:[0,1] neg_hi:[0,1]
	v_pk_mul_f32 v[164:165], v[164:165], v[124:125]
	v_pk_mul_f32 v[166:167], v[166:167], v[126:127]
	v_pk_mul_f32 v[168:169], v[168:169], v[128:129]
	v_pk_mul_f32 v[170:171], v[170:171], v[130:131]
	v_cvt_pk_bf16_f32 v156, v164, v165
	v_cvt_pk_bf16_f32 v157, v166, v167
	v_cvt_pk_bf16_f32 v158, v168, v169
	v_cvt_pk_bf16_f32 v159, v170, v171
	global_store_dwordx2 v218, v[156:157], s[10:11]
	global_store_dwordx2 v219, v[158:159], s[10:11]
	v_add_u32_e32 v210, 0x2c00, v210
	v_add_u32_e32 v211, 0x2c00, v210
	v_add_u32_e32 v212, v206, v211
	global_load_dwordx2 v[96:97], v212, s[6:7]
	v_add_u32_e32 v213, v207, v211
	global_load_dwordx2 v[98:99], v213, s[6:7]
	v_add_u32_e32 v214, v208, v211
	global_load_dwordx2 v[100:101], v214, s[6:7]
	v_add_u32_e32 v215, v209, v211
	global_load_dwordx2 v[102:103], v215, s[6:7]
	v_add_u32_e32 v218, v207, v210
	global_load_dwordx2 v[116:117], v218, s[8:9]
	v_add_u32_e32 v219, v208, v210
	global_load_dwordx2 v[118:119], v219, s[8:9]
	s_waitcnt vmcnt(16)
	v_lshlrev_b32_e32 v56, 16, v104
	v_and_b32_e32 v57, 0xffff0000, v104
	v_lshlrev_b32_e32 v58, 16, v105
	v_and_b32_e32 v59, 0xffff0000, v105
	v_lshlrev_b32_e32 v60, 16, v106
	v_and_b32_e32 v61, 0xffff0000, v106
	v_lshlrev_b32_e32 v62, 16, v107
	v_and_b32_e32 v63, 0xffff0000, v107
	v_lshlrev_b32_e32 v64, 16, v108
	v_and_b32_e32 v65, 0xffff0000, v108
	v_lshlrev_b32_e32 v66, 16, v109
	v_and_b32_e32 v67, 0xffff0000, v109
	v_lshlrev_b32_e32 v68, 16, v110
	v_and_b32_e32 v69, 0xffff0000, v110
	v_lshlrev_b32_e32 v70, 16, v111
	v_and_b32_e32 v71, 0xffff0000, v111
	v_pk_mul_f32 v[56:57], v[56:57], v[200:201]
	v_pk_mul_f32 v[58:59], v[58:59], v[200:201]
	v_pk_mul_f32 v[68:69], v[68:69], v[202:203]
	v_pk_mul_f32 v[70:71], v[70:71], v[202:203]
	v_lshlrev_b32_e32 v124, 16, v120
	v_and_b32_e32 v125, 0xffff0000, v120
	v_lshlrev_b32_e32 v126, 16, v121
	v_and_b32_e32 v127, 0xffff0000, v121
	v_lshlrev_b32_e32 v128, 16, v122
	v_and_b32_e32 v129, 0xffff0000, v122
	v_lshlrev_b32_e32 v130, 16, v123
	v_and_b32_e32 v131, 0xffff0000, v123
	v_pk_fma_f32 v[148:149], v[72:73], v[0:1], v[36:37]
	v_pk_fma_f32 v[150:151], v[74:75], v[2:3], v[38:39]
	v_pk_fma_f32 v[152:153], v[76:77], v[0:1], v[36:37]
	v_pk_fma_f32 v[154:155], v[78:79], v[2:3], v[38:39]
	v_pk_fma_f32 v[148:149], v[40:41], v[4:5], v[148:149]
	v_pk_fma_f32 v[150:151], v[42:43], v[6:7], v[150:151]
	v_pk_fma_f32 v[152:153], v[44:45], v[4:5], v[152:153]
	v_pk_fma_f32 v[154:155], v[46:47], v[6:7], v[154:155]
	v_pk_fma_f32 v[148:149], v[56:57], v[8:9], v[148:149]
	v_pk_fma_f32 v[150:151], v[58:59], v[10:11], v[150:151]
	v_pk_fma_f32 v[152:153], v[60:61], v[8:9], v[152:153]
	v_pk_fma_f32 v[154:155], v[62:63], v[10:11], v[154:155]
	v_pk_fma_f32 v[148:149], v[76:77], v[12:13], v[148:149]
	v_pk_fma_f32 v[150:151], v[78:79], v[14:15], v[150:151]
	v_pk_fma_f32 v[152:153], v[80:81], v[12:13], v[152:153]
	v_pk_fma_f32 v[154:155], v[82:83], v[14:15], v[154:155]
	v_pk_fma_f32 v[148:149], v[44:45], v[16:17], v[148:149]
; __device__ __forceinline__ unsigned cvt_pk_bf16(float lo, float hi) { unsigned r; asm volatile("v_cvt_pk_bf16_f32 %0, %1, %2" : "=v"(r) : "v"(lo), "v"(hi)); return r; }
; __device__ __forceinline__ float gelu_as(float v) {
;   const float av = fabsf(v); const float t = __builtin_amdgcn_rcpf(av * 0.2316418882f + 1.0f);
;   float q = t * 0.5307027145f + (-0.7265760135f); q = q * t + 0.7107068705f; q = q * t + (-0.142248368f); q = q * t + 0.127414796f; q = q * t;
;   const float e = __builtin_amdgcn_exp2f((v * v) * (-0.72134752044f));
;   const float m = v * (q * e);
;   return v < 0.f ? m : v - m;
; }
; __device__ __forceinline__ void phase_conv(KP p, int l, int tid) {
;     ...
;     for (int jb = j0; jb < j0 + 16; jb += CB) {
;       u32x2 an[CB][RB + 2], ur[CB][RB];
; #pragma unroll
;       for (int q = 0; q < CB; ++q) { const int col = jb + q + 1; const int cl = col > 63 ? 63 : col;
; #pragma unroll
;         for (int di = 0; di < RB + 2; ++di) an[q][di] = *(const u32x2*)(rowp[di] + (size_t)cl * DFF);
; #pragma unroll
;         for (int rr = 0; rr < RB; ++rr) ur[q][rr] = *(const u32x2*)(U + (size_t)((r0 + rr) * 64 + jb + q) * DFF + c0); }
;       __builtin_amdgcn_sched_barrier(0);
; #pragma unroll
;       for (int q = 0; q < CB; ++q) {
;         const int col = jb + q + 1;
; #pragma unroll
;         for (int di = 0; di < RB + 2; ++di) { const bool ok = rv[di] && (col < 64); unpack4(an[q][di], win[2][di]);
; #pragma unroll
;           for (int k = 0; k < 4; ++k) win[2][di][k] = ok ? win[2][di][k] : 0.f; }
; #pragma unroll
;         for (int rr = 0; rr < RB; ++rr) {
;           float uv[4]; unpack4(ur[q][rr], uv);
;           float o[4];
; #pragma unroll
;           for (int k = 0; k < 4; ++k) {
;             float a = bsv[k];
; #pragma unroll
;             for (int di = 0; di < 3; ++di)
; #pragma unroll
;               for (int dj = 0; dj < 3; ++dj) a += win[dj][rr + di][k] * w[di * 3 + dj][k];
;             o[k] = gelu_as(a) * uv[k];
;           }
;           u32x2 ow; ow.x = cvt_pk_bf16(o[0], o[1]); ow.y = cvt_pk_bf16(o[2], o[3]);
;           *(u32x2*)(G + (size_t)((r0 + rr) * 64 + jb + q) * DFF + c0) = ow;
;         }
; #pragma unroll
;         for (int di = 0; di < RB + 2; ++di)
; #pragma unroll
;           for (int k = 0; k < 4; ++k) { win[0][di][k] = win[1][di][k]; win[1][di][k] = win[2][di][k]; }
;       }
	v_pk_fma_f32 v[150:151], v[46:47], v[18:19], v[150:151]
	v_pk_fma_f32 v[152:153], v[48:49], v[16:17], v[152:153]
	v_pk_fma_f32 v[154:155], v[50:51], v[18:19], v[154:155]
	v_pk_fma_f32 v[148:149], v[60:61], v[20:21], v[148:149]
	v_pk_fma_f32 v[150:151], v[62:63], v[22:23], v[150:151]
	v_pk_fma_f32 v[152:153], v[64:65], v[20:21], v[152:153]
	v_pk_fma_f32 v[154:155], v[66:67], v[22:23], v[154:155]
	v_pk_fma_f32 v[148:149], v[80:81], v[24:25], v[148:149]
	v_pk_fma_f32 v[150:151], v[82:83], v[26:27], v[150:151]
	v_pk_fma_f32 v[152:153], v[84:85], v[24:25], v[152:153]
	v_pk_fma_f32 v[154:155], v[86:87], v[26:27], v[154:155]
	v_pk_fma_f32 v[148:149], v[48:49], v[28:29], v[148:149]
	v_pk_fma_f32 v[150:151], v[50:51], v[30:31], v[150:151]
	v_pk_fma_f32 v[152:153], v[52:53], v[28:29], v[152:153]
	v_pk_fma_f32 v[154:155], v[54:55], v[30:31], v[154:155]
	v_pk_fma_f32 v[148:149], v[64:65], v[32:33], v[148:149]
	v_pk_fma_f32 v[150:151], v[66:67], v[34:35], v[150:151]
	v_pk_fma_f32 v[152:153], v[68:69], v[32:33], v[152:153]
	v_pk_fma_f32 v[154:155], v[70:71], v[34:35], v[154:155]
	v_and_b32_e32 v156, 0x7fffffff, v148
	v_and_b32_e32 v157, 0x7fffffff, v149
	v_and_b32_e32 v158, 0x7fffffff, v150
	v_and_b32_e32 v159, 0x7fffffff, v151
	v_and_b32_e32 v160, 0x7fffffff, v152
	v_and_b32_e32 v161, 0x7fffffff, v153
	v_and_b32_e32 v162, 0x7fffffff, v154
	v_and_b32_e32 v163, 0x7fffffff, v155
	v_pk_fma_f32 v[164:165], v[156:157], v[184:185], v[186:187]
	v_pk_fma_f32 v[166:167], v[158:159], v[184:185], v[186:187]
	v_pk_fma_f32 v[168:169], v[160:161], v[184:185], v[186:187]
	v_pk_fma_f32 v[170:171], v[162:163], v[184:185], v[186:187]
	v_rcp_f32_e32 v164, v164
	v_rcp_f32_e32 v165, v165
	v_rcp_f32_e32 v166, v166
	v_rcp_f32_e32 v167, v167
	v_rcp_f32_e32 v168, v168
	v_rcp_f32_e32 v169, v169
	v_rcp_f32_e32 v170, v170
	v_rcp_f32_e32 v171, v171
	v_pk_fma_f32 v[172:173], v[164:165], v[188:189], v[190:191]
	v_pk_fma_f32 v[174:175], v[166:167], v[188:189], v[190:191]
	v_pk_fma_f32 v[176:177], v[168:169], v[188:189], v[190:191]
	v_pk_fma_f32 v[178:179], v[170:171], v[188:189], v[190:191]
	v_pk_fma_f32 v[172:173], v[172:173], v[164:165], v[192:193]
	v_pk_fma_f32 v[174:175], v[174:175], v[166:167], v[192:193]
	v_pk_fma_f32 v[176:177], v[176:177], v[168:169], v[192:193]
	v_pk_fma_f32 v[178:179], v[178:179], v[170:171], v[192:193]
	v_pk_fma_f32 v[172:173], v[172:173], v[164:165], v[194:195]
	v_pk_fma_f32 v[174:175], v[174:175], v[166:167], v[194:195]
	v_pk_fma_f32 v[176:177], v[176:177], v[168:169], v[194:195]
	v_pk_fma_f32 v[178:179], v[178:179], v[170:171], v[194:195]
	v_pk_fma_f32 v[172:173], v[172:173], v[164:165], v[196:197]
	v_pk_fma_f32 v[174:175], v[174:175], v[166:167], v[196:197]
	v_pk_fma_f32 v[176:177], v[176:177], v[168:169], v[196:197]
	v_pk_fma_f32 v[178:179], v[178:179], v[170:171], v[196:197]
	v_pk_mul_f32 v[172:173], v[172:173], v[164:165]
	v_pk_mul_f32 v[174:175], v[174:175], v[166:167]
	v_pk_mul_f32 v[176:177], v[176:177], v[168:169]
	v_pk_mul_f32 v[178:179], v[178:179], v[170:171]
	v_pk_mul_f32 v[164:165], v[148:149], v[148:149]
	v_pk_mul_f32 v[166:167], v[150:151], v[150:151]
	v_pk_mul_f32 v[168:169], v[152:153], v[152:153]
	v_pk_mul_f32 v[170:171], v[154:155], v[154:155]
	v_pk_mul_f32 v[164:165], v[164:165], v[198:199]
	v_pk_mul_f32 v[166:167], v[166:167], v[198:199]
	v_pk_mul_f32 v[168:169], v[168:169], v[198:199]
	v_pk_mul_f32 v[170:171], v[170:171], v[198:199]
	v_exp_f32_e32 v164, v164
	v_exp_f32_e32 v165, v165
	v_exp_f32_e32 v166, v166
	v_exp_f32_e32 v167, v167
	v_exp_f32_e32 v168, v168
	v_exp_f32_e32 v169, v169
	v_exp_f32_e32 v170, v170
	v_exp_f32_e32 v171, v171
	v_pk_mul_f32 v[172:173], v[172:173], v[164:165]
	v_pk_mul_f32 v[174:175], v[174:175], v[166:167]
	v_pk_mul_f32 v[176:177], v[176:177], v[168:169]
	v_pk_mul_f32 v[178:179], v[178:179], v[170:171]
	v_pk_mul_f32 v[172:173], v[156:157], v[172:173]
	v_pk_mul_f32 v[174:175], v[158:159], v[174:175]
	v_pk_mul_f32 v[176:177], v[160:161], v[176:177]
	v_pk_mul_f32 v[178:179], v[162:163], v[178:179]
	v_max_f32_e32 v164, 0, v148
	v_max_f32_e32 v165, 0, v149
	v_max_f32_e32 v166, 0, v150
	v_max_f32_e32 v167, 0, v151
	v_max_f32_e32 v168, 0, v152
	v_max_f32_e32 v169, 0, v153
	v_max_f32_e32 v170, 0, v154
	v_max_f32_e32 v171, 0, v155
	v_pk_add_f32 v[164:165], v[164:165], v[172:173] neg_lo:[0,1] neg_hi:[0,1]
	v_pk_add_f32 v[166:167], v[166:167], v[174:175] neg_lo:[0,1] neg_hi:[0,1]
	v_pk_add_f32 v[168:169], v[168:169], v[176:177] neg_lo:[0,1] neg_hi:[0,1]
	v_pk_add_f32 v[170:171], v[170:171], v[178:179] neg_lo:[0,1] neg_hi:[0,1]
	v_pk_mul_f32 v[164:165], v[164:165], v[124:125]
	v_pk_mul_f32 v[166:167], v[166:167], v[126:127]
	v_pk_mul_f32 v[168:169], v[168:169], v[128:129]
	v_pk_mul_f32 v[170:171], v[170:171], v[130:131]
	v_cvt_pk_bf16_f32 v156, v164, v165
	v_cvt_pk_bf16_f32 v157, v166, v167
	v_cvt_pk_bf16_f32 v158, v168, v169
	v_cvt_pk_bf16_f32 v159, v170, v171
	global_store_dwordx2 v220, v[156:157], s[10:11]
	global_store_dwordx2 v221, v[158:159], s[10:11]
	v_add_u32_e32 v210, 0x2c00, v210
	v_add_u32_e32 v211, 0x2c00, v210
	v_add_u32_e32 v212, v206, v211
	global_load_dwordx2 v[104:105], v212, s[6:7]
	v_add_u32_e32 v213, v207, v211
	global_load_dwordx2 v[106:107], v213, s[6:7]
	v_add_u32_e32 v214, v208, v211
	global_load_dwordx2 v[108:109], v214, s[6:7]
	v_add_u32_e32 v215, v209, v211
	global_load_dwordx2 v[110:111], v215, s[6:7]
	v_add_u32_e32 v220, v207, v210
	global_load_dwordx2 v[120:121], v220, s[8:9]
	v_add_u32_e32 v221, v208, v210
	global_load_dwordx2 v[122:123], v221, s[8:9]
	s_waitcnt vmcnt(16)
; __device__ __forceinline__ unsigned cvt_pk_bf16(float lo, float hi) { unsigned r; asm volatile("v_cvt_pk_bf16_f32 %0, %1, %2" : "=v"(r) : "v"(lo), "v"(hi)); return r; }
; __device__ __forceinline__ float gelu_as(float v) {
;   const float av = fabsf(v); const float t = __builtin_amdgcn_rcpf(av * 0.2316418882f + 1.0f);
;   float q = t * 0.5307027145f + (-0.7265760135f); q = q * t + 0.7107068705f; q = q * t + (-0.142248368f); q = q * t + 0.127414796f; q = q * t;
;   const float e = __builtin_amdgcn_exp2f((v * v) * (-0.72134752044f));
;   const float m = v * (q * e);
;   return v < 0.f ? m : v - m;
; }
; __device__ __forceinline__ void phase_conv(KP p, int l, int tid) {
;     ...
;     for (int jb = j0; jb < j0 + 16; jb += CB) {
;       u32x2 an[CB][RB + 2], ur[CB][RB];
; #pragma unroll
;       for (int q = 0; q < CB; ++q) { const int col = jb + q + 1; const int cl = col > 63 ? 63 : col;
; #pragma unroll
;         for (int di = 0; di < RB + 2; ++di) an[q][di] = *(const u32x2*)(rowp[di] + (size_t)cl * DFF);
; #pragma unroll
;         for (int rr = 0; rr < RB; ++rr) ur[q][rr] = *(const u32x2*)(U + (size_t)((r0 + rr) * 64 + jb + q) * DFF + c0); }
;       __builtin_amdgcn_sched_barrier(0);
; #pragma unroll
;       for (int q = 0; q < CB; ++q) {
;         const int col = jb + q + 1;
; #pragma unroll
;         for (int di = 0; di < RB + 2; ++di) { const bool ok = rv[di] && (col < 64); unpack4(an[q][di], win[2][di]);
; #pragma unroll
;           for (int k = 0; k < 4; ++k) win[2][di][k] = ok ? win[2][di][k] : 0.f; }
; #pragma unroll
;         for (int rr = 0; rr < RB; ++rr) {
;           float uv[4]; unpack4(ur[q][rr], uv);
;           float o[4];
; #pragma unroll
;           for (int k = 0; k < 4; ++k) {
;             float a = bsv[k];
; #pragma unroll
;             for (int di = 0; di < 3; ++di)
; #pragma unroll
;               for (int dj = 0; dj < 3; ++dj) a += win[dj][rr + di][k] * w[di * 3 + dj][k];
;             o[k] = gelu_as(a) * uv[k];
;           }
;           u32x2 ow; ow.x = cvt_pk_bf16(o[0], o[1]); ow.y = cvt_pk_bf16(o[2], o[3]);
;           *(u32x2*)(G + (size_t)((r0 + rr) * 64 + jb + q) * DFF + c0) = ow;
;         }
; #pragma unroll
;         for (int di = 0; di < RB + 2; ++di)
; #pragma unroll
;           for (int k = 0; k < 4; ++k) { win[0][di][k] = win[1][di][k]; win[1][di][k] = win[2][di][k]; }
;       }
	v_lshlrev_b32_e32 v72, 16, v88
	v_and_b32_e32 v73, 0xffff0000, v88
	v_lshlrev_b32_e32 v74, 16, v89
	v_and_b32_e32 v75, 0xffff0000, v89
	v_lshlrev_b32_e32 v76, 16, v90
	v_and_b32_e32 v77, 0xffff0000, v90
	v_lshlrev_b32_e32 v78, 16, v91
	v_and_b32_e32 v79, 0xffff0000, v91
	v_lshlrev_b32_e32 v80, 16, v92
	v_and_b32_e32 v81, 0xffff0000, v92
	v_lshlrev_b32_e32 v82, 16, v93
	v_and_b32_e32 v83, 0xffff0000, v93
	v_lshlrev_b32_e32 v84, 16, v94
	v_and_b32_e32 v85, 0xffff0000, v94
	v_lshlrev_b32_e32 v86, 16, v95
	v_and_b32_e32 v87, 0xffff0000, v95
	v_pk_mul_f32 v[72:73], v[72:73], v[200:201]
	v_pk_mul_f32 v[74:75], v[74:75], v[200:201]
	v_pk_mul_f32 v[84:85], v[84:85], v[202:203]
	v_pk_mul_f32 v[86:87], v[86:87], v[202:203]
	v_lshlrev_b32_e32 v124, 16, v112
	v_and_b32_e32 v125, 0xffff0000, v112
	v_lshlrev_b32_e32 v126, 16, v113
	v_and_b32_e32 v127, 0xffff0000, v113
	v_lshlrev_b32_e32 v128, 16, v114
	v_and_b32_e32 v129, 0xffff0000, v114
	v_lshlrev_b32_e32 v130, 16, v115
	v_and_b32_e32 v131, 0xffff0000, v115
	v_pk_fma_f32 v[148:149], v[40:41], v[0:1], v[36:37]
	v_pk_fma_f32 v[150:151], v[42:43], v[2:3], v[38:39]
	v_pk_fma_f32 v[152:153], v[44:45], v[0:1], v[36:37]
	v_pk_fma_f32 v[154:155], v[46:47], v[2:3], v[38:39]
	v_pk_fma_f32 v[148:149], v[56:57], v[4:5], v[148:149]
	v_pk_fma_f32 v[150:151], v[58:59], v[6:7], v[150:151]
	v_pk_fma_f32 v[152:153], v[60:61], v[4:5], v[152:153]
	v_pk_fma_f32 v[154:155], v[62:63], v[6:7], v[154:155]
	v_pk_fma_f32 v[148:149], v[72:73], v[8:9], v[148:149]
	v_pk_fma_f32 v[150:151], v[74:75], v[10:11], v[150:151]
	v_pk_fma_f32 v[152:153], v[76:77], v[8:9], v[152:153]
	v_pk_fma_f32 v[154:155], v[78:79], v[10:11], v[154:155]
	v_pk_fma_f32 v[148:149], v[44:45], v[12:13], v[148:149]
	v_pk_fma_f32 v[150:151], v[46:47], v[14:15], v[150:151]
	v_pk_fma_f32 v[152:153], v[48:49], v[12:13], v[152:153]
	v_pk_fma_f32 v[154:155], v[50:51], v[14:15], v[154:155]
	v_pk_fma_f32 v[148:149], v[60:61], v[16:17], v[148:149]
	v_pk_fma_f32 v[150:151], v[62:63], v[18:19], v[150:151]
	v_pk_fma_f32 v[152:153], v[64:65], v[16:17], v[152:153]
	v_pk_fma_f32 v[154:155], v[66:67], v[18:19], v[154:155]
	v_pk_fma_f32 v[148:149], v[76:77], v[20:21], v[148:149]
	v_pk_fma_f32 v[150:151], v[78:79], v[22:23], v[150:151]
	v_pk_fma_f32 v[152:153], v[80:81], v[20:21], v[152:153]
	v_pk_fma_f32 v[154:155], v[82:83], v[22:23], v[154:155]
	v_pk_fma_f32 v[148:149], v[48:49], v[24:25], v[148:149]
	v_pk_fma_f32 v[150:151], v[50:51], v[26:27], v[150:151]
	v_pk_fma_f32 v[152:153], v[52:53], v[24:25], v[152:153]
	v_pk_fma_f32 v[154:155], v[54:55], v[26:27], v[154:155]
	v_pk_fma_f32 v[148:149], v[64:65], v[28:29], v[148:149]
	v_pk_fma_f32 v[150:151], v[66:67], v[30:31], v[150:151]
	v_pk_fma_f32 v[152:153], v[68:69], v[28:29], v[152:153]
	v_pk_fma_f32 v[154:155], v[70:71], v[30:31], v[154:155]
	v_pk_fma_f32 v[148:149], v[80:81], v[32:33], v[148:149]
	v_pk_fma_f32 v[150:151], v[82:83], v[34:35], v[150:151]
	v_pk_fma_f32 v[152:153], v[84:85], v[32:33], v[152:153]
	v_pk_fma_f32 v[154:155], v[86:87], v[34:35], v[154:155]
	v_and_b32_e32 v156, 0x7fffffff, v148
	v_and_b32_e32 v157, 0x7fffffff, v149
	v_and_b32_e32 v158, 0x7fffffff, v150
	v_and_b32_e32 v159, 0x7fffffff, v151
	v_and_b32_e32 v160, 0x7fffffff, v152
	v_and_b32_e32 v161, 0x7fffffff, v153
	v_and_b32_e32 v162, 0x7fffffff, v154
	v_and_b32_e32 v163, 0x7fffffff, v155
	v_pk_fma_f32 v[164:165], v[156:157], v[184:185], v[186:187]
	v_pk_fma_f32 v[166:167], v[158:159], v[184:185], v[186:187]
	v_pk_fma_f32 v[168:169], v[160:161], v[184:185], v[186:187]
	v_pk_fma_f32 v[170:171], v[162:163], v[184:185], v[186:187]
	v_rcp_f32_e32 v164, v164
	v_rcp_f32_e32 v165, v165
	v_rcp_f32_e32 v166, v166
	v_rcp_f32_e32 v167, v167
	v_rcp_f32_e32 v168, v168
	v_rcp_f32_e32 v169, v169
	v_rcp_f32_e32 v170, v170
	v_rcp_f32_e32 v171, v171
	v_pk_fma_f32 v[172:173], v[164:165], v[188:189], v[190:191]
	v_pk_fma_f32 v[174:175], v[166:167], v[188:189], v[190:191]
	v_pk_fma_f32 v[176:177], v[168:169], v[188:189], v[190:191]
	v_pk_fma_f32 v[178:179], v[170:171], v[188:189], v[190:191]
	v_pk_fma_f32 v[172:173], v[172:173], v[164:165], v[192:193]
	v_pk_fma_f32 v[174:175], v[174:175], v[166:167], v[192:193]
	v_pk_fma_f32 v[176:177], v[176:177], v[168:169], v[192:193]
	v_pk_fma_f32 v[178:179], v[178:179], v[170:171], v[192:193]
	v_pk_fma_f32 v[172:173], v[172:173], v[164:165], v[194:195]
	v_pk_fma_f32 v[174:175], v[174:175], v[166:167], v[194:195]
	v_pk_fma_f32 v[176:177], v[176:177], v[168:169], v[194:195]
	v_pk_fma_f32 v[178:179], v[178:179], v[170:171], v[194:195]
	v_pk_fma_f32 v[172:173], v[172:173], v[164:165], v[196:197]
	v_pk_fma_f32 v[174:175], v[174:175], v[166:167], v[196:197]
	v_pk_fma_f32 v[176:177], v[176:177], v[168:169], v[196:197]
	v_pk_fma_f32 v[178:179], v[178:179], v[170:171], v[196:197]
	v_pk_mul_f32 v[172:173], v[172:173], v[164:165]
	v_pk_mul_f32 v[174:175], v[174:175], v[166:167]
	v_pk_mul_f32 v[176:177], v[176:177], v[168:169]
	v_pk_mul_f32 v[178:179], v[178:179], v[170:171]
	v_pk_mul_f32 v[164:165], v[148:149], v[148:149]
	v_pk_mul_f32 v[166:167], v[150:151], v[150:151]
	v_pk_mul_f32 v[168:169], v[152:153], v[152:153]
	v_pk_mul_f32 v[170:171], v[154:155], v[154:155]
	v_pk_mul_f32 v[164:165], v[164:165], v[198:199]
	v_pk_mul_f32 v[166:167], v[166:167], v[198:199]
	v_pk_mul_f32 v[168:169], v[168:169], v[198:199]
	v_pk_mul_f32 v[170:171], v[170:171], v[198:199]
	v_exp_f32_e32 v164, v164
	v_exp_f32_e32 v165, v165
	v_exp_f32_e32 v166, v166
	v_exp_f32_e32 v167, v167
	v_exp_f32_e32 v168, v168
	v_exp_f32_e32 v169, v169
	v_exp_f32_e32 v170, v170
	v_exp_f32_e32 v171, v171
	v_pk_mul_f32 v[172:173], v[172:173], v[164:165]
	v_pk_mul_f32 v[174:175], v[174:175], v[166:167]
; __device__ __forceinline__ unsigned cvt_pk_bf16(float lo, float hi) { unsigned r; asm volatile("v_cvt_pk_bf16_f32 %0, %1, %2" : "=v"(r) : "v"(lo), "v"(hi)); return r; }
; __device__ __forceinline__ float gelu_as(float v) {
;   const float av = fabsf(v); const float t = __builtin_amdgcn_rcpf(av * 0.2316418882f + 1.0f);
;   float q = t * 0.5307027145f + (-0.7265760135f); q = q * t + 0.7107068705f; q = q * t + (-0.142248368f); q = q * t + 0.127414796f; q = q * t;
;   const float e = __builtin_amdgcn_exp2f((v * v) * (-0.72134752044f));
;   const float m = v * (q * e);
;   return v < 0.f ? m : v - m;
; }
; __device__ __forceinline__ void phase_conv(KP p, int l, int tid) {
;     ...
;     for (int jb = j0; jb < j0 + 16; jb += CB) {
;       u32x2 an[CB][RB + 2], ur[CB][RB];
; #pragma unroll
;       for (int q = 0; q < CB; ++q) { const int col = jb + q + 1; const int cl = col > 63 ? 63 : col;
; #pragma unroll
;         for (int di = 0; di < RB + 2; ++di) an[q][di] = *(const u32x2*)(rowp[di] + (size_t)cl * DFF);
; #pragma unroll
;         for (int rr = 0; rr < RB; ++rr) ur[q][rr] = *(const u32x2*)(U + (size_t)((r0 + rr) * 64 + jb + q) * DFF + c0); }
;       __builtin_amdgcn_sched_barrier(0);
; #pragma unroll
;       for (int q = 0; q < CB; ++q) {
;         const int col = jb + q + 1;
; #pragma unroll
;         for (int di = 0; di < RB + 2; ++di) { const bool ok = rv[di] && (col < 64); unpack4(an[q][di], win[2][di]);
; #pragma unroll
;           for (int k = 0; k < 4; ++k) win[2][di][k] = ok ? win[2][di][k] : 0.f; }
; #pragma unroll
;         for (int rr = 0; rr < RB; ++rr) {
;           float uv[4]; unpack4(ur[q][rr], uv);
;           float o[4];
; #pragma unroll
;           for (int k = 0; k < 4; ++k) {
;             float a = bsv[k];
; #pragma unroll
;             for (int di = 0; di < 3; ++di)
; #pragma unroll
;               for (int dj = 0; dj < 3; ++dj) a += win[dj][rr + di][k] * w[di * 3 + dj][k];
;             o[k] = gelu_as(a) * uv[k];
;           }
;           u32x2 ow; ow.x = cvt_pk_bf16(o[0], o[1]); ow.y = cvt_pk_bf16(o[2], o[3]);
;           *(u32x2*)(G + (size_t)((r0 + rr) * 64 + jb + q) * DFF + c0) = ow;
;         }
; #pragma unroll
;         for (int di = 0; di < RB + 2; ++di)
; #pragma unroll
;           for (int k = 0; k < 4; ++k) { win[0][di][k] = win[1][di][k]; win[1][di][k] = win[2][di][k]; }
;       }
	v_pk_mul_f32 v[176:177], v[176:177], v[168:169]
	v_pk_mul_f32 v[178:179], v[178:179], v[170:171]
	v_pk_mul_f32 v[172:173], v[156:157], v[172:173]
	v_pk_mul_f32 v[174:175], v[158:159], v[174:175]
	v_pk_mul_f32 v[176:177], v[160:161], v[176:177]
	v_pk_mul_f32 v[178:179], v[162:163], v[178:179]
	v_max_f32_e32 v164, 0, v148
	v_max_f32_e32 v165, 0, v149
	v_max_f32_e32 v166, 0, v150
	v_max_f32_e32 v167, 0, v151
	v_max_f32_e32 v168, 0, v152
	v_max_f32_e32 v169, 0, v153
	v_max_f32_e32 v170, 0, v154
	v_max_f32_e32 v171, 0, v155
	v_pk_add_f32 v[164:165], v[164:165], v[172:173] neg_lo:[0,1] neg_hi:[0,1]
	v_pk_add_f32 v[166:167], v[166:167], v[174:175] neg_lo:[0,1] neg_hi:[0,1]
	v_pk_add_f32 v[168:169], v[168:169], v[176:177] neg_lo:[0,1] neg_hi:[0,1]
	v_pk_add_f32 v[170:171], v[170:171], v[178:179] neg_lo:[0,1] neg_hi:[0,1]
	v_pk_mul_f32 v[164:165], v[164:165], v[124:125]
	v_pk_mul_f32 v[166:167], v[166:167], v[126:127]
	v_pk_mul_f32 v[168:169], v[168:169], v[128:129]
	v_pk_mul_f32 v[170:171], v[170:171], v[130:131]
	v_cvt_pk_bf16_f32 v156, v164, v165
	v_cvt_pk_bf16_f32 v157, v166, v167
	v_cvt_pk_bf16_f32 v158, v168, v169
	v_cvt_pk_bf16_f32 v159, v170, v171
	global_store_dwordx2 v216, v[156:157], s[10:11]
	global_store_dwordx2 v217, v[158:159], s[10:11]
	v_add_u32_e32 v210, 0x2c00, v210
	v_add_u32_e32 v211, 0x2c00, v210
	v_min_u32_e32 v211, 0xad400, v211
	v_add_u32_e32 v212, v206, v211
	global_load_dwordx2 v[88:89], v212, s[6:7]
	v_add_u32_e32 v213, v207, v211
	global_load_dwordx2 v[90:91], v213, s[6:7]
	v_add_u32_e32 v214, v208, v211
	global_load_dwordx2 v[92:93], v214, s[6:7]
	v_add_u32_e32 v215, v209, v211
	global_load_dwordx2 v[94:95], v215, s[6:7]
	v_add_u32_e32 v216, v207, v210
	global_load_dwordx2 v[112:113], v216, s[8:9]
	v_add_u32_e32 v217, v208, v210
	global_load_dwordx2 v[114:115], v217, s[8:9]
	s_waitcnt vmcnt(16)
	v_lshlrev_b32_e32 v40, 16, v96
	v_and_b32_e32 v41, 0xffff0000, v96
	v_lshlrev_b32_e32 v42, 16, v97
	v_and_b32_e32 v43, 0xffff0000, v97
	v_lshlrev_b32_e32 v44, 16, v98
	v_and_b32_e32 v45, 0xffff0000, v98
	v_lshlrev_b32_e32 v46, 16, v99
	v_and_b32_e32 v47, 0xffff0000, v99
	v_lshlrev_b32_e32 v48, 16, v100
	v_and_b32_e32 v49, 0xffff0000, v100
	v_lshlrev_b32_e32 v50, 16, v101
	v_and_b32_e32 v51, 0xffff0000, v101
	v_lshlrev_b32_e32 v52, 16, v102
	v_and_b32_e32 v53, 0xffff0000, v102
	v_lshlrev_b32_e32 v54, 16, v103
	v_and_b32_e32 v55, 0xffff0000, v103
	v_pk_mul_f32 v[40:41], v[40:41], v[200:201]
	v_pk_mul_f32 v[42:43], v[42:43], v[200:201]
	v_pk_mul_f32 v[52:53], v[52:53], v[202:203]
	v_pk_mul_f32 v[54:55], v[54:55], v[202:203]
	v_lshlrev_b32_e32 v124, 16, v116
	v_and_b32_e32 v125, 0xffff0000, v116
	v_lshlrev_b32_e32 v126, 16, v117
	v_and_b32_e32 v127, 0xffff0000, v117
	v_lshlrev_b32_e32 v128, 16, v118
	v_and_b32_e32 v129, 0xffff0000, v118
	v_lshlrev_b32_e32 v130, 16, v119
	v_and_b32_e32 v131, 0xffff0000, v119
	v_pk_fma_f32 v[148:149], v[56:57], v[0:1], v[36:37]
	v_pk_fma_f32 v[150:151], v[58:59], v[2:3], v[38:39]
	v_pk_fma_f32 v[152:153], v[60:61], v[0:1], v[36:37]
	v_pk_fma_f32 v[154:155], v[62:63], v[2:3], v[38:39]
	v_pk_fma_f32 v[148:149], v[72:73], v[4:5], v[148:149]
	v_pk_fma_f32 v[150:151], v[74:75], v[6:7], v[150:151]
	v_pk_fma_f32 v[152:153], v[76:77], v[4:5], v[152:153]
	v_pk_fma_f32 v[154:155], v[78:79], v[6:7], v[154:155]
	v_pk_fma_f32 v[148:149], v[40:41], v[8:9], v[148:149]
	v_pk_fma_f32 v[150:151], v[42:43], v[10:11], v[150:151]
	v_pk_fma_f32 v[152:153], v[44:45], v[8:9], v[152:153]
	v_pk_fma_f32 v[154:155], v[46:47], v[10:11], v[154:155]
	v_pk_fma_f32 v[148:149], v[60:61], v[12:13], v[148:149]
	v_pk_fma_f32 v[150:151], v[62:63], v[14:15], v[150:151]
	v_pk_fma_f32 v[152:153], v[64:65], v[12:13], v[152:153]
	v_pk_fma_f32 v[154:155], v[66:67], v[14:15], v[154:155]
	v_pk_fma_f32 v[148:149], v[76:77], v[16:17], v[148:149]
	v_pk_fma_f32 v[150:151], v[78:79], v[18:19], v[150:151]
	v_pk_fma_f32 v[152:153], v[80:81], v[16:17], v[152:153]
	v_pk_fma_f32 v[154:155], v[82:83], v[18:19], v[154:155]
	v_pk_fma_f32 v[148:149], v[44:45], v[20:21], v[148:149]
	v_pk_fma_f32 v[150:151], v[46:47], v[22:23], v[150:151]
	v_pk_fma_f32 v[152:153], v[48:49], v[20:21], v[152:153]
	v_pk_fma_f32 v[154:155], v[50:51], v[22:23], v[154:155]
	v_pk_fma_f32 v[148:149], v[64:65], v[24:25], v[148:149]
	v_pk_fma_f32 v[150:151], v[66:67], v[26:27], v[150:151]
	v_pk_fma_f32 v[152:153], v[68:69], v[24:25], v[152:153]
	v_pk_fma_f32 v[154:155], v[70:71], v[26:27], v[154:155]
	v_pk_fma_f32 v[148:149], v[80:81], v[28:29], v[148:149]
	v_pk_fma_f32 v[150:151], v[82:83], v[30:31], v[150:151]
	v_pk_fma_f32 v[152:153], v[84:85], v[28:29], v[152:153]
	v_pk_fma_f32 v[154:155], v[86:87], v[30:31], v[154:155]
	v_pk_fma_f32 v[148:149], v[48:49], v[32:33], v[148:149]
	v_pk_fma_f32 v[150:151], v[50:51], v[34:35], v[150:151]
	v_pk_fma_f32 v[152:153], v[52:53], v[32:33], v[152:153]
	v_pk_fma_f32 v[154:155], v[54:55], v[34:35], v[154:155]
	v_and_b32_e32 v156, 0x7fffffff, v148
	v_and_b32_e32 v157, 0x7fffffff, v149
	v_and_b32_e32 v158, 0x7fffffff, v150
	v_and_b32_e32 v159, 0x7fffffff, v151
	v_and_b32_e32 v160, 0x7fffffff, v152
	v_and_b32_e32 v161, 0x7fffffff, v153
	v_and_b32_e32 v162, 0x7fffffff, v154
	v_and_b32_e32 v163, 0x7fffffff, v155
	v_pk_fma_f32 v[164:165], v[156:157], v[184:185], v[186:187]
	v_pk_fma_f32 v[166:167], v[158:159], v[184:185], v[186:187]
	v_pk_fma_f32 v[168:169], v[160:161], v[184:185], v[186:187]
	v_pk_fma_f32 v[170:171], v[162:163], v[184:185], v[186:187]
	v_rcp_f32_e32 v164, v164
	v_rcp_f32_e32 v165, v165
	v_rcp_f32_e32 v166, v166
	v_rcp_f32_e32 v167, v167
	v_rcp_f32_e32 v168, v168
	v_rcp_f32_e32 v169, v169
	v_rcp_f32_e32 v170, v170
	v_rcp_f32_e32 v171, v171
; __device__ __forceinline__ unsigned cvt_pk_bf16(float lo, float hi) { unsigned r; asm volatile("v_cvt_pk_bf16_f32 %0, %1, %2" : "=v"(r) : "v"(lo), "v"(hi)); return r; }
; __device__ __forceinline__ float gelu_as(float v) {
;   const float av = fabsf(v); const float t = __builtin_amdgcn_rcpf(av * 0.2316418882f + 1.0f);
;   float q = t * 0.5307027145f + (-0.7265760135f); q = q * t + 0.7107068705f; q = q * t + (-0.142248368f); q = q * t + 0.127414796f; q = q * t;
;   const float e = __builtin_amdgcn_exp2f((v * v) * (-0.72134752044f));
;   const float m = v * (q * e);
;   return v < 0.f ? m : v - m;
; }
; __device__ __forceinline__ void phase_conv(KP p, int l, int tid) {
;     ...
;     for (int jb = j0; jb < j0 + 16; jb += CB) {
;       u32x2 an[CB][RB + 2], ur[CB][RB];
; #pragma unroll
;       for (int q = 0; q < CB; ++q) { const int col = jb + q + 1; const int cl = col > 63 ? 63 : col;
; #pragma unroll
;         for (int di = 0; di < RB + 2; ++di) an[q][di] = *(const u32x2*)(rowp[di] + (size_t)cl * DFF);
; #pragma unroll
;         for (int rr = 0; rr < RB; ++rr) ur[q][rr] = *(const u32x2*)(U + (size_t)((r0 + rr) * 64 + jb + q) * DFF + c0); }
;       __builtin_amdgcn_sched_barrier(0);
; #pragma unroll
;       for (int q = 0; q < CB; ++q) {
;         const int col = jb + q + 1;
; #pragma unroll
;         for (int di = 0; di < RB + 2; ++di) { const bool ok = rv[di] && (col < 64); unpack4(an[q][di], win[2][di]);
; #pragma unroll
;           for (int k = 0; k < 4; ++k) win[2][di][k] = ok ? win[2][di][k] : 0.f; }
; #pragma unroll
;         for (int rr = 0; rr < RB; ++rr) {
;           float uv[4]; unpack4(ur[q][rr], uv);
;           float o[4];
; #pragma unroll
;           for (int k = 0; k < 4; ++k) {
;             float a = bsv[k];
; #pragma unroll
;             for (int di = 0; di < 3; ++di)
; #pragma unroll
;               for (int dj = 0; dj < 3; ++dj) a += win[dj][rr + di][k] * w[di * 3 + dj][k];
;             o[k] = gelu_as(a) * uv[k];
;           }
;           u32x2 ow; ow.x = cvt_pk_bf16(o[0], o[1]); ow.y = cvt_pk_bf16(o[2], o[3]);
;           *(u32x2*)(G + (size_t)((r0 + rr) * 64 + jb + q) * DFF + c0) = ow;
;         }
; #pragma unroll
;         for (int di = 0; di < RB + 2; ++di)
; #pragma unroll
;           for (int k = 0; k < 4; ++k) { win[0][di][k] = win[1][di][k]; win[1][di][k] = win[2][di][k]; }
;       }
	v_pk_fma_f32 v[172:173], v[164:165], v[188:189], v[190:191]
	v_pk_fma_f32 v[174:175], v[166:167], v[188:189], v[190:191]
	v_pk_fma_f32 v[176:177], v[168:169], v[188:189], v[190:191]
	v_pk_fma_f32 v[178:179], v[170:171], v[188:189], v[190:191]
	v_pk_fma_f32 v[172:173], v[172:173], v[164:165], v[192:193]
	v_pk_fma_f32 v[174:175], v[174:175], v[166:167], v[192:193]
	v_pk_fma_f32 v[176:177], v[176:177], v[168:169], v[192:193]
	v_pk_fma_f32 v[178:179], v[178:179], v[170:171], v[192:193]
	v_pk_fma_f32 v[172:173], v[172:173], v[164:165], v[194:195]
	v_pk_fma_f32 v[174:175], v[174:175], v[166:167], v[194:195]
	v_pk_fma_f32 v[176:177], v[176:177], v[168:169], v[194:195]
	v_pk_fma_f32 v[178:179], v[178:179], v[170:171], v[194:195]
	v_pk_fma_f32 v[172:173], v[172:173], v[164:165], v[196:197]
	v_pk_fma_f32 v[174:175], v[174:175], v[166:167], v[196:197]
	v_pk_fma_f32 v[176:177], v[176:177], v[168:169], v[196:197]
	v_pk_fma_f32 v[178:179], v[178:179], v[170:171], v[196:197]
	v_pk_mul_f32 v[172:173], v[172:173], v[164:165]
	v_pk_mul_f32 v[174:175], v[174:175], v[166:167]
	v_pk_mul_f32 v[176:177], v[176:177], v[168:169]
	v_pk_mul_f32 v[178:179], v[178:179], v[170:171]
	v_pk_mul_f32 v[164:165], v[148:149], v[148:149]
	v_pk_mul_f32 v[166:167], v[150:151], v[150:151]
	v_pk_mul_f32 v[168:169], v[152:153], v[152:153]
	v_pk_mul_f32 v[170:171], v[154:155], v[154:155]
	v_pk_mul_f32 v[164:165], v[164:165], v[198:199]
	v_pk_mul_f32 v[166:167], v[166:167], v[198:199]
	v_pk_mul_f32 v[168:169], v[168:169], v[198:199]
	v_pk_mul_f32 v[170:171], v[170:171], v[198:199]
	v_exp_f32_e32 v164, v164
	v_exp_f32_e32 v165, v165
	v_exp_f32_e32 v166, v166
	v_exp_f32_e32 v167, v167
	v_exp_f32_e32 v168, v168
	v_exp_f32_e32 v169, v169
	v_exp_f32_e32 v170, v170
	v_exp_f32_e32 v171, v171
	v_pk_mul_f32 v[172:173], v[172:173], v[164:165]
	v_pk_mul_f32 v[174:175], v[174:175], v[166:167]
	v_pk_mul_f32 v[176:177], v[176:177], v[168:169]
	v_pk_mul_f32 v[178:179], v[178:179], v[170:171]
	v_pk_mul_f32 v[172:173], v[156:157], v[172:173]
	v_pk_mul_f32 v[174:175], v[158:159], v[174:175]
	v_pk_mul_f32 v[176:177], v[160:161], v[176:177]
	v_pk_mul_f32 v[178:179], v[162:163], v[178:179]
	v_max_f32_e32 v164, 0, v148
	v_max_f32_e32 v165, 0, v149
	v_max_f32_e32 v166, 0, v150
	v_max_f32_e32 v167, 0, v151
	v_max_f32_e32 v168, 0, v152
	v_max_f32_e32 v169, 0, v153
	v_max_f32_e32 v170, 0, v154
	v_max_f32_e32 v171, 0, v155
	v_pk_add_f32 v[164:165], v[164:165], v[172:173] neg_lo:[0,1] neg_hi:[0,1]
	v_pk_add_f32 v[166:167], v[166:167], v[174:175] neg_lo:[0,1] neg_hi:[0,1]
	v_pk_add_f32 v[168:169], v[168:169], v[176:177] neg_lo:[0,1] neg_hi:[0,1]
	v_pk_add_f32 v[170:171], v[170:171], v[178:179] neg_lo:[0,1] neg_hi:[0,1]
	v_pk_mul_f32 v[164:165], v[164:165], v[124:125]
	v_pk_mul_f32 v[166:167], v[166:167], v[126:127]
	v_pk_mul_f32 v[168:169], v[168:169], v[128:129]
	v_pk_mul_f32 v[170:171], v[170:171], v[130:131]
	v_cvt_pk_bf16_f32 v156, v164, v165
	v_cvt_pk_bf16_f32 v157, v166, v167
	v_cvt_pk_bf16_f32 v158, v168, v169
	v_cvt_pk_bf16_f32 v159, v170, v171
	global_store_dwordx2 v218, v[156:157], s[10:11]
	global_store_dwordx2 v219, v[158:159], s[10:11]
	s_waitcnt vmcnt(10)
	v_lshlrev_b32_e32 v56, 16, v104
	v_and_b32_e32 v57, 0xffff0000, v104
	v_lshlrev_b32_e32 v58, 16, v105
	v_and_b32_e32 v59, 0xffff0000, v105
	v_lshlrev_b32_e32 v60, 16, v106
	v_and_b32_e32 v61, 0xffff0000, v106
	v_lshlrev_b32_e32 v62, 16, v107
	v_and_b32_e32 v63, 0xffff0000, v107
	v_lshlrev_b32_e32 v64, 16, v108
	v_and_b32_e32 v65, 0xffff0000, v108
	v_lshlrev_b32_e32 v66, 16, v109
	v_and_b32_e32 v67, 0xffff0000, v109
	v_lshlrev_b32_e32 v68, 16, v110
	v_and_b32_e32 v69, 0xffff0000, v110
	v_lshlrev_b32_e32 v70, 16, v111
	v_and_b32_e32 v71, 0xffff0000, v111
	v_pk_mul_f32 v[56:57], v[56:57], v[200:201]
	v_pk_mul_f32 v[58:59], v[58:59], v[200:201]
	v_pk_mul_f32 v[68:69], v[68:69], v[202:203]
	v_pk_mul_f32 v[70:71], v[70:71], v[202:203]
	v_lshlrev_b32_e32 v124, 16, v120
	v_and_b32_e32 v125, 0xffff0000, v120
	v_lshlrev_b32_e32 v126, 16, v121
	v_and_b32_e32 v127, 0xffff0000, v121
	v_lshlrev_b32_e32 v128, 16, v122
	v_and_b32_e32 v129, 0xffff0000, v122
	v_lshlrev_b32_e32 v130, 16, v123
	v_and_b32_e32 v131, 0xffff0000, v123
	v_pk_fma_f32 v[148:149], v[72:73], v[0:1], v[36:37]
	v_pk_fma_f32 v[150:151], v[74:75], v[2:3], v[38:39]
	v_pk_fma_f32 v[152:153], v[76:77], v[0:1], v[36:37]
	v_pk_fma_f32 v[154:155], v[78:79], v[2:3], v[38:39]
	v_pk_fma_f32 v[148:149], v[40:41], v[4:5], v[148:149]
	v_pk_fma_f32 v[150:151], v[42:43], v[6:7], v[150:151]
	v_pk_fma_f32 v[152:153], v[44:45], v[4:5], v[152:153]
	v_pk_fma_f32 v[154:155], v[46:47], v[6:7], v[154:155]
	v_pk_fma_f32 v[148:149], v[56:57], v[8:9], v[148:149]
	v_pk_fma_f32 v[150:151], v[58:59], v[10:11], v[150:151]
	v_pk_fma_f32 v[152:153], v[60:61], v[8:9], v[152:153]
	v_pk_fma_f32 v[154:155], v[62:63], v[10:11], v[154:155]
	v_pk_fma_f32 v[148:149], v[76:77], v[12:13], v[148:149]
	v_pk_fma_f32 v[150:151], v[78:79], v[14:15], v[150:151]
	v_pk_fma_f32 v[152:153], v[80:81], v[12:13], v[152:153]
	v_pk_fma_f32 v[154:155], v[82:83], v[14:15], v[154:155]
	v_pk_fma_f32 v[148:149], v[44:45], v[16:17], v[148:149]
	v_pk_fma_f32 v[150:151], v[46:47], v[18:19], v[150:151]
	v_pk_fma_f32 v[152:153], v[48:49], v[16:17], v[152:153]
	v_pk_fma_f32 v[154:155], v[50:51], v[18:19], v[154:155]
	v_pk_fma_f32 v[148:149], v[60:61], v[20:21], v[148:149]
	v_pk_fma_f32 v[150:151], v[62:63], v[22:23], v[150:151]
	v_pk_fma_f32 v[152:153], v[64:65], v[20:21], v[152:153]
	v_pk_fma_f32 v[154:155], v[66:67], v[22:23], v[154:155]
	v_pk_fma_f32 v[148:149], v[80:81], v[24:25], v[148:149]
	v_pk_fma_f32 v[150:151], v[82:83], v[26:27], v[150:151]
; __device__ __forceinline__ unsigned cvt_pk_bf16(float lo, float hi) { unsigned r; asm volatile("v_cvt_pk_bf16_f32 %0, %1, %2" : "=v"(r) : "v"(lo), "v"(hi)); return r; }
; __device__ __forceinline__ float gelu_as(float v) {
;   const float av = fabsf(v); const float t = __builtin_amdgcn_rcpf(av * 0.2316418882f + 1.0f);
;   float q = t * 0.5307027145f + (-0.7265760135f); q = q * t + 0.7107068705f; q = q * t + (-0.142248368f); q = q * t + 0.127414796f; q = q * t;
;   const float e = __builtin_amdgcn_exp2f((v * v) * (-0.72134752044f));
;   const float m = v * (q * e);
;   return v < 0.f ? m : v - m;
; }
; __device__ __forceinline__ void phase_conv(KP p, int l, int tid) {
;     ...
;     for (int jb = j0; jb < j0 + 16; jb += CB) {
;       u32x2 an[CB][RB + 2], ur[CB][RB];
; #pragma unroll
;       for (int q = 0; q < CB; ++q) { const int col = jb + q + 1; const int cl = col > 63 ? 63 : col;
; #pragma unroll
;         for (int di = 0; di < RB + 2; ++di) an[q][di] = *(const u32x2*)(rowp[di] + (size_t)cl * DFF);
; #pragma unroll
;         for (int rr = 0; rr < RB; ++rr) ur[q][rr] = *(const u32x2*)(U + (size_t)((r0 + rr) * 64 + jb + q) * DFF + c0); }
;       __builtin_amdgcn_sched_barrier(0);
; #pragma unroll
;       for (int q = 0; q < CB; ++q) {
;         const int col = jb + q + 1;
; #pragma unroll
;         for (int di = 0; di < RB + 2; ++di) { const bool ok = rv[di] && (col < 64); unpack4(an[q][di], win[2][di]);
; #pragma unroll
;           for (int k = 0; k < 4; ++k) win[2][di][k] = ok ? win[2][di][k] : 0.f; }
; #pragma unroll
;         for (int rr = 0; rr < RB; ++rr) {
;           float uv[4]; unpack4(ur[q][rr], uv);
;           float o[4];
; #pragma unroll
;           for (int k = 0; k < 4; ++k) {
;             float a = bsv[k];
; #pragma unroll
;             for (int di = 0; di < 3; ++di)
; #pragma unroll
;               for (int dj = 0; dj < 3; ++dj) a += win[dj][rr + di][k] * w[di * 3 + dj][k];
;             o[k] = gelu_as(a) * uv[k];
;           }
;           u32x2 ow; ow.x = cvt_pk_bf16(o[0], o[1]); ow.y = cvt_pk_bf16(o[2], o[3]);
;           *(u32x2*)(G + (size_t)((r0 + rr) * 64 + jb + q) * DFF + c0) = ow;
;         }
; #pragma unroll
;         for (int di = 0; di < RB + 2; ++di)
; #pragma unroll
;           for (int k = 0; k < 4; ++k) { win[0][di][k] = win[1][di][k]; win[1][di][k] = win[2][di][k]; }
;       }
	v_pk_fma_f32 v[152:153], v[84:85], v[24:25], v[152:153]
	v_pk_fma_f32 v[154:155], v[86:87], v[26:27], v[154:155]
	v_pk_fma_f32 v[148:149], v[48:49], v[28:29], v[148:149]
	v_pk_fma_f32 v[150:151], v[50:51], v[30:31], v[150:151]
	v_pk_fma_f32 v[152:153], v[52:53], v[28:29], v[152:153]
	v_pk_fma_f32 v[154:155], v[54:55], v[30:31], v[154:155]
	v_pk_fma_f32 v[148:149], v[64:65], v[32:33], v[148:149]
	v_pk_fma_f32 v[150:151], v[66:67], v[34:35], v[150:151]
	v_pk_fma_f32 v[152:153], v[68:69], v[32:33], v[152:153]
	v_pk_fma_f32 v[154:155], v[70:71], v[34:35], v[154:155]
	v_and_b32_e32 v156, 0x7fffffff, v148
	v_and_b32_e32 v157, 0x7fffffff, v149
	v_and_b32_e32 v158, 0x7fffffff, v150
	v_and_b32_e32 v159, 0x7fffffff, v151
	v_and_b32_e32 v160, 0x7fffffff, v152
	v_and_b32_e32 v161, 0x7fffffff, v153
	v_and_b32_e32 v162, 0x7fffffff, v154
	v_and_b32_e32 v163, 0x7fffffff, v155
	v_pk_fma_f32 v[164:165], v[156:157], v[184:185], v[186:187]
	v_pk_fma_f32 v[166:167], v[158:159], v[184:185], v[186:187]
	v_pk_fma_f32 v[168:169], v[160:161], v[184:185], v[186:187]
	v_pk_fma_f32 v[170:171], v[162:163], v[184:185], v[186:187]
	v_rcp_f32_e32 v164, v164
	v_rcp_f32_e32 v165, v165
	v_rcp_f32_e32 v166, v166
	v_rcp_f32_e32 v167, v167
	v_rcp_f32_e32 v168, v168
	v_rcp_f32_e32 v169, v169
	v_rcp_f32_e32 v170, v170
	v_rcp_f32_e32 v171, v171
	v_pk_fma_f32 v[172:173], v[164:165], v[188:189], v[190:191]
	v_pk_fma_f32 v[174:175], v[166:167], v[188:189], v[190:191]
	v_pk_fma_f32 v[176:177], v[168:169], v[188:189], v[190:191]
	v_pk_fma_f32 v[178:179], v[170:171], v[188:189], v[190:191]
	v_pk_fma_f32 v[172:173], v[172:173], v[164:165], v[192:193]
	v_pk_fma_f32 v[174:175], v[174:175], v[166:167], v[192:193]
	v_pk_fma_f32 v[176:177], v[176:177], v[168:169], v[192:193]
	v_pk_fma_f32 v[178:179], v[178:179], v[170:171], v[192:193]
	v_pk_fma_f32 v[172:173], v[172:173], v[164:165], v[194:195]
	v_pk_fma_f32 v[174:175], v[174:175], v[166:167], v[194:195]
	v_pk_fma_f32 v[176:177], v[176:177], v[168:169], v[194:195]
	v_pk_fma_f32 v[178:179], v[178:179], v[170:171], v[194:195]
	v_pk_fma_f32 v[172:173], v[172:173], v[164:165], v[196:197]
	v_pk_fma_f32 v[174:175], v[174:175], v[166:167], v[196:197]
	v_pk_fma_f32 v[176:177], v[176:177], v[168:169], v[196:197]
	v_pk_fma_f32 v[178:179], v[178:179], v[170:171], v[196:197]
	v_pk_mul_f32 v[172:173], v[172:173], v[164:165]
	v_pk_mul_f32 v[174:175], v[174:175], v[166:167]
	v_pk_mul_f32 v[176:177], v[176:177], v[168:169]
	v_pk_mul_f32 v[178:179], v[178:179], v[170:171]
	v_pk_mul_f32 v[164:165], v[148:149], v[148:149]
	v_pk_mul_f32 v[166:167], v[150:151], v[150:151]
	v_pk_mul_f32 v[168:169], v[152:153], v[152:153]
	v_pk_mul_f32 v[170:171], v[154:155], v[154:155]
	v_pk_mul_f32 v[164:165], v[164:165], v[198:199]
	v_pk_mul_f32 v[166:167], v[166:167], v[198:199]
	v_pk_mul_f32 v[168:169], v[168:169], v[198:199]
	v_pk_mul_f32 v[170:171], v[170:171], v[198:199]
	v_exp_f32_e32 v164, v164
	v_exp_f32_e32 v165, v165
	v_exp_f32_e32 v166, v166
	v_exp_f32_e32 v167, v167
	v_exp_f32_e32 v168, v168
	v_exp_f32_e32 v169, v169
	v_exp_f32_e32 v170, v170
	v_exp_f32_e32 v171, v171
	v_pk_mul_f32 v[172:173], v[172:173], v[164:165]
	v_pk_mul_f32 v[174:175], v[174:175], v[166:167]
	v_pk_mul_f32 v[176:177], v[176:177], v[168:169]
	v_pk_mul_f32 v[178:179], v[178:179], v[170:171]
	v_pk_mul_f32 v[172:173], v[156:157], v[172:173]
	v_pk_mul_f32 v[174:175], v[158:159], v[174:175]
	v_pk_mul_f32 v[176:177], v[160:161], v[176:177]
	v_pk_mul_f32 v[178:179], v[162:163], v[178:179]
	v_max_f32_e32 v164, 0, v148
	v_max_f32_e32 v165, 0, v149
	v_max_f32_e32 v166, 0, v150
	v_max_f32_e32 v167, 0, v151
	v_max_f32_e32 v168, 0, v152
	v_max_f32_e32 v169, 0, v153
	v_max_f32_e32 v170, 0, v154
	v_max_f32_e32 v171, 0, v155
	v_pk_add_f32 v[164:165], v[164:165], v[172:173] neg_lo:[0,1] neg_hi:[0,1]
	v_pk_add_f32 v[166:167], v[166:167], v[174:175] neg_lo:[0,1] neg_hi:[0,1]
	v_pk_add_f32 v[168:169], v[168:169], v[176:177] neg_lo:[0,1] neg_hi:[0,1]
	v_pk_add_f32 v[170:171], v[170:171], v[178:179] neg_lo:[0,1] neg_hi:[0,1]
	v_pk_mul_f32 v[164:165], v[164:165], v[124:125]
	v_pk_mul_f32 v[166:167], v[166:167], v[126:127]
	v_pk_mul_f32 v[168:169], v[168:169], v[128:129]
	v_pk_mul_f32 v[170:171], v[170:171], v[130:131]
	v_cvt_pk_bf16_f32 v156, v164, v165
	v_cvt_pk_bf16_f32 v157, v166, v167
	v_cvt_pk_bf16_f32 v158, v168, v169
	v_cvt_pk_bf16_f32 v159, v170, v171
	global_store_dwordx2 v220, v[156:157], s[10:11]
	global_store_dwordx2 v221, v[158:159], s[10:11]
	s_waitcnt vmcnt(4)
; __device__ __forceinline__ unsigned cvt_pk_bf16(float lo, float hi) { unsigned r; asm volatile("v_cvt_pk_bf16_f32 %0, %1, %2" : "=v"(r) : "v"(lo), "v"(hi)); return r; }
; __device__ __forceinline__ float gelu_as(float v) {
;   const float av = fabsf(v); const float t = __builtin_amdgcn_rcpf(av * 0.2316418882f + 1.0f);
;   float q = t * 0.5307027145f + (-0.7265760135f); q = q * t + 0.7107068705f; q = q * t + (-0.142248368f); q = q * t + 0.127414796f; q = q * t;
;   const float e = __builtin_amdgcn_exp2f((v * v) * (-0.72134752044f));
;   const float m = v * (q * e);
;   return v < 0.f ? m : v - m;
; }
; __device__ __forceinline__ void phase_conv(KP p, int l, int tid) {
;     ...
;       for (int q = 0; q < CB; ++q) {
;         const int col = jb + q + 1;
; #pragma unroll
;         for (int di = 0; di < RB + 2; ++di) { const bool ok = rv[di] && (col < 64); unpack4(an[q][di], win[2][di]);
; #pragma unroll
;           for (int k = 0; k < 4; ++k) win[2][di][k] = ok ? win[2][di][k] : 0.f; }
; #pragma unroll
;         for (int rr = 0; rr < RB; ++rr) {
;           float uv[4]; unpack4(ur[q][rr], uv);
;           float o[4];
; #pragma unroll
;           for (int k = 0; k < 4; ++k) {
;             float a = bsv[k];
; #pragma unroll
;             for (int di = 0; di < 3; ++di)
; #pragma unroll
;               for (int dj = 0; dj < 3; ++dj) a += win[dj][rr + di][k] * w[di * 3 + dj][k];
;             o[k] = gelu_as(a) * uv[k];
;           }
;           u32x2 ow; ow.x = cvt_pk_bf16(o[0], o[1]); ow.y = cvt_pk_bf16(o[2], o[3]);
;           *(u32x2*)(G + (size_t)((r0 + rr) * 64 + jb + q) * DFF + c0) = ow;
;         }
; #pragma unroll
;         for (int di = 0; di < RB + 2; ++di)
; #pragma unroll
;           for (int k = 0; k < 4; ++k) { win[0][di][k] = win[1][di][k]; win[1][di][k] = win[2][di][k]; }
;       }
	v_lshlrev_b32_e32 v72, 16, v88
	v_and_b32_e32 v73, 0xffff0000, v88
	v_lshlrev_b32_e32 v74, 16, v89
	v_and_b32_e32 v75, 0xffff0000, v89
	v_lshlrev_b32_e32 v76, 16, v90
	v_and_b32_e32 v77, 0xffff0000, v90
	v_lshlrev_b32_e32 v78, 16, v91
	v_and_b32_e32 v79, 0xffff0000, v91
	v_lshlrev_b32_e32 v80, 16, v92
	v_and_b32_e32 v81, 0xffff0000, v92
	v_lshlrev_b32_e32 v82, 16, v93
	v_and_b32_e32 v83, 0xffff0000, v93
	v_lshlrev_b32_e32 v84, 16, v94
	v_and_b32_e32 v85, 0xffff0000, v94
	v_lshlrev_b32_e32 v86, 16, v95
	v_and_b32_e32 v87, 0xffff0000, v95
	v_pk_mul_f32 v[72:73], v[72:73], v[200:201]
	v_pk_mul_f32 v[74:75], v[74:75], v[200:201]
	v_pk_mul_f32 v[84:85], v[84:85], v[202:203]
	v_pk_mul_f32 v[86:87], v[86:87], v[202:203]
	v_pk_mul_f32 v[72:73], v[72:73], v[204:205]
	v_pk_mul_f32 v[74:75], v[74:75], v[204:205]
	v_pk_mul_f32 v[76:77], v[76:77], v[204:205]
	v_pk_mul_f32 v[78:79], v[78:79], v[204:205]
	v_pk_mul_f32 v[80:81], v[80:81], v[204:205]
	v_pk_mul_f32 v[82:83], v[82:83], v[204:205]
	v_pk_mul_f32 v[84:85], v[84:85], v[204:205]
	v_pk_mul_f32 v[86:87], v[86:87], v[204:205]
	v_lshlrev_b32_e32 v124, 16, v112
	v_and_b32_e32 v125, 0xffff0000, v112
	v_lshlrev_b32_e32 v126, 16, v113
	v_and_b32_e32 v127, 0xffff0000, v113
	v_lshlrev_b32_e32 v128, 16, v114
	v_and_b32_e32 v129, 0xffff0000, v114
	v_lshlrev_b32_e32 v130, 16, v115
	v_and_b32_e32 v131, 0xffff0000, v115
	v_pk_fma_f32 v[148:149], v[40:41], v[0:1], v[36:37]
	v_pk_fma_f32 v[150:151], v[42:43], v[2:3], v[38:39]
	v_pk_fma_f32 v[152:153], v[44:45], v[0:1], v[36:37]
	v_pk_fma_f32 v[154:155], v[46:47], v[2:3], v[38:39]
	v_pk_fma_f32 v[148:149], v[56:57], v[4:5], v[148:149]
	v_pk_fma_f32 v[150:151], v[58:59], v[6:7], v[150:151]
	v_pk_fma_f32 v[152:153], v[60:61], v[4:5], v[152:153]
	v_pk_fma_f32 v[154:155], v[62:63], v[6:7], v[154:155]
	v_pk_fma_f32 v[148:149], v[72:73], v[8:9], v[148:149]
	v_pk_fma_f32 v[150:151], v[74:75], v[10:11], v[150:151]
	v_pk_fma_f32 v[152:153], v[76:77], v[8:9], v[152:153]
	v_pk_fma_f32 v[154:155], v[78:79], v[10:11], v[154:155]
	v_pk_fma_f32 v[148:149], v[44:45], v[12:13], v[148:149]
	v_pk_fma_f32 v[150:151], v[46:47], v[14:15], v[150:151]
	v_pk_fma_f32 v[152:153], v[48:49], v[12:13], v[152:153]
	v_pk_fma_f32 v[154:155], v[50:51], v[14:15], v[154:155]
	v_pk_fma_f32 v[148:149], v[60:61], v[16:17], v[148:149]
	v_pk_fma_f32 v[150:151], v[62:63], v[18:19], v[150:151]
	v_pk_fma_f32 v[152:153], v[64:65], v[16:17], v[152:153]
	v_pk_fma_f32 v[154:155], v[66:67], v[18:19], v[154:155]
	v_pk_fma_f32 v[148:149], v[76:77], v[20:21], v[148:149]
	v_pk_fma_f32 v[150:151], v[78:79], v[22:23], v[150:151]
	v_pk_fma_f32 v[152:153], v[80:81], v[20:21], v[152:153]
	v_pk_fma_f32 v[154:155], v[82:83], v[22:23], v[154:155]
	v_pk_fma_f32 v[148:149], v[48:49], v[24:25], v[148:149]
	v_pk_fma_f32 v[150:151], v[50:51], v[26:27], v[150:151]
	v_pk_fma_f32 v[152:153], v[52:53], v[24:25], v[152:153]
	v_pk_fma_f32 v[154:155], v[54:55], v[26:27], v[154:155]
	v_pk_fma_f32 v[148:149], v[64:65], v[28:29], v[148:149]
	v_pk_fma_f32 v[150:151], v[66:67], v[30:31], v[150:151]
	v_pk_fma_f32 v[152:153], v[68:69], v[28:29], v[152:153]
	v_pk_fma_f32 v[154:155], v[70:71], v[30:31], v[154:155]
	v_pk_fma_f32 v[148:149], v[80:81], v[32:33], v[148:149]
	v_pk_fma_f32 v[150:151], v[82:83], v[34:35], v[150:151]
	v_pk_fma_f32 v[152:153], v[84:85], v[32:33], v[152:153]
	v_pk_fma_f32 v[154:155], v[86:87], v[34:35], v[154:155]
	v_and_b32_e32 v156, 0x7fffffff, v148
	v_and_b32_e32 v157, 0x7fffffff, v149
	v_and_b32_e32 v158, 0x7fffffff, v150
	v_and_b32_e32 v159, 0x7fffffff, v151
	v_and_b32_e32 v160, 0x7fffffff, v152
	v_and_b32_e32 v161, 0x7fffffff, v153
	v_and_b32_e32 v162, 0x7fffffff, v154
	v_and_b32_e32 v163, 0x7fffffff, v155
	v_pk_fma_f32 v[164:165], v[156:157], v[184:185], v[186:187]
; __device__ __forceinline__ unsigned cvt_pk_bf16(float lo, float hi) { unsigned r; asm volatile("v_cvt_pk_bf16_f32 %0, %1, %2" : "=v"(r) : "v"(lo), "v"(hi)); return r; }
; __device__ __forceinline__ float gelu_as(float v) {
;   const float av = fabsf(v); const float t = __builtin_amdgcn_rcpf(av * 0.2316418882f + 1.0f);
;   float q = t * 0.5307027145f + (-0.7265760135f); q = q * t + 0.7107068705f; q = q * t + (-0.142248368f); q = q * t + 0.127414796f; q = q * t;
;   const float e = __builtin_amdgcn_exp2f((v * v) * (-0.72134752044f));
;   const float m = v * (q * e);
;   return v < 0.f ? m : v - m;
; }
; __device__ __forceinline__ void phase_conv(KP p, int l, int tid) {
;     ...
;   for (int it = blockIdx.x * NTH + tid; it < total; it += gridDim.x * NTH) {
;     ...
;             o[k] = gelu_as(a) * uv[k];
;           }
;           u32x2 ow; ow.x = cvt_pk_bf16(o[0], o[1]); ow.y = cvt_pk_bf16(o[2], o[3]);
;           *(u32x2*)(G + (size_t)((r0 + rr) * 64 + jb + q) * DFF + c0) = ow;
	v_pk_fma_f32 v[166:167], v[158:159], v[184:185], v[186:187]
	v_pk_fma_f32 v[168:169], v[160:161], v[184:185], v[186:187]
	v_pk_fma_f32 v[170:171], v[162:163], v[184:185], v[186:187]
	v_rcp_f32_e32 v164, v164
	v_rcp_f32_e32 v165, v165
	v_rcp_f32_e32 v166, v166
	v_rcp_f32_e32 v167, v167
	v_rcp_f32_e32 v168, v168
	v_rcp_f32_e32 v169, v169
	v_rcp_f32_e32 v170, v170
	v_rcp_f32_e32 v171, v171
	v_pk_fma_f32 v[172:173], v[164:165], v[188:189], v[190:191]
	v_pk_fma_f32 v[174:175], v[166:167], v[188:189], v[190:191]
	v_pk_fma_f32 v[176:177], v[168:169], v[188:189], v[190:191]
	v_pk_fma_f32 v[178:179], v[170:171], v[188:189], v[190:191]
	v_pk_fma_f32 v[172:173], v[172:173], v[164:165], v[192:193]
	v_pk_fma_f32 v[174:175], v[174:175], v[166:167], v[192:193]
	v_pk_fma_f32 v[176:177], v[176:177], v[168:169], v[192:193]
	v_pk_fma_f32 v[178:179], v[178:179], v[170:171], v[192:193]
	v_pk_fma_f32 v[172:173], v[172:173], v[164:165], v[194:195]
	v_pk_fma_f32 v[174:175], v[174:175], v[166:167], v[194:195]
	v_pk_fma_f32 v[176:177], v[176:177], v[168:169], v[194:195]
	v_pk_fma_f32 v[178:179], v[178:179], v[170:171], v[194:195]
	v_pk_fma_f32 v[172:173], v[172:173], v[164:165], v[196:197]
	v_pk_fma_f32 v[174:175], v[174:175], v[166:167], v[196:197]
	v_pk_fma_f32 v[176:177], v[176:177], v[168:169], v[196:197]
	v_pk_fma_f32 v[178:179], v[178:179], v[170:171], v[196:197]
	v_pk_mul_f32 v[172:173], v[172:173], v[164:165]
	v_pk_mul_f32 v[174:175], v[174:175], v[166:167]
	v_pk_mul_f32 v[176:177], v[176:177], v[168:169]
	v_pk_mul_f32 v[178:179], v[178:179], v[170:171]
	v_pk_mul_f32 v[164:165], v[148:149], v[148:149]
	v_pk_mul_f32 v[166:167], v[150:151], v[150:151]
	v_pk_mul_f32 v[168:169], v[152:153], v[152:153]
	v_pk_mul_f32 v[170:171], v[154:155], v[154:155]
	v_pk_mul_f32 v[164:165], v[164:165], v[198:199]
	v_pk_mul_f32 v[166:167], v[166:167], v[198:199]
	v_pk_mul_f32 v[168:169], v[168:169], v[198:199]
	v_pk_mul_f32 v[170:171], v[170:171], v[198:199]
	v_exp_f32_e32 v164, v164
	v_exp_f32_e32 v165, v165
	v_exp_f32_e32 v166, v166
	v_exp_f32_e32 v167, v167
	v_exp_f32_e32 v168, v168
	v_exp_f32_e32 v169, v169
	v_exp_f32_e32 v170, v170
	v_exp_f32_e32 v171, v171
	v_pk_mul_f32 v[172:173], v[172:173], v[164:165]
	v_pk_mul_f32 v[174:175], v[174:175], v[166:167]
	v_pk_mul_f32 v[176:177], v[176:177], v[168:169]
	v_pk_mul_f32 v[178:179], v[178:179], v[170:171]
	v_pk_mul_f32 v[172:173], v[156:157], v[172:173]
	v_pk_mul_f32 v[174:175], v[158:159], v[174:175]
	v_pk_mul_f32 v[176:177], v[160:161], v[176:177]
	v_pk_mul_f32 v[178:179], v[162:163], v[178:179]
	v_max_f32_e32 v164, 0, v148
	v_max_f32_e32 v165, 0, v149
	v_max_f32_e32 v166, 0, v150
	v_max_f32_e32 v167, 0, v151
	v_max_f32_e32 v168, 0, v152
	v_max_f32_e32 v169, 0, v153
	v_max_f32_e32 v170, 0, v154
	v_max_f32_e32 v171, 0, v155
	v_pk_add_f32 v[164:165], v[164:165], v[172:173] neg_lo:[0,1] neg_hi:[0,1]
	v_pk_add_f32 v[166:167], v[166:167], v[174:175] neg_lo:[0,1] neg_hi:[0,1]
	v_pk_add_f32 v[168:169], v[168:169], v[176:177] neg_lo:[0,1] neg_hi:[0,1]
	v_pk_add_f32 v[170:171], v[170:171], v[178:179] neg_lo:[0,1] neg_hi:[0,1]
	v_pk_mul_f32 v[164:165], v[164:165], v[124:125]
	v_pk_mul_f32 v[166:167], v[166:167], v[126:127]
	v_pk_mul_f32 v[168:169], v[168:169], v[128:129]
	v_pk_mul_f32 v[170:171], v[170:171], v[130:131]
	v_cvt_pk_bf16_f32 v156, v164, v165
	v_cvt_pk_bf16_f32 v157, v166, v167
	v_cvt_pk_bf16_f32 v158, v168, v169
	v_cvt_pk_bf16_f32 v159, v170, v171
	global_store_dwordx2 v216, v[156:157], s[10:11]
	global_store_dwordx2 v217, v[158:159], s[10:11]
	v_add_u32_e32 v142, s73, v142
	s_mov_b32 s0, 0xaffff
	v_cmp_lt_i32_e32 vcc, s0, v142
	s_or_b64 s[28:29], vcc, s[28:29]
	s_andn2_b64 exec, exec, s[28:29]
	s_cbranch_execnz .Lcv_item

; __device__ __forceinline__ void norm_rows(const float* src, int nrows, const float* gam, const float* sc, const float* sh, bf16_t* dst, int tid) {
;   const int lane = tid & 63; const int gw = blockIdx.x * 8 + (tid >> 6), nw = gridDim.x * 8;
; #pragma unroll 1
;   for (int r0 = gw; r0 < nrows; r0 += 4 * nw) {
;     f32x4 v[4][8]; float ss[4]; int rr[4]; bool ok[4];
; #pragma unroll
;     for (int q = 0; q < 4; ++q) { const int r = r0 + q * nw; ok[q] = r < nrows; rr[q] = ok[q] ? r : r0; }
; #pragma unroll
;     for (int q = 0; q < 4; ++q) { const f32x4* xr = (const f32x4*)(src + (size_t)rr[q] * DM) + lane;
; #pragma unroll
;       for (int j = 0; j < 8; ++j) v[q][j] = xr[64 * j]; }
; #pragma unroll
;     for (int q = 0; q < 4; ++q) { float s = 0.f;
; #pragma unroll
;       for (int j = 0; j < 8; ++j) s += v[q][j][0] * v[q][j][0] + v[q][j][1] * v[q][j][1] + v[q][j][2] * v[q][j][2] + v[q][j][3] * v[q][j][3];
;       ss[q] = rsqrtf(wave_sum(s) * (1.0f / DM) + 1e-6f); }
; #pragma unroll
;     for (int j = 0; j < 8; ++j) {
;       const int c = 4 * (lane + 64 * j);
;       const f32x4 mul = *(const f32x4*)(gam + c) * (1.0f + *(const f32x4*)(sc + c)); const f32x4 add = *(const f32x4*)(sh + c);
; __device__ __forceinline__ void phase_norm(KP p, int ph, unsigned char* shm, int tid) {
;   unsigned char* ws = p->ws; const float* modv = (const float*)(ws + WS_MODV); bf16_t* HA = (bf16_t*)(ws + WS_HA);
;   if (ph == 18) { final_norm(p->out, p->in[32], tid); return; }
;   const int l = (ph >= 11), ffn = (ph == 7 || ph == 14);
;   const float* gam = (ffn ? p->in[5] : p->in[4]) + l * DM;
;   const float* sh = modv + l * 12288 + (ffn ? 3 : 0) * DM; const float* sc = sh + DM;
;   norm_rows(ph == 1 ? p->in[0] : p->out, SEQ, gam, sc, sh, HA, tid);
.LBB0_348:
	s_cmp_gt_u32 s84, 10
	v_readlane_b32 s4, v254, 9
	s_cselect_b64 s[8:9], -1, 0
	v_readlane_b32 s5, v254, 10
	s_add_u32 s0, s4, s0
	s_addc_u32 s1, s5, s1
	s_load_dwordx2 s[2:3], s[0:1], 0x0
	s_nop 0
	s_load_dwordx2 s[0:1], s[4:5], 0x110
	s_and_b64 s[4:5], s[8:9], exec
	s_cselect_b32 s4, 0x2000, 0
	v_ashrrev_i32_e32 v145, 6, v146
	s_waitcnt lgkmcnt(0)
	s_add_u32 s2, s2, s4
	s_addc_u32 s3, s3, 0
	v_readlane_b32 s7, v253, 19
	s_cmp_eq_u32 s84, 1
	s_cselect_b64 s[4:5], -1, 0
	v_add_u32_e32 v132, s7, v145
	s_movk_i32 s7, 0x4000
	v_cmp_gt_i32_e32 vcc, s7, v132
	v_ashrrev_i32_e32 v133, 31, v132
	s_and_saveexec_b64 s[14:15], vcc
	s_cbranch_execz .LBB0_399
	s_and_b64 s[10:11], s[4:5], exec
	s_cselect_b32 s7, 0, 0x108
	v_readlane_b32 s10, v254, 9
	v_readlane_b32 s11, v254, 10
	s_add_u32 s10, s10, s7
	s_addc_u32 s11, s11, 0
	s_and_b64 s[8:9], s[8:9], exec
	s_cselect_b32 s7, 0xc000, 0
	s_add_u32 s7, s0, s7
	s_addc_u32 s8, s1, 0
	s_lshl_b32 s6, s6, 2
	s_add_u32 s9, s7, s6
	s_addc_u32 s12, s8, 0
	s_add_u32 s6, s9, 0x6c00000
	s_addc_u32 s7, s12, 0
	v_and_b32_e32 v0, 63, v229
	s_add_u32 s8, s9, 0x6c02000
	v_lshlrev_b32_e32 v138, 4, v0
	v_lshlrev_b32_e32 v0, 3, v0
	v_mov_b32_e32 v1, v139
	s_addc_u32 s9, s12, 0
	v_lshl_add_u64 v[2:3], s[0:1], 0, v[0:1]
	s_mov_b64 s[12:13], 0x6c21000
	v_lshl_add_u64 v[136:137], v[2:3], 0, s[12:13]
	v_or_b32_e32 v2, 0x400, v138
	v_mov_b32_e32 v3, v139
	v_lshl_add_u64 v[154:155], s[8:9], 0, v[2:3]
	v_or_b32_e32 v2, 0x800, v138
	v_lshl_add_u64 v[156:157], s[8:9], 0, v[2:3]
	v_or_b32_e32 v2, 0xc00, v138
	v_lshl_add_u64 v[158:159], s[8:9], 0, v[2:3]
	v_or_b32_e32 v2, 0x1000, v138
	v_lshl_add_u64 v[160:161], s[2:3], 0, v[2:3]
	v_lshl_add_u64 v[162:163], s[8:9], 0, v[2:3]
	v_lshl_add_u64 v[164:165], s[6:7], 0, v[2:3]
	v_or_b32_e32 v2, 0x1400, v138
	v_lshl_add_u64 v[166:167], s[2:3], 0, v[2:3]
	v_lshl_add_u64 v[168:169], s[8:9], 0, v[2:3]
	v_lshl_add_u64 v[170:171], s[6:7], 0, v[2:3]
	v_or_b32_e32 v2, 0x1800, v138
	v_lshl_add_u64 v[172:173], s[2:3], 0, v[2:3]
	v_lshl_add_u64 v[174:175], s[8:9], 0, v[2:3]
	v_lshl_add_u64 v[176:177], s[6:7], 0, v[2:3]
	v_or_b32_e32 v2, 0x1c00, v138
	s_load_dwordx2 s[10:11], s[10:11], 0x0
	v_lshl_add_u64 v[178:179], s[2:3], 0, v[2:3]
	v_lshl_add_u64 v[180:181], s[8:9], 0, v[2:3]
	v_lshl_add_u64 v[182:183], s[6:7], 0, v[2:3]
	v_lshlrev_b64 v[2:3], 12, v[132:133]
	v_or_b32_e32 v2, v2, v0
	v_lshl_add_u64 v[152:153], s[6:7], 0, v[138:139]
	v_lshl_add_u64 v[0:1], s[0:1], 0, v[2:3]
	s_mov_b64 s[6:7], 0x6c21e00
	v_lshl_add_u64 v[184:185], v[0:1], 0, s[6:7]
	v_lshlrev_b64 v[0:1], 13, v[132:133]
	v_or_b32_e32 v0, v0, v138
	s_waitcnt lgkmcnt(0)
	v_lshl_add_u64 v[0:1], s[10:11], 0, v[0:1]
	s_mov_b64 s[6:7], 0x1c00
	v_lshl_add_u64 v[134:135], s[10:11], 0, v[138:139]
	v_lshl_add_u64 v[148:149], s[2:3], 0, v[138:139]
	v_lshl_add_u64 v[150:151], s[8:9], 0, v[138:139]
	v_lshl_add_u64 v[186:187], v[0:1], 0, s[6:7]
	s_mov_b64 s[16:17], 0
	v_mov_b32_e32 v147, v132
	s_mov_b64 s[8:9], 0x1000
	v_lshl_add_u64 v[218:219], v[148:149], 0, s[8:9]
	global_load_dwordx4 v[154:157], v[148:149], off
	global_load_dwordx4 v[158:161], v[148:149], off offset:1024
	global_load_dwordx4 v[162:165], v[148:149], off offset:2048
	global_load_dwordx4 v[166:169], v[148:149], off offset:3072
	global_load_dwordx4 v[170:173], v[218:219], off
	global_load_dwordx4 v[174:177], v[218:219], off offset:1024
	global_load_dwordx4 v[178:181], v[218:219], off offset:2048
	global_load_dwordx4 v[182:185], v[218:219], off offset:3072
	v_lshl_add_u64 v[218:219], v[152:153], 0, s[8:9]
	global_load_dwordx4 v[186:189], v[152:153], off
	global_load_dwordx4 v[190:193], v[152:153], off offset:1024
	global_load_dwordx4 v[194:197], v[152:153], off offset:2048
	global_load_dwordx4 v[198:201], v[152:153], off offset:3072
	global_load_dwordx4 v[202:205], v[218:219], off
	global_load_dwordx4 v[206:209], v[218:219], off offset:1024
	global_load_dwordx4 v[210:213], v[218:219], off offset:2048
	global_load_dwordx4 v[214:217], v[218:219], off offset:3072
	v_lshl_add_u64 v[218:219], v[150:151], 0, s[8:9]
	global_load_dwordx4 v[0:3], v[150:151], off
	global_load_dwordx4 v[4:7], v[150:151], off offset:1024
	global_load_dwordx4 v[8:11], v[150:151], off offset:2048
	global_load_dwordx4 v[12:15], v[150:151], off offset:3072
	global_load_dwordx4 v[16:19], v[218:219], off
	global_load_dwordx4 v[20:23], v[218:219], off offset:1024
	global_load_dwordx4 v[24:27], v[218:219], off offset:2048
	global_load_dwordx4 v[28:31], v[218:219], off offset:3072
	s_waitcnt vmcnt(0)
	v_pk_add_f32 v[0:1], v[0:1], 1.0 op_sel_hi:[1,0]
	v_pk_mul_f32 v[154:155], v[154:155], v[0:1]
	v_pk_add_f32 v[2:3], v[2:3], 1.0 op_sel_hi:[1,0]
	v_pk_mul_f32 v[156:157], v[156:157], v[2:3]
	v_pk_add_f32 v[4:5], v[4:5], 1.0 op_sel_hi:[1,0]
	v_pk_mul_f32 v[158:159], v[158:159], v[4:5]
	v_pk_add_f32 v[6:7], v[6:7], 1.0 op_sel_hi:[1,0]
	v_pk_mul_f32 v[160:161], v[160:161], v[6:7]
	v_pk_add_f32 v[8:9], v[8:9], 1.0 op_sel_hi:[1,0]
	v_pk_mul_f32 v[162:163], v[162:163], v[8:9]
	v_pk_add_f32 v[10:11], v[10:11], 1.0 op_sel_hi:[1,0]
	v_pk_mul_f32 v[164:165], v[164:165], v[10:11]
	v_pk_add_f32 v[12:13], v[12:13], 1.0 op_sel_hi:[1,0]
	v_pk_mul_f32 v[166:167], v[166:167], v[12:13]
	v_pk_add_f32 v[14:15], v[14:15], 1.0 op_sel_hi:[1,0]
	v_pk_mul_f32 v[168:169], v[168:169], v[14:15]
	v_pk_add_f32 v[16:17], v[16:17], 1.0 op_sel_hi:[1,0]
	v_pk_mul_f32 v[170:171], v[170:171], v[16:17]
	v_pk_add_f32 v[18:19], v[18:19], 1.0 op_sel_hi:[1,0]
	v_pk_mul_f32 v[172:173], v[172:173], v[18:19]
	v_pk_add_f32 v[20:21], v[20:21], 1.0 op_sel_hi:[1,0]
	v_pk_mul_f32 v[174:175], v[174:175], v[20:21]
	v_pk_add_f32 v[22:23], v[22:23], 1.0 op_sel_hi:[1,0]
	v_pk_mul_f32 v[176:177], v[176:177], v[22:23]
	v_pk_add_f32 v[24:25], v[24:25], 1.0 op_sel_hi:[1,0]
	v_pk_mul_f32 v[178:179], v[178:179], v[24:25]
	v_pk_add_f32 v[26:27], v[26:27], 1.0 op_sel_hi:[1,0]
	v_pk_mul_f32 v[180:181], v[180:181], v[26:27]
	v_pk_add_f32 v[28:29], v[28:29], 1.0 op_sel_hi:[1,0]
	v_pk_mul_f32 v[182:183], v[182:183], v[28:29]
	v_pk_add_f32 v[30:31], v[30:31], 1.0 op_sel_hi:[1,0]
	v_pk_mul_f32 v[184:185], v[184:185], v[30:31]
	v_mbcnt_lo_u32_b32 v153, -1, 0
	v_mbcnt_hi_u32_b32 v153, -1, v153
	v_lshlrev_b32_e32 v153, 2, v153
	v_xor_b32_e32 v140, 4, v153
	v_xor_b32_e32 v141, 8, v153
	v_xor_b32_e32 v142, 16, v153
	v_xor_b32_e32 v150, 32, v153
	v_xor_b32_e32 v151, 64, v153
	v_xor_b32_e32 v152, 0x80, v153
	s_nop 0
	v_readfirstlane_b32 s6, v147
; __device__ __forceinline__ void norm_rows(const float* src, int nrows, const float* gam, const float* sc, const float* sh, bf16_t* dst, int tid) {
;     ...
;   for (int r0 = gw; r0 < nrows; r0 += 4 * nw) {
;     f32x4 v[4][8]; float ss[4]; int rr[4]; bool ok[4];
; #pragma unroll
;     for (int q = 0; q < 4; ++q) { const int r = r0 + q * nw; ok[q] = r < nrows; rr[q] = ok[q] ? r : r0; }
; #pragma unroll
;     for (int q = 0; q < 4; ++q) { const f32x4* xr = (const f32x4*)(src + (size_t)rr[q] * DM) + lane;
; #pragma unroll
;       for (int j = 0; j < 8; ++j) v[q][j] = xr[64 * j]; }
; #pragma unroll
;     for (int q = 0; q < 4; ++q) { float s = 0.f;
; #pragma unroll
;       for (int j = 0; j < 8; ++j) s += v[q][j][0] * v[q][j][0] + v[q][j][1] * v[q][j][1] + v[q][j][2] * v[q][j][2] + v[q][j][3] * v[q][j][3];
.Lnr_loop:
	s_mov_b32 s10, s6
	s_lshl_b32 s8, s10, 13
	s_add_u32 s8, s8, 0x1000
	s_mov_b32 s9, 0
	v_lshl_add_u64 v[244:245], v[134:135], 0, s[8:9]
	global_load_dwordx4 v[0:3], v[244:245], off offset:-4096
	global_load_dwordx4 v[4:7], v[244:245], off offset:-3072
	global_load_dwordx4 v[8:11], v[244:245], off offset:-2048
	global_load_dwordx4 v[12:15], v[244:245], off offset:-1024
	global_load_dwordx4 v[16:19], v[244:245], off
	global_load_dwordx4 v[20:23], v[244:245], off offset:1024
	global_load_dwordx4 v[24:27], v[244:245], off offset:2048
	global_load_dwordx4 v[28:31], v[244:245], off offset:3072
	s_add_i32 s10, s6, s82
	s_cmp_lt_i32 s10, 0x4000
	s_cselect_b32 s10, s10, s6
	s_lshl_b32 s8, s10, 13
	s_add_u32 s8, s8, 0x1000
	s_mov_b32 s9, 0
	v_lshl_add_u64 v[246:247], v[134:135], 0, s[8:9]
	global_load_dwordx4 v[32:35], v[246:247], off offset:-4096
	global_load_dwordx4 v[36:39], v[246:247], off offset:-3072
	global_load_dwordx4 v[40:43], v[246:247], off offset:-2048
	global_load_dwordx4 v[44:47], v[246:247], off offset:-1024
	global_load_dwordx4 v[48:51], v[246:247], off
	global_load_dwordx4 v[52:55], v[246:247], off offset:1024
	global_load_dwordx4 v[56:59], v[246:247], off offset:2048
	global_load_dwordx4 v[60:63], v[246:247], off offset:3072
	s_add_i32 s10, s6, s71
	s_cmp_lt_i32 s10, 0x4000
	s_cselect_b32 s10, s10, s6
	s_lshl_b32 s8, s10, 13
	s_add_u32 s8, s8, 0x1000
	s_mov_b32 s9, 0
	v_lshl_add_u64 v[248:249], v[134:135], 0, s[8:9]
	global_load_dwordx4 v[64:67], v[248:249], off offset:-4096
	global_load_dwordx4 v[68:71], v[248:249], off offset:-3072
	global_load_dwordx4 v[72:75], v[248:249], off offset:-2048
	global_load_dwordx4 v[76:79], v[248:249], off offset:-1024
	global_load_dwordx4 v[80:83], v[248:249], off
	global_load_dwordx4 v[84:87], v[248:249], off offset:1024
	global_load_dwordx4 v[88:91], v[248:249], off offset:2048
	global_load_dwordx4 v[92:95], v[248:249], off offset:3072
	s_add_i32 s10, s6, s87
	s_cmp_lt_i32 s10, 0x4000
	s_cselect_b32 s10, s10, s6
	s_lshl_b32 s8, s10, 13
	s_add_u32 s8, s8, 0x1000
	s_mov_b32 s9, 0
	v_lshl_add_u64 v[250:251], v[134:135], 0, s[8:9]
	global_load_dwordx4 v[96:99], v[250:251], off offset:-4096
	global_load_dwordx4 v[100:103], v[250:251], off offset:-3072
	global_load_dwordx4 v[104:107], v[250:251], off offset:-2048
	global_load_dwordx4 v[108:111], v[250:251], off offset:-1024
	global_load_dwordx4 v[112:115], v[250:251], off
	global_load_dwordx4 v[116:119], v[250:251], off offset:1024
	global_load_dwordx4 v[120:123], v[250:251], off offset:2048
	global_load_dwordx4 v[124:127], v[250:251], off offset:3072
	s_waitcnt vmcnt(31)
	v_pk_mul_f32 v[218:219], v[0:1], v[0:1]
	v_pk_fma_f32 v[218:219], v[2:3], v[2:3], v[218:219]
	s_waitcnt vmcnt(30)
	v_pk_mul_f32 v[220:221], v[4:5], v[4:5]
	v_pk_fma_f32 v[220:221], v[6:7], v[6:7], v[220:221]
	s_waitcnt vmcnt(29)
	v_pk_mul_f32 v[222:223], v[8:9], v[8:9]
	v_pk_fma_f32 v[222:223], v[10:11], v[10:11], v[222:223]
	s_waitcnt vmcnt(28)
	v_pk_mul_f32 v[224:225], v[12:13], v[12:13]
	v_pk_fma_f32 v[224:225], v[14:15], v[14:15], v[224:225]
	s_waitcnt vmcnt(27)
	v_pk_fma_f32 v[218:219], v[16:17], v[16:17], v[218:219]
	v_pk_fma_f32 v[218:219], v[18:19], v[18:19], v[218:219]
	s_waitcnt vmcnt(26)
	v_pk_fma_f32 v[220:221], v[20:21], v[20:21], v[220:221]
	v_pk_fma_f32 v[220:221], v[22:23], v[22:23], v[220:221]
	s_waitcnt vmcnt(25)
	v_pk_fma_f32 v[222:223], v[24:25], v[24:25], v[222:223]
	v_pk_fma_f32 v[222:223], v[26:27], v[26:27], v[222:223]
	s_waitcnt vmcnt(24)
	v_pk_fma_f32 v[224:225], v[28:29], v[28:29], v[224:225]
	v_pk_fma_f32 v[224:225], v[30:31], v[30:31], v[224:225]
	v_pk_add_f32 v[218:219], v[218:219], v[220:221]
	v_pk_add_f32 v[222:223], v[222:223], v[224:225]
	v_pk_add_f32 v[218:219], v[218:219], v[222:223]
	v_add_f32_e32 v128, v218, v219
	s_waitcnt vmcnt(23)
	v_pk_mul_f32 v[218:219], v[32:33], v[32:33]
	v_pk_fma_f32 v[218:219], v[34:35], v[34:35], v[218:219]
	s_waitcnt vmcnt(22)
	v_pk_mul_f32 v[220:221], v[36:37], v[36:37]
	v_pk_fma_f32 v[220:221], v[38:39], v[38:39], v[220:221]
	s_waitcnt vmcnt(21)
	v_pk_mul_f32 v[222:223], v[40:41], v[40:41]
	v_pk_fma_f32 v[222:223], v[42:43], v[42:43], v[222:223]
	s_waitcnt vmcnt(20)
	v_pk_mul_f32 v[224:225], v[44:45], v[44:45]
	v_pk_fma_f32 v[224:225], v[46:47], v[46:47], v[224:225]
	s_waitcnt vmcnt(19)
	v_pk_fma_f32 v[218:219], v[48:49], v[48:49], v[218:219]
	v_pk_fma_f32 v[218:219], v[50:51], v[50:51], v[218:219]
	s_waitcnt vmcnt(18)
	v_pk_fma_f32 v[220:221], v[52:53], v[52:53], v[220:221]
	v_pk_fma_f32 v[220:221], v[54:55], v[54:55], v[220:221]
	s_waitcnt vmcnt(17)
	v_pk_fma_f32 v[222:223], v[56:57], v[56:57], v[222:223]
	v_pk_fma_f32 v[222:223], v[58:59], v[58:59], v[222:223]
	s_waitcnt vmcnt(16)
	v_pk_fma_f32 v[224:225], v[60:61], v[60:61], v[224:225]
	v_pk_fma_f32 v[224:225], v[62:63], v[62:63], v[224:225]
	v_pk_add_f32 v[218:219], v[218:219], v[220:221]
	v_pk_add_f32 v[222:223], v[222:223], v[224:225]
	v_pk_add_f32 v[218:219], v[218:219], v[222:223]
	v_add_f32_e32 v130, v218, v219
	s_waitcnt vmcnt(15)
	v_pk_mul_f32 v[218:219], v[64:65], v[64:65]
	v_pk_fma_f32 v[218:219], v[66:67], v[66:67], v[218:219]
	s_waitcnt vmcnt(14)
	v_pk_mul_f32 v[220:221], v[68:69], v[68:69]
	v_pk_fma_f32 v[220:221], v[70:71], v[70:71], v[220:221]
	s_waitcnt vmcnt(13)
	v_pk_mul_f32 v[222:223], v[72:73], v[72:73]
	v_pk_fma_f32 v[222:223], v[74:75], v[74:75], v[222:223]
	s_waitcnt vmcnt(12)
	v_pk_mul_f32 v[224:225], v[76:77], v[76:77]
	v_pk_fma_f32 v[224:225], v[78:79], v[78:79], v[224:225]
	s_waitcnt vmcnt(11)
	v_pk_fma_f32 v[218:219], v[80:81], v[80:81], v[218:219]
	v_pk_fma_f32 v[218:219], v[82:83], v[82:83], v[218:219]
	s_waitcnt vmcnt(10)
; __device__ __forceinline__ unsigned cvt_pk_bf16(float lo, float hi) { unsigned r; asm volatile("v_cvt_pk_bf16_f32 %0, %1, %2" : "=v"(r) : "v"(lo), "v"(hi)); return r; }
; __device__ __forceinline__ void norm_rows(const float* src, int nrows, const float* gam, const float* sc, const float* sh, bf16_t* dst, int tid) {
;     ...
;     for (int q = 0; q < 4; ++q) { float s = 0.f;
; #pragma unroll
;       for (int j = 0; j < 8; ++j) s += v[q][j][0] * v[q][j][0] + v[q][j][1] * v[q][j][1] + v[q][j][2] * v[q][j][2] + v[q][j][3] * v[q][j][3];
;       ss[q] = rsqrtf(wave_sum(s) * (1.0f / DM) + 1e-6f); }
; #pragma unroll
;     for (int j = 0; j < 8; ++j) {
;       const int c = 4 * (lane + 64 * j);
;       const f32x4 mul = *(const f32x4*)(gam + c) * (1.0f + *(const f32x4*)(sc + c)); const f32x4 add = *(const f32x4*)(sh + c);
; #pragma unroll
;       for (int q = 0; q < 4; ++q) if (ok[q]) {
;         const f32x4 h = v[q][j] * ss[q] * mul + add; u32x2 w; w.x = cvt_pk_bf16(h[0], h[1]); w.y = cvt_pk_bf16(h[2], h[3]);
;         ((u32x2*)(dst + (size_t)rr[q] * DM) + lane)[64 * j] = w;
	v_pk_fma_f32 v[220:221], v[84:85], v[84:85], v[220:221]
	v_pk_fma_f32 v[220:221], v[86:87], v[86:87], v[220:221]
	s_waitcnt vmcnt(9)
	v_pk_fma_f32 v[222:223], v[88:89], v[88:89], v[222:223]
	v_pk_fma_f32 v[222:223], v[90:91], v[90:91], v[222:223]
	s_waitcnt vmcnt(8)
	v_pk_fma_f32 v[224:225], v[92:93], v[92:93], v[224:225]
	v_pk_fma_f32 v[224:225], v[94:95], v[94:95], v[224:225]
	v_pk_add_f32 v[218:219], v[218:219], v[220:221]
	v_pk_add_f32 v[222:223], v[222:223], v[224:225]
	v_pk_add_f32 v[218:219], v[218:219], v[222:223]
	v_add_f32_e32 v238, v218, v219
	s_waitcnt vmcnt(7)
	v_pk_mul_f32 v[218:219], v[96:97], v[96:97]
	v_pk_fma_f32 v[218:219], v[98:99], v[98:99], v[218:219]
	s_waitcnt vmcnt(6)
	v_pk_mul_f32 v[220:221], v[100:101], v[100:101]
	v_pk_fma_f32 v[220:221], v[102:103], v[102:103], v[220:221]
	s_waitcnt vmcnt(5)
	v_pk_mul_f32 v[222:223], v[104:105], v[104:105]
	v_pk_fma_f32 v[222:223], v[106:107], v[106:107], v[222:223]
	s_waitcnt vmcnt(4)
	v_pk_mul_f32 v[224:225], v[108:109], v[108:109]
	v_pk_fma_f32 v[224:225], v[110:111], v[110:111], v[224:225]
	s_waitcnt vmcnt(3)
	v_pk_fma_f32 v[218:219], v[112:113], v[112:113], v[218:219]
	v_pk_fma_f32 v[218:219], v[114:115], v[114:115], v[218:219]
	s_waitcnt vmcnt(2)
	v_pk_fma_f32 v[220:221], v[116:117], v[116:117], v[220:221]
	v_pk_fma_f32 v[220:221], v[118:119], v[118:119], v[220:221]
	s_waitcnt vmcnt(1)
	v_pk_fma_f32 v[222:223], v[120:121], v[120:121], v[222:223]
	v_pk_fma_f32 v[222:223], v[122:123], v[122:123], v[222:223]
	s_waitcnt vmcnt(0)
	v_pk_fma_f32 v[224:225], v[124:125], v[124:125], v[224:225]
	v_pk_fma_f32 v[224:225], v[126:127], v[126:127], v[224:225]
	v_pk_add_f32 v[218:219], v[218:219], v[220:221]
	v_pk_add_f32 v[222:223], v[222:223], v[224:225]
	v_pk_add_f32 v[218:219], v[218:219], v[222:223]
	v_add_f32_e32 v240, v218, v219
	ds_bpermute_b32 v129, v140, v128
	ds_bpermute_b32 v131, v140, v130
	ds_bpermute_b32 v239, v140, v238
	ds_bpermute_b32 v241, v140, v240
	s_waitcnt lgkmcnt(0)
	v_add_f32_e32 v128, v128, v129
	v_add_f32_e32 v130, v130, v131
	v_add_f32_e32 v238, v238, v239
	v_add_f32_e32 v240, v240, v241
	ds_bpermute_b32 v129, v141, v128
	ds_bpermute_b32 v131, v141, v130
	ds_bpermute_b32 v239, v141, v238
	ds_bpermute_b32 v241, v141, v240
	s_waitcnt lgkmcnt(0)
	v_add_f32_e32 v128, v128, v129
	v_add_f32_e32 v130, v130, v131
	v_add_f32_e32 v238, v238, v239
	v_add_f32_e32 v240, v240, v241
	ds_bpermute_b32 v129, v142, v128
	ds_bpermute_b32 v131, v142, v130
	ds_bpermute_b32 v239, v142, v238
	ds_bpermute_b32 v241, v142, v240
	s_waitcnt lgkmcnt(0)
	v_add_f32_e32 v128, v128, v129
	v_add_f32_e32 v130, v130, v131
	v_add_f32_e32 v238, v238, v239
	v_add_f32_e32 v240, v240, v241
	ds_bpermute_b32 v129, v150, v128
	ds_bpermute_b32 v131, v150, v130
	ds_bpermute_b32 v239, v150, v238
	ds_bpermute_b32 v241, v150, v240
	s_waitcnt lgkmcnt(0)
	v_add_f32_e32 v128, v128, v129
	v_add_f32_e32 v130, v130, v131
	v_add_f32_e32 v238, v238, v239
	v_add_f32_e32 v240, v240, v241
	ds_bpermute_b32 v129, v151, v128
	ds_bpermute_b32 v131, v151, v130
	ds_bpermute_b32 v239, v151, v238
	ds_bpermute_b32 v241, v151, v240
	s_waitcnt lgkmcnt(0)
	v_add_f32_e32 v128, v128, v129
	v_add_f32_e32 v130, v130, v131
	v_add_f32_e32 v238, v238, v239
	v_add_f32_e32 v240, v240, v241
	ds_bpermute_b32 v129, v152, v128
	ds_bpermute_b32 v131, v152, v130
	ds_bpermute_b32 v239, v152, v238
	ds_bpermute_b32 v241, v152, v240
	s_waitcnt lgkmcnt(0)
	v_add_f32_e32 v128, v128, v129
	v_add_f32_e32 v130, v130, v131
	v_add_f32_e32 v238, v238, v239
	v_add_f32_e32 v240, v240, v241
	v_fmamk_f32 v128, v128, 0x3a000000, v228
	v_mul_f32_e32 v129, 0x4b800000, v128
	v_cmp_gt_f32_e32 vcc, s67, v128
	s_nop 1
	v_cndmask_b32_e32 v128, v128, v129, vcc
	v_rsq_f32_e32 v128, v128
	s_nop 0
	v_mul_f32_e32 v129, 0x45800000, v128
	v_cndmask_b32_e32 v128, v128, v129, vcc
	v_fmamk_f32 v130, v130, 0x3a000000, v228
	v_mul_f32_e32 v131, 0x4b800000, v130
	v_cmp_gt_f32_e32 vcc, s67, v130
	s_nop 1
	v_cndmask_b32_e32 v130, v130, v131, vcc
	v_rsq_f32_e32 v130, v130
	s_nop 0
	v_mul_f32_e32 v131, 0x45800000, v130
	v_cndmask_b32_e32 v130, v130, v131, vcc
	v_fmamk_f32 v238, v238, 0x3a000000, v228
	v_mul_f32_e32 v239, 0x4b800000, v238
	v_cmp_gt_f32_e32 vcc, s67, v238
	s_nop 1
	v_cndmask_b32_e32 v238, v238, v239, vcc
	v_rsq_f32_e32 v238, v238
	s_nop 0
	v_mul_f32_e32 v239, 0x45800000, v238
	v_cndmask_b32_e32 v238, v238, v239, vcc
	v_fmamk_f32 v240, v240, 0x3a000000, v228
	v_mul_f32_e32 v241, 0x4b800000, v240
	v_cmp_gt_f32_e32 vcc, s67, v240
	s_nop 1
	v_cndmask_b32_e32 v240, v240, v241, vcc
	v_rsq_f32_e32 v240, v240
	s_nop 0
	v_mul_f32_e32 v241, 0x45800000, v240
	v_cndmask_b32_e32 v240, v240, v241, vcc
	s_mov_b32 s10, s6
	s_lshl_b32 s8, s10, 12
	s_add_u32 s8, s8, 0x800
	s_mov_b32 s9, 0
	v_lshl_add_u64 v[230:231], v[136:137], 0, s[8:9]
	v_pk_mul_f32 v[0:1], v[0:1], v[128:129] op_sel_hi:[1,0]
	v_pk_fma_f32 v[0:1], v[0:1], v[154:155], v[186:187]
	v_pk_mul_f32 v[2:3], v[2:3], v[128:129] op_sel_hi:[1,0]
	v_pk_fma_f32 v[2:3], v[2:3], v[156:157], v[188:189]
	v_cvt_pk_bf16_f32 v0, v0, v1
	v_cvt_pk_bf16_f32 v1, v2, v3
	global_store_dwordx2 v[230:231], v[0:1], off offset:-2048
	v_pk_mul_f32 v[4:5], v[4:5], v[128:129] op_sel_hi:[1,0]
	v_pk_fma_f32 v[4:5], v[4:5], v[158:159], v[190:191]
	v_pk_mul_f32 v[6:7], v[6:7], v[128:129] op_sel_hi:[1,0]
	v_pk_fma_f32 v[6:7], v[6:7], v[160:161], v[192:193]
	v_cvt_pk_bf16_f32 v4, v4, v5
	v_cvt_pk_bf16_f32 v5, v6, v7
	global_store_dwordx2 v[230:231], v[4:5], off offset:-1536
	v_pk_mul_f32 v[8:9], v[8:9], v[128:129] op_sel_hi:[1,0]
	v_pk_fma_f32 v[8:9], v[8:9], v[162:163], v[194:195]
	v_pk_mul_f32 v[10:11], v[10:11], v[128:129] op_sel_hi:[1,0]
; __device__ __forceinline__ unsigned cvt_pk_bf16(float lo, float hi) { unsigned r; asm volatile("v_cvt_pk_bf16_f32 %0, %1, %2" : "=v"(r) : "v"(lo), "v"(hi)); return r; }
; __device__ __forceinline__ void norm_rows(const float* src, int nrows, const float* gam, const float* sc, const float* sh, bf16_t* dst, int tid) {
;     ...
; #pragma unroll
;     for (int j = 0; j < 8; ++j) {
;       const int c = 4 * (lane + 64 * j);
;       const f32x4 mul = *(const f32x4*)(gam + c) * (1.0f + *(const f32x4*)(sc + c)); const f32x4 add = *(const f32x4*)(sh + c);
; #pragma unroll
;       for (int q = 0; q < 4; ++q) if (ok[q]) {
;         const f32x4 h = v[q][j] * ss[q] * mul + add; u32x2 w; w.x = cvt_pk_bf16(h[0], h[1]); w.y = cvt_pk_bf16(h[2], h[3]);
;         ((u32x2*)(dst + (size_t)rr[q] * DM) + lane)[64 * j] = w;
;       }
	v_pk_fma_f32 v[10:11], v[10:11], v[164:165], v[196:197]
	v_cvt_pk_bf16_f32 v8, v8, v9
	v_cvt_pk_bf16_f32 v9, v10, v11
	global_store_dwordx2 v[230:231], v[8:9], off offset:-1024
	v_pk_mul_f32 v[12:13], v[12:13], v[128:129] op_sel_hi:[1,0]
	v_pk_fma_f32 v[12:13], v[12:13], v[166:167], v[198:199]
	v_pk_mul_f32 v[14:15], v[14:15], v[128:129] op_sel_hi:[1,0]
	v_pk_fma_f32 v[14:15], v[14:15], v[168:169], v[200:201]
	v_cvt_pk_bf16_f32 v12, v12, v13
	v_cvt_pk_bf16_f32 v13, v14, v15
	global_store_dwordx2 v[230:231], v[12:13], off offset:-512
	v_pk_mul_f32 v[16:17], v[16:17], v[128:129] op_sel_hi:[1,0]
	v_pk_fma_f32 v[16:17], v[16:17], v[170:171], v[202:203]
	v_pk_mul_f32 v[18:19], v[18:19], v[128:129] op_sel_hi:[1,0]
	v_pk_fma_f32 v[18:19], v[18:19], v[172:173], v[204:205]
	v_cvt_pk_bf16_f32 v16, v16, v17
	v_cvt_pk_bf16_f32 v17, v18, v19
	global_store_dwordx2 v[230:231], v[16:17], off
	v_pk_mul_f32 v[20:21], v[20:21], v[128:129] op_sel_hi:[1,0]
	v_pk_fma_f32 v[20:21], v[20:21], v[174:175], v[206:207]
	v_pk_mul_f32 v[22:23], v[22:23], v[128:129] op_sel_hi:[1,0]
	v_pk_fma_f32 v[22:23], v[22:23], v[176:177], v[208:209]
	v_cvt_pk_bf16_f32 v20, v20, v21
	v_cvt_pk_bf16_f32 v21, v22, v23
	global_store_dwordx2 v[230:231], v[20:21], off offset:512
	v_pk_mul_f32 v[24:25], v[24:25], v[128:129] op_sel_hi:[1,0]
	v_pk_fma_f32 v[24:25], v[24:25], v[178:179], v[210:211]
	v_pk_mul_f32 v[26:27], v[26:27], v[128:129] op_sel_hi:[1,0]
	v_pk_fma_f32 v[26:27], v[26:27], v[180:181], v[212:213]
	v_cvt_pk_bf16_f32 v24, v24, v25
	v_cvt_pk_bf16_f32 v25, v26, v27
	global_store_dwordx2 v[230:231], v[24:25], off offset:1024
	v_pk_mul_f32 v[28:29], v[28:29], v[128:129] op_sel_hi:[1,0]
	v_pk_fma_f32 v[28:29], v[28:29], v[182:183], v[214:215]
	v_pk_mul_f32 v[30:31], v[30:31], v[128:129] op_sel_hi:[1,0]
	v_pk_fma_f32 v[30:31], v[30:31], v[184:185], v[216:217]
	v_cvt_pk_bf16_f32 v28, v28, v29
	v_cvt_pk_bf16_f32 v29, v30, v31
	global_store_dwordx2 v[230:231], v[28:29], off offset:1536
	s_add_i32 s10, s6, s82
	s_cmp_lt_i32 s10, 0x4000
	s_cbranch_scc0 .Lnr_skip1
	s_lshl_b32 s8, s10, 12
	s_add_u32 s8, s8, 0x800
	s_mov_b32 s9, 0
	v_lshl_add_u64 v[232:233], v[136:137], 0, s[8:9]
	v_pk_mul_f32 v[32:33], v[32:33], v[130:131] op_sel_hi:[1,0]
	v_pk_fma_f32 v[32:33], v[32:33], v[154:155], v[186:187]
	v_pk_mul_f32 v[34:35], v[34:35], v[130:131] op_sel_hi:[1,0]
	v_pk_fma_f32 v[34:35], v[34:35], v[156:157], v[188:189]
	v_cvt_pk_bf16_f32 v32, v32, v33
	v_cvt_pk_bf16_f32 v33, v34, v35
	global_store_dwordx2 v[232:233], v[32:33], off offset:-2048
	v_pk_mul_f32 v[36:37], v[36:37], v[130:131] op_sel_hi:[1,0]
	v_pk_fma_f32 v[36:37], v[36:37], v[158:159], v[190:191]
	v_pk_mul_f32 v[38:39], v[38:39], v[130:131] op_sel_hi:[1,0]
	v_pk_fma_f32 v[38:39], v[38:39], v[160:161], v[192:193]
	v_cvt_pk_bf16_f32 v36, v36, v37
	v_cvt_pk_bf16_f32 v37, v38, v39
	global_store_dwordx2 v[232:233], v[36:37], off offset:-1536
	v_pk_mul_f32 v[40:41], v[40:41], v[130:131] op_sel_hi:[1,0]
	v_pk_fma_f32 v[40:41], v[40:41], v[162:163], v[194:195]
	v_pk_mul_f32 v[42:43], v[42:43], v[130:131] op_sel_hi:[1,0]
	v_pk_fma_f32 v[42:43], v[42:43], v[164:165], v[196:197]
	v_cvt_pk_bf16_f32 v40, v40, v41
	v_cvt_pk_bf16_f32 v41, v42, v43
	global_store_dwordx2 v[232:233], v[40:41], off offset:-1024
	v_pk_mul_f32 v[44:45], v[44:45], v[130:131] op_sel_hi:[1,0]
	v_pk_fma_f32 v[44:45], v[44:45], v[166:167], v[198:199]
	v_pk_mul_f32 v[46:47], v[46:47], v[130:131] op_sel_hi:[1,0]
	v_pk_fma_f32 v[46:47], v[46:47], v[168:169], v[200:201]
	v_cvt_pk_bf16_f32 v44, v44, v45
	v_cvt_pk_bf16_f32 v45, v46, v47
	global_store_dwordx2 v[232:233], v[44:45], off offset:-512
	v_pk_mul_f32 v[48:49], v[48:49], v[130:131] op_sel_hi:[1,0]
	v_pk_fma_f32 v[48:49], v[48:49], v[170:171], v[202:203]
	v_pk_mul_f32 v[50:51], v[50:51], v[130:131] op_sel_hi:[1,0]
	v_pk_fma_f32 v[50:51], v[50:51], v[172:173], v[204:205]
	v_cvt_pk_bf16_f32 v48, v48, v49
	v_cvt_pk_bf16_f32 v49, v50, v51
	global_store_dwordx2 v[232:233], v[48:49], off
	v_pk_mul_f32 v[52:53], v[52:53], v[130:131] op_sel_hi:[1,0]
	v_pk_fma_f32 v[52:53], v[52:53], v[174:175], v[206:207]
	v_pk_mul_f32 v[54:55], v[54:55], v[130:131] op_sel_hi:[1,0]
	v_pk_fma_f32 v[54:55], v[54:55], v[176:177], v[208:209]
	v_cvt_pk_bf16_f32 v52, v52, v53
	v_cvt_pk_bf16_f32 v53, v54, v55
	global_store_dwordx2 v[232:233], v[52:53], off offset:512
	v_pk_mul_f32 v[56:57], v[56:57], v[130:131] op_sel_hi:[1,0]
	v_pk_fma_f32 v[56:57], v[56:57], v[178:179], v[210:211]
	v_pk_mul_f32 v[58:59], v[58:59], v[130:131] op_sel_hi:[1,0]
	v_pk_fma_f32 v[58:59], v[58:59], v[180:181], v[212:213]
	v_cvt_pk_bf16_f32 v56, v56, v57
	v_cvt_pk_bf16_f32 v57, v58, v59
	global_store_dwordx2 v[232:233], v[56:57], off offset:1024
	v_pk_mul_f32 v[60:61], v[60:61], v[130:131] op_sel_hi:[1,0]
	v_pk_fma_f32 v[60:61], v[60:61], v[182:183], v[214:215]
	v_pk_mul_f32 v[62:63], v[62:63], v[130:131] op_sel_hi:[1,0]
	v_pk_fma_f32 v[62:63], v[62:63], v[184:185], v[216:217]
	v_cvt_pk_bf16_f32 v60, v60, v61
	v_cvt_pk_bf16_f32 v61, v62, v63
	global_store_dwordx2 v[232:233], v[60:61], off offset:1536
; __device__ __forceinline__ unsigned cvt_pk_bf16(float lo, float hi) { unsigned r; asm volatile("v_cvt_pk_bf16_f32 %0, %1, %2" : "=v"(r) : "v"(lo), "v"(hi)); return r; }
; __device__ __forceinline__ void norm_rows(const float* src, int nrows, const float* gam, const float* sc, const float* sh, bf16_t* dst, int tid) {
;     ...
; #pragma unroll
;     for (int j = 0; j < 8; ++j) {
;       const int c = 4 * (lane + 64 * j);
;       const f32x4 mul = *(const f32x4*)(gam + c) * (1.0f + *(const f32x4*)(sc + c)); const f32x4 add = *(const f32x4*)(sh + c);
; #pragma unroll
;       for (int q = 0; q < 4; ++q) if (ok[q]) {
;         const f32x4 h = v[q][j] * ss[q] * mul + add; u32x2 w; w.x = cvt_pk_bf16(h[0], h[1]); w.y = cvt_pk_bf16(h[2], h[3]);
;         ((u32x2*)(dst + (size_t)rr[q] * DM) + lane)[64 * j] = w;
;       }
;     }
;   }
.Lnr_skip1:
	s_add_i32 s10, s6, s71
	s_cmp_lt_i32 s10, 0x4000
	s_cbranch_scc0 .Lnr_skip2
	s_lshl_b32 s8, s10, 12
	s_add_u32 s8, s8, 0x800
	s_mov_b32 s9, 0
	v_lshl_add_u64 v[234:235], v[136:137], 0, s[8:9]
	v_pk_mul_f32 v[64:65], v[64:65], v[238:239] op_sel_hi:[1,0]
	v_pk_fma_f32 v[64:65], v[64:65], v[154:155], v[186:187]
	v_pk_mul_f32 v[66:67], v[66:67], v[238:239] op_sel_hi:[1,0]
	v_pk_fma_f32 v[66:67], v[66:67], v[156:157], v[188:189]
	v_cvt_pk_bf16_f32 v64, v64, v65
	v_cvt_pk_bf16_f32 v65, v66, v67
	global_store_dwordx2 v[234:235], v[64:65], off offset:-2048
	v_pk_mul_f32 v[68:69], v[68:69], v[238:239] op_sel_hi:[1,0]
	v_pk_fma_f32 v[68:69], v[68:69], v[158:159], v[190:191]
	v_pk_mul_f32 v[70:71], v[70:71], v[238:239] op_sel_hi:[1,0]
	v_pk_fma_f32 v[70:71], v[70:71], v[160:161], v[192:193]
	v_cvt_pk_bf16_f32 v68, v68, v69
	v_cvt_pk_bf16_f32 v69, v70, v71
	global_store_dwordx2 v[234:235], v[68:69], off offset:-1536
	v_pk_mul_f32 v[72:73], v[72:73], v[238:239] op_sel_hi:[1,0]
	v_pk_fma_f32 v[72:73], v[72:73], v[162:163], v[194:195]
	v_pk_mul_f32 v[74:75], v[74:75], v[238:239] op_sel_hi:[1,0]
	v_pk_fma_f32 v[74:75], v[74:75], v[164:165], v[196:197]
	v_cvt_pk_bf16_f32 v72, v72, v73
	v_cvt_pk_bf16_f32 v73, v74, v75
	global_store_dwordx2 v[234:235], v[72:73], off offset:-1024
	v_pk_mul_f32 v[76:77], v[76:77], v[238:239] op_sel_hi:[1,0]
	v_pk_fma_f32 v[76:77], v[76:77], v[166:167], v[198:199]
	v_pk_mul_f32 v[78:79], v[78:79], v[238:239] op_sel_hi:[1,0]
	v_pk_fma_f32 v[78:79], v[78:79], v[168:169], v[200:201]
	v_cvt_pk_bf16_f32 v76, v76, v77
	v_cvt_pk_bf16_f32 v77, v78, v79
	global_store_dwordx2 v[234:235], v[76:77], off offset:-512
	v_pk_mul_f32 v[80:81], v[80:81], v[238:239] op_sel_hi:[1,0]
	v_pk_fma_f32 v[80:81], v[80:81], v[170:171], v[202:203]
	v_pk_mul_f32 v[82:83], v[82:83], v[238:239] op_sel_hi:[1,0]
	v_pk_fma_f32 v[82:83], v[82:83], v[172:173], v[204:205]
	v_cvt_pk_bf16_f32 v80, v80, v81
	v_cvt_pk_bf16_f32 v81, v82, v83
	global_store_dwordx2 v[234:235], v[80:81], off
	v_pk_mul_f32 v[84:85], v[84:85], v[238:239] op_sel_hi:[1,0]
	v_pk_fma_f32 v[84:85], v[84:85], v[174:175], v[206:207]
	v_pk_mul_f32 v[86:87], v[86:87], v[238:239] op_sel_hi:[1,0]
	v_pk_fma_f32 v[86:87], v[86:87], v[176:177], v[208:209]
	v_cvt_pk_bf16_f32 v84, v84, v85
	v_cvt_pk_bf16_f32 v85, v86, v87
	global_store_dwordx2 v[234:235], v[84:85], off offset:512
	v_pk_mul_f32 v[88:89], v[88:89], v[238:239] op_sel_hi:[1,0]
	v_pk_fma_f32 v[88:89], v[88:89], v[178:179], v[210:211]
	v_pk_mul_f32 v[90:91], v[90:91], v[238:239] op_sel_hi:[1,0]
	v_pk_fma_f32 v[90:91], v[90:91], v[180:181], v[212:213]
	v_cvt_pk_bf16_f32 v88, v88, v89
	v_cvt_pk_bf16_f32 v89, v90, v91
	global_store_dwordx2 v[234:235], v[88:89], off offset:1024
	v_pk_mul_f32 v[92:93], v[92:93], v[238:239] op_sel_hi:[1,0]
	v_pk_fma_f32 v[92:93], v[92:93], v[182:183], v[214:215]
	v_pk_mul_f32 v[94:95], v[94:95], v[238:239] op_sel_hi:[1,0]
	v_pk_fma_f32 v[94:95], v[94:95], v[184:185], v[216:217]
	v_cvt_pk_bf16_f32 v92, v92, v93
	v_cvt_pk_bf16_f32 v93, v94, v95
	global_store_dwordx2 v[234:235], v[92:93], off offset:1536
.Lnr_skip2:
	s_add_i32 s10, s6, s87
	s_cmp_lt_i32 s10, 0x4000
	s_cbranch_scc0 .Lnr_skip3
	s_lshl_b32 s8, s10, 12
	s_add_u32 s8, s8, 0x800
	s_mov_b32 s9, 0
	v_lshl_add_u64 v[236:237], v[136:137], 0, s[8:9]
	v_pk_mul_f32 v[96:97], v[96:97], v[240:241] op_sel_hi:[1,0]
	v_pk_fma_f32 v[96:97], v[96:97], v[154:155], v[186:187]
	v_pk_mul_f32 v[98:99], v[98:99], v[240:241] op_sel_hi:[1,0]
	v_pk_fma_f32 v[98:99], v[98:99], v[156:157], v[188:189]
	v_cvt_pk_bf16_f32 v96, v96, v97
	v_cvt_pk_bf16_f32 v97, v98, v99
	global_store_dwordx2 v[236:237], v[96:97], off offset:-2048
	v_pk_mul_f32 v[100:101], v[100:101], v[240:241] op_sel_hi:[1,0]
	v_pk_fma_f32 v[100:101], v[100:101], v[158:159], v[190:191]
	v_pk_mul_f32 v[102:103], v[102:103], v[240:241] op_sel_hi:[1,0]
	v_pk_fma_f32 v[102:103], v[102:103], v[160:161], v[192:193]
	v_cvt_pk_bf16_f32 v100, v100, v101
	v_cvt_pk_bf16_f32 v101, v102, v103
	global_store_dwordx2 v[236:237], v[100:101], off offset:-1536
	v_pk_mul_f32 v[104:105], v[104:105], v[240:241] op_sel_hi:[1,0]
	v_pk_fma_f32 v[104:105], v[104:105], v[162:163], v[194:195]
	v_pk_mul_f32 v[106:107], v[106:107], v[240:241] op_sel_hi:[1,0]
	v_pk_fma_f32 v[106:107], v[106:107], v[164:165], v[196:197]
	v_cvt_pk_bf16_f32 v104, v104, v105
	v_cvt_pk_bf16_f32 v105, v106, v107
	global_store_dwordx2 v[236:237], v[104:105], off offset:-1024
	v_pk_mul_f32 v[108:109], v[108:109], v[240:241] op_sel_hi:[1,0]
	v_pk_fma_f32 v[108:109], v[108:109], v[166:167], v[198:199]
	v_pk_mul_f32 v[110:111], v[110:111], v[240:241] op_sel_hi:[1,0]
	v_pk_fma_f32 v[110:111], v[110:111], v[168:169], v[200:201]
	v_cvt_pk_bf16_f32 v108, v108, v109
	v_cvt_pk_bf16_f32 v109, v110, v111
	global_store_dwordx2 v[236:237], v[108:109], off offset:-512
	v_pk_mul_f32 v[112:113], v[112:113], v[240:241] op_sel_hi:[1,0]
	v_pk_fma_f32 v[112:113], v[112:113], v[170:171], v[202:203]
	v_pk_mul_f32 v[114:115], v[114:115], v[240:241] op_sel_hi:[1,0]
	v_pk_fma_f32 v[114:115], v[114:115], v[172:173], v[204:205]
	v_cvt_pk_bf16_f32 v112, v112, v113
	v_cvt_pk_bf16_f32 v113, v114, v115
	global_store_dwordx2 v[236:237], v[112:113], off
	v_pk_mul_f32 v[116:117], v[116:117], v[240:241] op_sel_hi:[1,0]
	v_pk_fma_f32 v[116:117], v[116:117], v[174:175], v[206:207]
	v_pk_mul_f32 v[118:119], v[118:119], v[240:241] op_sel_hi:[1,0]
	v_pk_fma_f32 v[118:119], v[118:119], v[176:177], v[208:209]
	v_cvt_pk_bf16_f32 v116, v116, v117
	v_cvt_pk_bf16_f32 v117, v118, v119
	global_store_dwordx2 v[236:237], v[116:117], off offset:512
	v_pk_mul_f32 v[120:121], v[120:121], v[240:241] op_sel_hi:[1,0]
	v_pk_fma_f32 v[120:121], v[120:121], v[178:179], v[210:211]
	v_pk_mul_f32 v[122:123], v[122:123], v[240:241] op_sel_hi:[1,0]
	v_pk_fma_f32 v[122:123], v[122:123], v[180:181], v[212:213]
	v_cvt_pk_bf16_f32 v120, v120, v121
	v_cvt_pk_bf16_f32 v121, v122, v123
	global_store_dwordx2 v[236:237], v[120:121], off offset:1024
	v_pk_mul_f32 v[124:125], v[124:125], v[240:241] op_sel_hi:[1,0]
	v_pk_fma_f32 v[124:125], v[124:125], v[182:183], v[214:215]
	v_pk_mul_f32 v[126:127], v[126:127], v[240:241] op_sel_hi:[1,0]
	v_pk_fma_f32 v[126:127], v[126:127], v[184:185], v[216:217]
	v_cvt_pk_bf16_f32 v124, v124, v125
	v_cvt_pk_bf16_f32 v125, v126, v127
	global_store_dwordx2 v[236:237], v[124:125], off offset:1536
.Lnr_skip3:
	s_add_i32 s6, s6, s56
	s_cmp_gt_i32 s6, s51
	s_cbranch_scc0 .Lnr_loop
